# v23: v20 + K-loops: redundant s_waitcnt lgkmcnt(0) after each pre-MFMA barrier removed (40), vmcnt+lgkmcnt waits merged (40)
# speedup vs baseline: 1.0235x; 1.0235x over previous
; #define PG8_STAGE(bufoff, gbase, voff) do { _Pragma("unroll") for (int _i = 0; _i < 2; ++_i) \
;         __builtin_amdgcn_global_load_lds((const unsigned*)((const char*)(gbase) + (voff)[_i]), (PG8_LAS unsigned*)(lds + (bufoff) + ldsw + _i * 8192), 16, 0, 0); } while (0)
; #define PG8_LDA(dst, b, h) do { _Pragma("unroll") for (int m = 0; m < 4; ++m) _Pragma("unroll") for (int k = 0; k < 2; ++k) dst[m][k] = *(const PG8_LAS bf16x8*)(lds + PG8_SA(b, h) + aoff + m * 2048 + k * 1024); } while (0)
; #define PG8_LDB(dst, b, h) do { _Pragma("unroll") for (int n = 0; n < 2; ++n) _Pragma("unroll") for (int k = 0; k < 2; ++k) dst[n][k] = *(const PG8_LAS bf16x8*)(lds + PG8_SB(b, h) + boff + n * 2048 + k * 1024); } while (0)
; #define PG8_MMA(ai, bj, At, Bt) do { __builtin_amdgcn_s_setprio(1); _Pragma("unroll") for (int m = 0; m < 4; ++m) _Pragma("unroll") for (int n = 0; n < 2; ++n) _Pragma("unroll") for (int k = 0; k < 2; ++k) \
;         acc[ai][bj][m][n] = mma_<I8>(Bt[n][k], At[m][k], acc[ai][bj][m][n]); __builtin_amdgcn_s_setprio(0); } while (0)
; #define PG8_WAIT_V(n) asm volatile("s_waitcnt vmcnt(" #n ")" ::: "memory")
; #define PG8_WAIT_L(n) asm volatile("s_waitcnt lgkmcnt(" #n ")" ::: "memory")
; #define PG8_BAR __builtin_amdgcn_s_barrier()
; template <class Epi, class Sched, bool ALIGN_EPI = false, bool SP2 = false, bool I8 = false>
; __device__ __forceinline__ void gemm_phase(PG8_LAS unsigned char* lds, const Gemm g, const Sched& S, const Epi& E) {
;     ...
;             const bool last = (t == nt - 2);
;             const char* a1 = cA + (size_t)(t + 1) * kstep;
;             const char* a2 = last ? nA : cA + (size_t)(t + 2) * kstep; const char* b2 = last ? nB : cB + (size_t)(t + 2) * kstep;
;             const char* a3 = a2 + kstep; const char* b3 = b2 + kstep;
;             if (last && has_next) S.a_ready(nxt);
;             if constexpr (SP2) {
;             PG8_LDB(B0, 0, 0); PG8_LDB(B1, 0, 1); PG8_SCHED; PG8_LDA(At, 0, 0); PG8_STAGE(PG8_SA(1, 1), a1 + hstepA, voffA);
;             PG8_WAIT_V(8); PG8_WAIT_L(0); PG8_BAR; PG8_MMA(0, 0, At, B0); PG8_MMA(0, 1, At, B1); PG8_BAR; PG8_SCHED;
;             PG8_LDA(At, 0, 1); PG8_STAGE(PG8_SB(0, 0), b2, voffB); PG8_STAGE(PG8_SB(0, 1), b2 + hstepB, voffB); PG8_STAGE(PG8_SA(0, 0), a2, voffA);
;             PG8_WAIT_V(8); PG8_WAIT_L(0); PG8_BAR; PG8_MMA(1, 0, At, B0); PG8_MMA(1, 1, At, B1); PG8_BAR; PG8_SCHED;
.LBB0_483:
	ds_read_b128 v[58:61], v187
	ds_read_b128 v[62:65], v187 offset:1024
	ds_read_b128 v[74:77], v187 offset:2048
	ds_read_b128 v[78:81], v187 offset:3072
	ds_read_b128 v[162:165], v188
	ds_read_b128 v[166:169], v188 offset:1024
	ds_read_b128 v[170:173], v188 offset:2048
	ds_read_b128 v[190:193], v188 offset:3072
	s_add_u32 s34, s2, 0xfff80080
	s_addc_u32 s35, s3, -1
	s_cmp_eq_u32 s40, 28
	s_cselect_b32 s37, s7, s35
	s_cselect_b32 s36, s25, s34
	s_cselect_b32 s35, s23, s39
	s_cselect_b32 s34, s33, s38
	s_add_i32 m0, s31, 0xc000
	ds_read_b128 v[194:197], v189
	ds_read_b128 v[198:201], v189 offset:1024
	ds_read_b128 v[202:205], v189 offset:2048
	ds_read_b128 v[206:209], v189 offset:3072
	ds_read_b128 v[210:213], v189 offset:4096
	ds_read_b128 v[214:217], v189 offset:5120
	ds_read_b128 v[218:221], v189 offset:6144
	ds_read_b128 v[222:225], v189 offset:7168
	global_load_lds_dwordx4 v154, s[2:3]
	s_add_i32 m0, s31, 0xe000
	s_nop 0
	global_load_lds_dwordx4 v156, s[2:3]
	s_waitcnt vmcnt(8) lgkmcnt(0)
	s_barrier
	v_mfma_i32_16x16x64_i8 v[142:145], v[58:61], v[194:197], v[142:145]
	v_mfma_i32_16x16x64_i8 v[138:141], v[74:77], v[194:197], v[138:141]
	v_mfma_i32_16x16x64_i8 v[126:129], v[58:61], v[202:205], v[126:129]
	v_mfma_i32_16x16x64_i8 v[122:125], v[74:77], v[202:205], v[122:125]
	v_mfma_i32_16x16x64_i8 v[110:113], v[58:61], v[210:213], v[110:113]
	v_mfma_i32_16x16x64_i8 v[106:109], v[74:77], v[210:213], v[106:109]
	v_mfma_i32_16x16x64_i8 v[94:97], v[58:61], v[218:221], v[94:97]
	v_mfma_i32_16x16x64_i8 v[90:93], v[74:77], v[218:221], v[90:93]
	v_mfma_i32_16x16x64_i8 v[142:145], v[62:65], v[198:201], v[142:145]
	v_mfma_i32_16x16x64_i8 v[138:141], v[78:81], v[198:201], v[138:141]
	v_mfma_i32_16x16x64_i8 v[126:129], v[62:65], v[206:209], v[126:129]
	v_mfma_i32_16x16x64_i8 v[122:125], v[78:81], v[206:209], v[122:125]
	v_mfma_i32_16x16x64_i8 v[110:113], v[62:65], v[214:217], v[110:113]
	v_mfma_i32_16x16x64_i8 v[106:109], v[78:81], v[214:217], v[106:109]
	v_mfma_i32_16x16x64_i8 v[94:97], v[62:65], v[222:225], v[94:97]
	v_mfma_i32_16x16x64_i8 v[90:93], v[78:81], v[222:225], v[90:93]
	v_mfma_i32_16x16x64_i8 v[134:137], v[162:165], v[194:197], v[134:137]
	v_mfma_i32_16x16x64_i8 v[130:133], v[170:173], v[194:197], v[130:133]
	v_mfma_i32_16x16x64_i8 v[118:121], v[162:165], v[202:205], v[118:121]
	v_mfma_i32_16x16x64_i8 v[114:117], v[170:173], v[202:205], v[114:117]
	v_mfma_i32_16x16x64_i8 v[102:105], v[162:165], v[210:213], v[102:105]
	v_mfma_i32_16x16x64_i8 v[98:101], v[170:173], v[210:213], v[98:101]
	v_mfma_i32_16x16x64_i8 v[86:89], v[162:165], v[218:221], v[86:89]
	v_mfma_i32_16x16x64_i8 v[82:85], v[170:173], v[218:221], v[82:85]
	v_mfma_i32_16x16x64_i8 v[134:137], v[166:169], v[198:201], v[134:137]
	v_mfma_i32_16x16x64_i8 v[130:133], v[190:193], v[198:201], v[130:133]
	v_mfma_i32_16x16x64_i8 v[118:121], v[166:169], v[206:209], v[118:121]
	v_mfma_i32_16x16x64_i8 v[114:117], v[190:193], v[206:209], v[114:117]
	v_mfma_i32_16x16x64_i8 v[102:105], v[166:169], v[214:217], v[102:105]
	v_mfma_i32_16x16x64_i8 v[98:101], v[190:193], v[214:217], v[98:101]
	v_mfma_i32_16x16x64_i8 v[86:89], v[166:169], v[222:225], v[86:89]
	v_mfma_i32_16x16x64_i8 v[82:85], v[190:193], v[222:225], v[82:85]
	s_barrier
	s_add_i32 s41, s8, s68
	s_mov_b64 s[98:99], s[34:35]
	s_mov_b32 m0, s41
	ds_read_b128 v[194:197], v189 offset:16384
	ds_read_b128 v[198:201], v189 offset:17408
	ds_read_b128 v[202:205], v189 offset:18432
	ds_read_b128 v[206:209], v189 offset:19456
	ds_read_b128 v[210:213], v189 offset:20480
	ds_read_b128 v[214:217], v189 offset:21504
	ds_read_b128 v[218:221], v189 offset:22528
	ds_read_b128 v[222:225], v189 offset:23552
	global_load_lds_dwordx4 v148, s[34:35]
	s_add_i32 m0, s41, 0x2000
	s_add_u32 vcc_lo, s34, 0x80000
	s_mov_b64 s[98:99], s[34:35]
	s_addc_u32 vcc_hi, s35, 0
	s_add_i32 s41, s9, s68
	global_load_lds_dwordx4 v152, s[34:35]
	s_mov_b32 m0, s41
	s_mov_b64 s[100:101], s[36:37]
	global_load_lds_dwordx4 v148, vcc
	s_add_i32 m0, s41, 0x2000
	s_nop 0
	global_load_lds_dwordx4 v152, vcc
	s_mov_b64 s[100:101], s[36:37]
	s_mov_b32 m0, s31
	s_nop 0
	global_load_lds_dwordx4 v146, s[36:37]
	s_mov_b32 m0, s69
	s_nop 0
	global_load_lds_dwordx4 v150, s[36:37]
	s_waitcnt vmcnt(8) lgkmcnt(0)
	s_barrier
	v_mfma_i32_16x16x64_i8 v[70:73], v[58:61], v[194:197], v[70:73]
	v_mfma_i32_16x16x64_i8 v[66:69], v[74:77], v[194:197], v[66:69]
	v_mfma_i32_16x16x64_i8 v[46:49], v[58:61], v[202:205], v[46:49]
	v_mfma_i32_16x16x64_i8 v[42:45], v[74:77], v[202:205], v[42:45]
	v_mfma_i32_16x16x64_i8 v[30:33], v[58:61], v[210:213], v[30:33]
	v_mfma_i32_16x16x64_i8 v[26:29], v[74:77], v[210:213], v[26:29]
	v_mfma_i32_16x16x64_i8 v[14:17], v[58:61], v[218:221], v[14:17]
	v_mfma_i32_16x16x64_i8 v[10:13], v[74:77], v[218:221], v[10:13]
	v_mfma_i32_16x16x64_i8 v[70:73], v[62:65], v[198:201], v[70:73]
	v_mfma_i32_16x16x64_i8 v[66:69], v[78:81], v[198:201], v[66:69]
	v_mfma_i32_16x16x64_i8 v[46:49], v[62:65], v[206:209], v[46:49]
	v_mfma_i32_16x16x64_i8 v[42:45], v[78:81], v[206:209], v[42:45]
	v_mfma_i32_16x16x64_i8 v[30:33], v[62:65], v[214:217], v[30:33]
	v_mfma_i32_16x16x64_i8 v[26:29], v[78:81], v[214:217], v[26:29]
	v_mfma_i32_16x16x64_i8 v[14:17], v[62:65], v[222:225], v[14:17]
	v_mfma_i32_16x16x64_i8 v[10:13], v[78:81], v[222:225], v[10:13]
	v_mfma_i32_16x16x64_i8 v[54:57], v[162:165], v[194:197], v[54:57]
	v_mfma_i32_16x16x64_i8 v[50:53], v[170:173], v[194:197], v[50:53]
	v_mfma_i32_16x16x64_i8 v[38:41], v[162:165], v[202:205], v[38:41]
	v_mfma_i32_16x16x64_i8 v[34:37], v[170:173], v[202:205], v[34:37]
	v_mfma_i32_16x16x64_i8 v[22:25], v[162:165], v[210:213], v[22:25]
	v_mfma_i32_16x16x64_i8 v[18:21], v[170:173], v[210:213], v[18:21]
	v_mfma_i32_16x16x64_i8 v[6:9], v[162:165], v[218:221], v[6:9]
	v_mfma_i32_16x16x64_i8 v[2:5], v[170:173], v[218:221], v[2:5]
	v_mfma_i32_16x16x64_i8 v[54:57], v[166:169], v[198:201], v[54:57]
	v_mfma_i32_16x16x64_i8 v[50:53], v[190:193], v[198:201], v[50:53]
	v_mfma_i32_16x16x64_i8 v[38:41], v[166:169], v[206:209], v[38:41]
	v_mfma_i32_16x16x64_i8 v[34:37], v[190:193], v[206:209], v[34:37]
	v_mfma_i32_16x16x64_i8 v[22:25], v[166:169], v[214:217], v[22:25]
	v_mfma_i32_16x16x64_i8 v[18:21], v[190:193], v[214:217], v[18:21]
	v_mfma_i32_16x16x64_i8 v[6:9], v[166:169], v[222:225], v[6:9]
	v_mfma_i32_16x16x64_i8 v[2:5], v[190:193], v[222:225], v[2:5]
	s_barrier
; #define PG8_STAGE(bufoff, gbase, voff) do { _Pragma("unroll") for (int _i = 0; _i < 2; ++_i) \
;         __builtin_amdgcn_global_load_lds((const unsigned*)((const char*)(gbase) + (voff)[_i]), (PG8_LAS unsigned*)(lds + (bufoff) + ldsw + _i * 8192), 16, 0, 0); } while (0)
; #define PG8_LDA(dst, b, h) do { _Pragma("unroll") for (int m = 0; m < 4; ++m) _Pragma("unroll") for (int k = 0; k < 2; ++k) dst[m][k] = *(const PG8_LAS bf16x8*)(lds + PG8_SA(b, h) + aoff + m * 2048 + k * 1024); } while (0)
; #define PG8_LDB(dst, b, h) do { _Pragma("unroll") for (int n = 0; n < 2; ++n) _Pragma("unroll") for (int k = 0; k < 2; ++k) dst[n][k] = *(const PG8_LAS bf16x8*)(lds + PG8_SB(b, h) + boff + n * 2048 + k * 1024); } while (0)
; #define PG8_MMA(ai, bj, At, Bt) do { __builtin_amdgcn_s_setprio(1); _Pragma("unroll") for (int m = 0; m < 4; ++m) _Pragma("unroll") for (int n = 0; n < 2; ++n) _Pragma("unroll") for (int k = 0; k < 2; ++k) \
;         acc[ai][bj][m][n] = mma_<I8>(Bt[n][k], At[m][k], acc[ai][bj][m][n]); __builtin_amdgcn_s_setprio(0); } while (0)
; #define PG8_WAIT_V(n) asm volatile("s_waitcnt vmcnt(" #n ")" ::: "memory")
; #define PG8_WAIT_L(n) asm volatile("s_waitcnt lgkmcnt(" #n ")" ::: "memory")
; #define PG8_BAR __builtin_amdgcn_s_barrier()
; #define PG8_SCHED __builtin_amdgcn_sched_barrier(0)
; template <class Epi, class Sched, bool ALIGN_EPI = false, bool SP2 = false, bool I8 = false>
; __device__ __forceinline__ void gemm_phase(PG8_LAS unsigned char* lds, const Gemm g, const Sched& S, const Epi& E) {
;     ...
;         for (int t = 0; t < nt; t += 2) {
;     ...
;             PG8_LDB(B0, 1, 0); PG8_LDB(B1, 1, 1); PG8_SCHED; PG8_LDA(At, 1, 0); PG8_STAGE(PG8_SA(0, 1), a2 + hstepA, voffA);
;             PG8_WAIT_V(8); PG8_WAIT_L(0); PG8_BAR; PG8_MMA(0, 0, At, B0); PG8_MMA(0, 1, At, B1); PG8_BAR; PG8_SCHED;
;             PG8_LDA(At, 1, 1); PG8_STAGE(PG8_SB(1, 0), b3, voffB); PG8_STAGE(PG8_SB(1, 1), b3 + hstepB, voffB); PG8_STAGE(PG8_SA(1, 0), a3, voffA);
;             PG8_WAIT_V(8); PG8_WAIT_L(0); PG8_BAR; PG8_MMA(1, 0, At, B0); PG8_MMA(1, 1, At, B1); PG8_BAR; PG8_SCHED;
	s_add_i32 s41, 0, 0x18000
	s_add_i32 s95, 0, 0x1c000
	v_add_u32_e32 v78, s41, v181
	v_add_u32_e32 v190, s95, v181
	ds_read_b128 v[58:61], v78
	ds_read_b128 v[62:65], v78 offset:1024
	ds_read_b128 v[74:77], v78 offset:2048
	ds_read_b128 v[78:81], v78 offset:3072
	ds_read_b128 v[162:165], v190
	ds_read_b128 v[166:169], v190 offset:1024
	ds_read_b128 v[170:173], v190 offset:2048
	ds_read_b128 v[190:193], v190 offset:3072
	s_add_u32 s36, s36, 0x80000
	s_addc_u32 s37, s37, 0
	s_mov_b32 m0, s70
	ds_read_b128 v[194:197], v189 offset:32768
	ds_read_b128 v[198:201], v189 offset:33792
	ds_read_b128 v[202:205], v189 offset:34816
	ds_read_b128 v[206:209], v189 offset:35840
	ds_read_b128 v[210:213], v189 offset:36864
	ds_read_b128 v[214:217], v189 offset:37888
	ds_read_b128 v[218:221], v189 offset:38912
	ds_read_b128 v[222:225], v189 offset:39936
	global_load_lds_dwordx4 v146, s[36:37]
	s_mov_b32 m0, s71
	s_nop 0
	global_load_lds_dwordx4 v150, s[36:37]
	s_waitcnt vmcnt(8) lgkmcnt(0)
	s_barrier
	v_mfma_i32_16x16x64_i8 v[142:145], v[58:61], v[194:197], v[142:145]
	v_mfma_i32_16x16x64_i8 v[138:141], v[74:77], v[194:197], v[138:141]
	v_mfma_i32_16x16x64_i8 v[126:129], v[58:61], v[202:205], v[126:129]
	v_mfma_i32_16x16x64_i8 v[122:125], v[74:77], v[202:205], v[122:125]
	v_mfma_i32_16x16x64_i8 v[110:113], v[58:61], v[210:213], v[110:113]
	v_mfma_i32_16x16x64_i8 v[106:109], v[74:77], v[210:213], v[106:109]
	v_mfma_i32_16x16x64_i8 v[94:97], v[58:61], v[218:221], v[94:97]
	v_mfma_i32_16x16x64_i8 v[90:93], v[74:77], v[218:221], v[90:93]
	v_mfma_i32_16x16x64_i8 v[142:145], v[62:65], v[198:201], v[142:145]
	v_mfma_i32_16x16x64_i8 v[138:141], v[78:81], v[198:201], v[138:141]
	v_mfma_i32_16x16x64_i8 v[126:129], v[62:65], v[206:209], v[126:129]
	v_mfma_i32_16x16x64_i8 v[122:125], v[78:81], v[206:209], v[122:125]
	v_mfma_i32_16x16x64_i8 v[110:113], v[62:65], v[214:217], v[110:113]
	v_mfma_i32_16x16x64_i8 v[106:109], v[78:81], v[214:217], v[106:109]
	v_mfma_i32_16x16x64_i8 v[94:97], v[62:65], v[222:225], v[94:97]
	v_mfma_i32_16x16x64_i8 v[90:93], v[78:81], v[222:225], v[90:93]
	v_mfma_i32_16x16x64_i8 v[134:137], v[162:165], v[194:197], v[134:137]
	v_mfma_i32_16x16x64_i8 v[130:133], v[170:173], v[194:197], v[130:133]
	v_mfma_i32_16x16x64_i8 v[118:121], v[162:165], v[202:205], v[118:121]
	v_mfma_i32_16x16x64_i8 v[114:117], v[170:173], v[202:205], v[114:117]
	v_mfma_i32_16x16x64_i8 v[102:105], v[162:165], v[210:213], v[102:105]
	v_mfma_i32_16x16x64_i8 v[98:101], v[170:173], v[210:213], v[98:101]
	v_mfma_i32_16x16x64_i8 v[86:89], v[162:165], v[218:221], v[86:89]
	v_mfma_i32_16x16x64_i8 v[82:85], v[170:173], v[218:221], v[82:85]
	v_mfma_i32_16x16x64_i8 v[134:137], v[166:169], v[198:201], v[134:137]
	v_mfma_i32_16x16x64_i8 v[130:133], v[190:193], v[198:201], v[130:133]
	v_mfma_i32_16x16x64_i8 v[118:121], v[166:169], v[206:209], v[118:121]
	v_mfma_i32_16x16x64_i8 v[114:117], v[190:193], v[206:209], v[114:117]
	v_mfma_i32_16x16x64_i8 v[102:105], v[166:169], v[214:217], v[102:105]
	v_mfma_i32_16x16x64_i8 v[98:101], v[190:193], v[214:217], v[98:101]
	v_mfma_i32_16x16x64_i8 v[86:89], v[166:169], v[222:225], v[86:89]
	v_mfma_i32_16x16x64_i8 v[82:85], v[190:193], v[222:225], v[82:85]
	s_barrier
	s_add_i32 s36, s41, s68
	s_add_i32 m0, s36, 0xffffff80
	ds_read_b128 v[194:197], v189 offset:49152
	ds_read_b128 v[198:201], v189 offset:50176
	ds_read_b128 v[202:205], v189 offset:51200
	ds_read_b128 v[206:209], v189 offset:52224
	ds_read_b128 v[210:213], v189 offset:53248
	ds_read_b128 v[214:217], v189 offset:54272
	ds_read_b128 v[218:221], v189 offset:55296
	ds_read_b128 v[222:225], v189 offset:56320
	global_load_lds_dwordx4 v148, s[98:99] offset:128
	s_add_i32 m0, s36, 0x1f80
	s_add_u32 s34, s34, 0x80080
	s_addc_u32 s35, s35, 0
	s_add_i32 s36, s95, s68
	global_load_lds_dwordx4 v152, s[98:99] offset:128
	s_mov_b32 m0, s36
	s_nop 0
	global_load_lds_dwordx4 v148, s[34:35]
	s_add_i32 m0, s36, 0x2000
	s_nop 0
	global_load_lds_dwordx4 v152, s[34:35]
	s_add_i32 m0, s89, 0xffffff80
	s_nop 0
	global_load_lds_dwordx4 v146, s[100:101] offset:128
	s_add_i32 m0, s92, 0xffffff80
	s_nop 0
	global_load_lds_dwordx4 v150, s[100:101] offset:128
	s_waitcnt vmcnt(8) lgkmcnt(0)
	s_barrier
	v_mfma_i32_16x16x64_i8 v[70:73], v[58:61], v[194:197], v[70:73]
	v_mfma_i32_16x16x64_i8 v[66:69], v[74:77], v[194:197], v[66:69]
	v_mfma_i32_16x16x64_i8 v[46:49], v[58:61], v[202:205], v[46:49]
	v_mfma_i32_16x16x64_i8 v[42:45], v[74:77], v[202:205], v[42:45]
	v_mfma_i32_16x16x64_i8 v[30:33], v[58:61], v[210:213], v[30:33]
	v_mfma_i32_16x16x64_i8 v[26:29], v[74:77], v[210:213], v[26:29]
	v_mfma_i32_16x16x64_i8 v[14:17], v[58:61], v[218:221], v[14:17]
	v_mfma_i32_16x16x64_i8 v[10:13], v[74:77], v[218:221], v[10:13]
	v_mfma_i32_16x16x64_i8 v[70:73], v[62:65], v[198:201], v[70:73]
	v_mfma_i32_16x16x64_i8 v[66:69], v[78:81], v[198:201], v[66:69]
	v_mfma_i32_16x16x64_i8 v[46:49], v[62:65], v[206:209], v[46:49]
	v_mfma_i32_16x16x64_i8 v[42:45], v[78:81], v[206:209], v[42:45]
	v_mfma_i32_16x16x64_i8 v[30:33], v[62:65], v[214:217], v[30:33]
	v_mfma_i32_16x16x64_i8 v[26:29], v[78:81], v[214:217], v[26:29]
	v_mfma_i32_16x16x64_i8 v[14:17], v[62:65], v[222:225], v[14:17]
	v_mfma_i32_16x16x64_i8 v[10:13], v[78:81], v[222:225], v[10:13]
	v_mfma_i32_16x16x64_i8 v[54:57], v[162:165], v[194:197], v[54:57]
	v_mfma_i32_16x16x64_i8 v[50:53], v[170:173], v[194:197], v[50:53]
	v_mfma_i32_16x16x64_i8 v[38:41], v[162:165], v[202:205], v[38:41]
	v_mfma_i32_16x16x64_i8 v[34:37], v[170:173], v[202:205], v[34:37]
	v_mfma_i32_16x16x64_i8 v[22:25], v[162:165], v[210:213], v[22:25]
	v_mfma_i32_16x16x64_i8 v[18:21], v[170:173], v[210:213], v[18:21]
	v_mfma_i32_16x16x64_i8 v[6:9], v[162:165], v[218:221], v[6:9]
	v_mfma_i32_16x16x64_i8 v[2:5], v[170:173], v[218:221], v[2:5]
	v_mfma_i32_16x16x64_i8 v[54:57], v[166:169], v[198:201], v[54:57]
	v_mfma_i32_16x16x64_i8 v[50:53], v[190:193], v[198:201], v[50:53]
	v_mfma_i32_16x16x64_i8 v[38:41], v[166:169], v[206:209], v[38:41]
	v_mfma_i32_16x16x64_i8 v[34:37], v[190:193], v[206:209], v[34:37]
	v_mfma_i32_16x16x64_i8 v[22:25], v[166:169], v[214:217], v[22:25]
	v_mfma_i32_16x16x64_i8 v[18:21], v[190:193], v[214:217], v[18:21]
	v_mfma_i32_16x16x64_i8 v[6:9], v[166:169], v[222:225], v[6:9]
	v_mfma_i32_16x16x64_i8 v[2:5], v[190:193], v[222:225], v[2:5]
	s_barrier
	s_add_i32 s40, s40, 2
	s_add_u32 s2, s2, 0x100
	s_addc_u32 s3, s3, 0
	s_add_u32 s38, s38, 0x100
	s_addc_u32 s39, s39, 0
	s_cmp_gt_u32 s40, 29
	s_cbranch_scc0 .LBB0_483
	s_and_b64 vcc, exec, s[20:21]
	s_cbranch_vccz .LBB0_486
	s_barrier

; #define PG8_STAGE(bufoff, gbase, voff) do { _Pragma("unroll") for (int _i = 0; _i < 2; ++_i) \
;         __builtin_amdgcn_global_load_lds((const unsigned*)((const char*)(gbase) + (voff)[_i]), (PG8_LAS unsigned*)(lds + (bufoff) + ldsw + _i * 8192), 16, 0, 0); } while (0)
; #define PG8_LDA(dst, b, h) do { _Pragma("unroll") for (int m = 0; m < 4; ++m) _Pragma("unroll") for (int k = 0; k < 2; ++k) dst[m][k] = *(const PG8_LAS bf16x8*)(lds + PG8_SA(b, h) + aoff + m * 2048 + k * 1024); } while (0)
; #define PG8_LDB(dst, b, h) do { _Pragma("unroll") for (int n = 0; n < 2; ++n) _Pragma("unroll") for (int k = 0; k < 2; ++k) dst[n][k] = *(const PG8_LAS bf16x8*)(lds + PG8_SB(b, h) + boff + n * 2048 + k * 1024); } while (0)
; #define PG8_MMA(ai, bj, At, Bt) do { __builtin_amdgcn_s_setprio(1); _Pragma("unroll") for (int m = 0; m < 4; ++m) _Pragma("unroll") for (int n = 0; n < 2; ++n) _Pragma("unroll") for (int k = 0; k < 2; ++k) \
;         acc[ai][bj][m][n] = mma_<I8>(Bt[n][k], At[m][k], acc[ai][bj][m][n]); __builtin_amdgcn_s_setprio(0); } while (0)
; #define PG8_WAIT_V(n) asm volatile("s_waitcnt vmcnt(" #n ")" ::: "memory")
; #define PG8_WAIT_L(n) asm volatile("s_waitcnt lgkmcnt(" #n ")" ::: "memory")
; #define PG8_BAR __builtin_amdgcn_s_barrier()
; template <class Epi, class Sched, bool ALIGN_EPI = false, bool SP2 = false, bool I8 = false>
; __device__ __forceinline__ void gemm_phase(PG8_LAS unsigned char* lds, const Gemm g, const Sched& S, const Epi& E) {
;     ...
;             const bool last = (t == nt - 2);
;             const char* a1 = cA + (size_t)(t + 1) * kstep;
;             const char* a2 = last ? nA : cA + (size_t)(t + 2) * kstep; const char* b2 = last ? nB : cB + (size_t)(t + 2) * kstep;
;             const char* a3 = a2 + kstep; const char* b3 = b2 + kstep;
;             if (last && has_next) S.a_ready(nxt);
;             if constexpr (SP2) {
;             PG8_LDB(B0, 0, 0); PG8_LDB(B1, 0, 1); PG8_SCHED; PG8_LDA(At, 0, 0); PG8_STAGE(PG8_SA(1, 1), a1 + hstepA, voffA);
;             PG8_WAIT_V(8); PG8_WAIT_L(0); PG8_BAR; PG8_MMA(0, 0, At, B0); PG8_MMA(0, 1, At, B1); PG8_BAR; PG8_SCHED;
;             PG8_LDA(At, 0, 1); PG8_STAGE(PG8_SB(0, 0), b2, voffB); PG8_STAGE(PG8_SB(0, 1), b2 + hstepB, voffB); PG8_STAGE(PG8_SA(0, 0), a2, voffA);
;             PG8_WAIT_V(8); PG8_WAIT_L(0); PG8_BAR; PG8_MMA(1, 0, At, B0); PG8_MMA(1, 1, At, B1); PG8_BAR; PG8_SCHED;
.LBB0_541:
	ds_read_b128 v[154:157], v149
	ds_read_b128 v[158:161], v149 offset:1024
	ds_read_b128 v[162:165], v149 offset:2048
	ds_read_b128 v[166:169], v149 offset:3072
	ds_read_b128 v[170:173], v151
	ds_read_b128 v[174:177], v151 offset:1024
	ds_read_b128 v[178:181], v151 offset:2048
	ds_read_b128 v[188:191], v151 offset:3072
	s_add_u32 s34, s30, 0xfff00080
	s_addc_u32 s35, s31, -1
	s_cmp_eq_u32 s94, 60
	s_cselect_b32 s37, s7, s35
	s_cselect_b32 s36, s25, s34
	s_cselect_b32 s35, s23, s93
	s_cselect_b32 s34, s29, s92
	s_add_i32 m0, s39, 0xc000
	ds_read_b128 v[192:195], v153
	ds_read_b128 v[196:199], v153 offset:1024
	ds_read_b128 v[200:203], v153 offset:2048
	ds_read_b128 v[204:207], v153 offset:3072
	ds_read_b128 v[208:211], v153 offset:4096
	ds_read_b128 v[212:215], v153 offset:5120
	ds_read_b128 v[216:219], v153 offset:6144
	ds_read_b128 v[220:223], v153 offset:7168
	global_load_lds_dwordx4 v138, s[30:31]
	s_add_i32 m0, s39, 0xe000
	s_nop 0
	global_load_lds_dwordx4 v140, s[30:31]
	s_waitcnt vmcnt(8) lgkmcnt(0)
	s_barrier
	v_mfma_f32_16x16x32_bf16 v[126:129], v[154:157], v[192:195], v[126:129]
	v_mfma_f32_16x16x32_bf16 v[122:125], v[162:165], v[192:195], v[122:125]
	v_mfma_f32_16x16x32_bf16 v[110:113], v[154:157], v[200:203], v[110:113]
	v_mfma_f32_16x16x32_bf16 v[106:109], v[162:165], v[200:203], v[106:109]
	v_mfma_f32_16x16x32_bf16 v[94:97], v[154:157], v[208:211], v[94:97]
	v_mfma_f32_16x16x32_bf16 v[90:93], v[162:165], v[208:211], v[90:93]
	v_mfma_f32_16x16x32_bf16 v[78:81], v[154:157], v[216:219], v[78:81]
	v_mfma_f32_16x16x32_bf16 v[74:77], v[162:165], v[216:219], v[74:77]
	v_mfma_f32_16x16x32_bf16 v[126:129], v[158:161], v[196:199], v[126:129]
	v_mfma_f32_16x16x32_bf16 v[122:125], v[166:169], v[196:199], v[122:125]
	v_mfma_f32_16x16x32_bf16 v[110:113], v[158:161], v[204:207], v[110:113]
	v_mfma_f32_16x16x32_bf16 v[106:109], v[166:169], v[204:207], v[106:109]
	v_mfma_f32_16x16x32_bf16 v[94:97], v[158:161], v[212:215], v[94:97]
	v_mfma_f32_16x16x32_bf16 v[90:93], v[166:169], v[212:215], v[90:93]
	v_mfma_f32_16x16x32_bf16 v[78:81], v[158:161], v[220:223], v[78:81]
	v_mfma_f32_16x16x32_bf16 v[74:77], v[166:169], v[220:223], v[74:77]
	v_mfma_f32_16x16x32_bf16 v[118:121], v[170:173], v[192:195], v[118:121]
	v_mfma_f32_16x16x32_bf16 v[114:117], v[178:181], v[192:195], v[114:117]
	v_mfma_f32_16x16x32_bf16 v[102:105], v[170:173], v[200:203], v[102:105]
	v_mfma_f32_16x16x32_bf16 v[98:101], v[178:181], v[200:203], v[98:101]
	v_mfma_f32_16x16x32_bf16 v[86:89], v[170:173], v[208:211], v[86:89]
	v_mfma_f32_16x16x32_bf16 v[82:85], v[178:181], v[208:211], v[82:85]
	v_mfma_f32_16x16x32_bf16 v[70:73], v[170:173], v[216:219], v[70:73]
	v_mfma_f32_16x16x32_bf16 v[66:69], v[178:181], v[216:219], v[66:69]
	v_mfma_f32_16x16x32_bf16 v[118:121], v[174:177], v[196:199], v[118:121]
	v_mfma_f32_16x16x32_bf16 v[114:117], v[188:191], v[196:199], v[114:117]
	v_mfma_f32_16x16x32_bf16 v[102:105], v[174:177], v[204:207], v[102:105]
	v_mfma_f32_16x16x32_bf16 v[98:101], v[188:191], v[204:207], v[98:101]
	v_mfma_f32_16x16x32_bf16 v[86:89], v[174:177], v[212:215], v[86:89]
	v_mfma_f32_16x16x32_bf16 v[82:85], v[188:191], v[212:215], v[82:85]
	v_mfma_f32_16x16x32_bf16 v[70:73], v[174:177], v[220:223], v[70:73]
	v_mfma_f32_16x16x32_bf16 v[66:69], v[188:191], v[220:223], v[66:69]
	s_barrier
	s_add_i32 s95, s88, s38
	s_mov_b64 s[98:99], s[34:35]
	s_mov_b32 m0, s95
	ds_read_b128 v[192:195], v153 offset:16384
	ds_read_b128 v[196:199], v153 offset:17408
	ds_read_b128 v[200:203], v153 offset:18432
	ds_read_b128 v[204:207], v153 offset:19456
	ds_read_b128 v[208:211], v153 offset:20480
	ds_read_b128 v[212:215], v153 offset:21504
	ds_read_b128 v[216:219], v153 offset:22528
	ds_read_b128 v[220:223], v153 offset:23552
	global_load_lds_dwordx4 v132, s[34:35]
	s_add_i32 m0, s95, 0x2000
	s_add_u32 vcc_lo, s34, 0x100000
	s_mov_b64 s[98:99], s[34:35]
	s_addc_u32 vcc_hi, s35, 0
	s_add_i32 s95, s89, s38
	global_load_lds_dwordx4 v136, s[34:35]
	s_mov_b32 m0, s95
	s_mov_b64 s[100:101], s[36:37]
	global_load_lds_dwordx4 v132, vcc
	s_add_i32 m0, s95, 0x2000
	s_nop 0
	global_load_lds_dwordx4 v136, vcc
	s_mov_b64 s[100:101], s[36:37]
	s_mov_b32 m0, s39
	s_nop 0
	global_load_lds_dwordx4 v130, s[36:37]
	s_mov_b32 m0, s40
	s_nop 0
	global_load_lds_dwordx4 v134, s[36:37]
	s_waitcnt vmcnt(8) lgkmcnt(0)
	s_barrier
	v_mfma_f32_16x16x32_bf16 v[62:65], v[154:157], v[192:195], v[62:65]
	v_mfma_f32_16x16x32_bf16 v[58:61], v[162:165], v[192:195], v[58:61]
	v_mfma_f32_16x16x32_bf16 v[46:49], v[154:157], v[200:203], v[46:49]
	v_mfma_f32_16x16x32_bf16 v[42:45], v[162:165], v[200:203], v[42:45]
	v_mfma_f32_16x16x32_bf16 v[30:33], v[154:157], v[208:211], v[30:33]
	v_mfma_f32_16x16x32_bf16 v[26:29], v[162:165], v[208:211], v[26:29]
	v_mfma_f32_16x16x32_bf16 v[14:17], v[154:157], v[216:219], v[14:17]
	v_mfma_f32_16x16x32_bf16 v[10:13], v[162:165], v[216:219], v[10:13]
	v_mfma_f32_16x16x32_bf16 v[62:65], v[158:161], v[196:199], v[62:65]
	v_mfma_f32_16x16x32_bf16 v[58:61], v[166:169], v[196:199], v[58:61]
	v_mfma_f32_16x16x32_bf16 v[46:49], v[158:161], v[204:207], v[46:49]
	v_mfma_f32_16x16x32_bf16 v[42:45], v[166:169], v[204:207], v[42:45]
	v_mfma_f32_16x16x32_bf16 v[30:33], v[158:161], v[212:215], v[30:33]
	v_mfma_f32_16x16x32_bf16 v[26:29], v[166:169], v[212:215], v[26:29]
	v_mfma_f32_16x16x32_bf16 v[14:17], v[158:161], v[220:223], v[14:17]
	v_mfma_f32_16x16x32_bf16 v[10:13], v[166:169], v[220:223], v[10:13]
	v_mfma_f32_16x16x32_bf16 v[54:57], v[170:173], v[192:195], v[54:57]
	v_mfma_f32_16x16x32_bf16 v[50:53], v[178:181], v[192:195], v[50:53]
	v_mfma_f32_16x16x32_bf16 v[38:41], v[170:173], v[200:203], v[38:41]
	v_mfma_f32_16x16x32_bf16 v[34:37], v[178:181], v[200:203], v[34:37]
	v_mfma_f32_16x16x32_bf16 v[22:25], v[170:173], v[208:211], v[22:25]
	v_mfma_f32_16x16x32_bf16 v[18:21], v[178:181], v[208:211], v[18:21]
	v_mfma_f32_16x16x32_bf16 v[6:9], v[170:173], v[216:219], v[6:9]
	v_mfma_f32_16x16x32_bf16 v[2:5], v[178:181], v[216:219], v[2:5]
	v_mfma_f32_16x16x32_bf16 v[54:57], v[174:177], v[196:199], v[54:57]
	v_mfma_f32_16x16x32_bf16 v[50:53], v[188:191], v[196:199], v[50:53]
	v_mfma_f32_16x16x32_bf16 v[38:41], v[174:177], v[204:207], v[38:41]
	v_mfma_f32_16x16x32_bf16 v[34:37], v[188:191], v[204:207], v[34:37]
	v_mfma_f32_16x16x32_bf16 v[22:25], v[174:177], v[212:215], v[22:25]
	v_mfma_f32_16x16x32_bf16 v[18:21], v[188:191], v[212:215], v[18:21]
	v_mfma_f32_16x16x32_bf16 v[6:9], v[174:177], v[220:223], v[6:9]
	v_mfma_f32_16x16x32_bf16 v[2:5], v[188:191], v[220:223], v[2:5]
	s_barrier
; #define PG8_STAGE(bufoff, gbase, voff) do { _Pragma("unroll") for (int _i = 0; _i < 2; ++_i) \
;         __builtin_amdgcn_global_load_lds((const unsigned*)((const char*)(gbase) + (voff)[_i]), (PG8_LAS unsigned*)(lds + (bufoff) + ldsw + _i * 8192), 16, 0, 0); } while (0)
; #define PG8_LDA(dst, b, h) do { _Pragma("unroll") for (int m = 0; m < 4; ++m) _Pragma("unroll") for (int k = 0; k < 2; ++k) dst[m][k] = *(const PG8_LAS bf16x8*)(lds + PG8_SA(b, h) + aoff + m * 2048 + k * 1024); } while (0)
; #define PG8_LDB(dst, b, h) do { _Pragma("unroll") for (int n = 0; n < 2; ++n) _Pragma("unroll") for (int k = 0; k < 2; ++k) dst[n][k] = *(const PG8_LAS bf16x8*)(lds + PG8_SB(b, h) + boff + n * 2048 + k * 1024); } while (0)
; #define PG8_MMA(ai, bj, At, Bt) do { __builtin_amdgcn_s_setprio(1); _Pragma("unroll") for (int m = 0; m < 4; ++m) _Pragma("unroll") for (int n = 0; n < 2; ++n) _Pragma("unroll") for (int k = 0; k < 2; ++k) \
;         acc[ai][bj][m][n] = mma_<I8>(Bt[n][k], At[m][k], acc[ai][bj][m][n]); __builtin_amdgcn_s_setprio(0); } while (0)
; #define PG8_WAIT_V(n) asm volatile("s_waitcnt vmcnt(" #n ")" ::: "memory")
; #define PG8_WAIT_L(n) asm volatile("s_waitcnt lgkmcnt(" #n ")" ::: "memory")
; #define PG8_BAR __builtin_amdgcn_s_barrier()
; #define PG8_SCHED __builtin_amdgcn_sched_barrier(0)
; template <class Epi, class Sched, bool ALIGN_EPI = false, bool SP2 = false, bool I8 = false>
; __device__ __forceinline__ void gemm_phase(PG8_LAS unsigned char* lds, const Gemm g, const Sched& S, const Epi& E) {
;     ...
;         for (int t = 0; t < nt; t += 2) {
;     ...
;             PG8_LDB(B0, 1, 0); PG8_LDB(B1, 1, 1); PG8_SCHED; PG8_LDA(At, 1, 0); PG8_STAGE(PG8_SA(0, 1), a2 + hstepA, voffA);
;             PG8_WAIT_V(8); PG8_WAIT_L(0); PG8_BAR; PG8_MMA(0, 0, At, B0); PG8_MMA(0, 1, At, B1); PG8_BAR; PG8_SCHED;
;             PG8_LDA(At, 1, 1); PG8_STAGE(PG8_SB(1, 0), b3, voffB); PG8_STAGE(PG8_SB(1, 1), b3 + hstepB, voffB); PG8_STAGE(PG8_SA(1, 0), a3, voffA);
;             PG8_WAIT_V(8); PG8_WAIT_L(0); PG8_BAR; PG8_MMA(1, 0, At, B0); PG8_MMA(1, 1, At, B1); PG8_BAR; PG8_SCHED;
	s_add_i32 s95, 0, 0x18000
	s_add_i32 vcc_lo, 0, 0x1c000
	v_add_u32_e32 v166, s95, v147
	v_add_u32_e32 v187, vcc_lo, v147
	ds_read_b128 v[154:157], v166
	ds_read_b128 v[158:161], v166 offset:1024
	ds_read_b128 v[162:165], v166 offset:2048
	ds_read_b128 v[166:169], v166 offset:3072
	ds_read_b128 v[170:173], v187
	ds_read_b128 v[174:177], v187 offset:1024
	ds_read_b128 v[178:181], v187 offset:2048
	ds_read_b128 v[188:191], v187 offset:3072
	s_add_u32 s36, s36, 0x100000
	s_addc_u32 s37, s37, 0
	s_mov_b32 m0, s41
	ds_read_b128 v[192:195], v153 offset:32768
	ds_read_b128 v[196:199], v153 offset:33792
	ds_read_b128 v[200:203], v153 offset:34816
	ds_read_b128 v[204:207], v153 offset:35840
	ds_read_b128 v[208:211], v153 offset:36864
	ds_read_b128 v[212:215], v153 offset:37888
	ds_read_b128 v[216:219], v153 offset:38912
	ds_read_b128 v[220:223], v153 offset:39936
	global_load_lds_dwordx4 v130, s[36:37]
	s_mov_b32 m0, s46
	s_nop 0
	global_load_lds_dwordx4 v134, s[36:37]
	s_waitcnt vmcnt(8) lgkmcnt(0)
	s_barrier
	v_mfma_f32_16x16x32_bf16 v[126:129], v[154:157], v[192:195], v[126:129]
	v_mfma_f32_16x16x32_bf16 v[122:125], v[162:165], v[192:195], v[122:125]
	v_mfma_f32_16x16x32_bf16 v[110:113], v[154:157], v[200:203], v[110:113]
	v_mfma_f32_16x16x32_bf16 v[106:109], v[162:165], v[200:203], v[106:109]
	v_mfma_f32_16x16x32_bf16 v[94:97], v[154:157], v[208:211], v[94:97]
	v_mfma_f32_16x16x32_bf16 v[90:93], v[162:165], v[208:211], v[90:93]
	v_mfma_f32_16x16x32_bf16 v[78:81], v[154:157], v[216:219], v[78:81]
	v_mfma_f32_16x16x32_bf16 v[74:77], v[162:165], v[216:219], v[74:77]
	v_mfma_f32_16x16x32_bf16 v[126:129], v[158:161], v[196:199], v[126:129]
	v_mfma_f32_16x16x32_bf16 v[122:125], v[166:169], v[196:199], v[122:125]
	v_mfma_f32_16x16x32_bf16 v[110:113], v[158:161], v[204:207], v[110:113]
	v_mfma_f32_16x16x32_bf16 v[106:109], v[166:169], v[204:207], v[106:109]
	v_mfma_f32_16x16x32_bf16 v[94:97], v[158:161], v[212:215], v[94:97]
	v_mfma_f32_16x16x32_bf16 v[90:93], v[166:169], v[212:215], v[90:93]
	v_mfma_f32_16x16x32_bf16 v[78:81], v[158:161], v[220:223], v[78:81]
	v_mfma_f32_16x16x32_bf16 v[74:77], v[166:169], v[220:223], v[74:77]
	v_mfma_f32_16x16x32_bf16 v[118:121], v[170:173], v[192:195], v[118:121]
	v_mfma_f32_16x16x32_bf16 v[114:117], v[178:181], v[192:195], v[114:117]
	v_mfma_f32_16x16x32_bf16 v[102:105], v[170:173], v[200:203], v[102:105]
	v_mfma_f32_16x16x32_bf16 v[98:101], v[178:181], v[200:203], v[98:101]
	v_mfma_f32_16x16x32_bf16 v[86:89], v[170:173], v[208:211], v[86:89]
	v_mfma_f32_16x16x32_bf16 v[82:85], v[178:181], v[208:211], v[82:85]
	v_mfma_f32_16x16x32_bf16 v[70:73], v[170:173], v[216:219], v[70:73]
	v_mfma_f32_16x16x32_bf16 v[66:69], v[178:181], v[216:219], v[66:69]
	v_mfma_f32_16x16x32_bf16 v[118:121], v[174:177], v[196:199], v[118:121]
	v_mfma_f32_16x16x32_bf16 v[114:117], v[188:191], v[196:199], v[114:117]
	v_mfma_f32_16x16x32_bf16 v[102:105], v[174:177], v[204:207], v[102:105]
	v_mfma_f32_16x16x32_bf16 v[98:101], v[188:191], v[204:207], v[98:101]
	v_mfma_f32_16x16x32_bf16 v[86:89], v[174:177], v[212:215], v[86:89]
	v_mfma_f32_16x16x32_bf16 v[82:85], v[188:191], v[212:215], v[82:85]
	v_mfma_f32_16x16x32_bf16 v[70:73], v[174:177], v[220:223], v[70:73]
	v_mfma_f32_16x16x32_bf16 v[66:69], v[188:191], v[220:223], v[66:69]
	s_barrier
	s_add_i32 s36, s95, s38
	s_add_i32 m0, s36, 0xffffff80
	ds_read_b128 v[192:195], v153 offset:49152
	ds_read_b128 v[196:199], v153 offset:50176
	ds_read_b128 v[200:203], v153 offset:51200
	ds_read_b128 v[204:207], v153 offset:52224
	ds_read_b128 v[208:211], v153 offset:53248
	ds_read_b128 v[212:215], v153 offset:54272
	ds_read_b128 v[216:219], v153 offset:55296
	ds_read_b128 v[220:223], v153 offset:56320
	global_load_lds_dwordx4 v132, s[98:99] offset:128
	s_add_i32 m0, s36, 0x1f80
	s_add_u32 s34, s34, 0x100080
	s_addc_u32 s35, s35, 0
	s_add_i32 s36, vcc_lo, s38
	global_load_lds_dwordx4 v136, s[98:99] offset:128
	s_mov_b32 m0, s36
	s_nop 0
	global_load_lds_dwordx4 v132, s[34:35]
	s_add_i32 m0, s36, 0x2000
	s_nop 0
	global_load_lds_dwordx4 v136, s[34:35]
	s_add_i32 m0, s68, 0xffffff80
	s_nop 0
	global_load_lds_dwordx4 v130, s[100:101] offset:128
	s_add_i32 m0, s69, 0xffffff80
	s_nop 0
	global_load_lds_dwordx4 v134, s[100:101] offset:128
	s_waitcnt vmcnt(8) lgkmcnt(0)
	s_barrier
	v_mfma_f32_16x16x32_bf16 v[62:65], v[154:157], v[192:195], v[62:65]
	v_mfma_f32_16x16x32_bf16 v[58:61], v[162:165], v[192:195], v[58:61]
	v_mfma_f32_16x16x32_bf16 v[46:49], v[154:157], v[200:203], v[46:49]
	v_mfma_f32_16x16x32_bf16 v[42:45], v[162:165], v[200:203], v[42:45]
	v_mfma_f32_16x16x32_bf16 v[30:33], v[154:157], v[208:211], v[30:33]
	v_mfma_f32_16x16x32_bf16 v[26:29], v[162:165], v[208:211], v[26:29]
	v_mfma_f32_16x16x32_bf16 v[14:17], v[154:157], v[216:219], v[14:17]
	v_mfma_f32_16x16x32_bf16 v[10:13], v[162:165], v[216:219], v[10:13]
	v_mfma_f32_16x16x32_bf16 v[62:65], v[158:161], v[196:199], v[62:65]
	v_mfma_f32_16x16x32_bf16 v[58:61], v[166:169], v[196:199], v[58:61]
	v_mfma_f32_16x16x32_bf16 v[46:49], v[158:161], v[204:207], v[46:49]
	v_mfma_f32_16x16x32_bf16 v[42:45], v[166:169], v[204:207], v[42:45]
	v_mfma_f32_16x16x32_bf16 v[30:33], v[158:161], v[212:215], v[30:33]
	v_mfma_f32_16x16x32_bf16 v[26:29], v[166:169], v[212:215], v[26:29]
	v_mfma_f32_16x16x32_bf16 v[14:17], v[158:161], v[220:223], v[14:17]
	v_mfma_f32_16x16x32_bf16 v[10:13], v[166:169], v[220:223], v[10:13]
	v_mfma_f32_16x16x32_bf16 v[54:57], v[170:173], v[192:195], v[54:57]
	v_mfma_f32_16x16x32_bf16 v[50:53], v[178:181], v[192:195], v[50:53]
	v_mfma_f32_16x16x32_bf16 v[38:41], v[170:173], v[200:203], v[38:41]
	v_mfma_f32_16x16x32_bf16 v[34:37], v[178:181], v[200:203], v[34:37]
	v_mfma_f32_16x16x32_bf16 v[22:25], v[170:173], v[208:211], v[22:25]
	v_mfma_f32_16x16x32_bf16 v[18:21], v[178:181], v[208:211], v[18:21]
	v_mfma_f32_16x16x32_bf16 v[6:9], v[170:173], v[216:219], v[6:9]
	v_mfma_f32_16x16x32_bf16 v[2:5], v[178:181], v[216:219], v[2:5]
	v_mfma_f32_16x16x32_bf16 v[54:57], v[174:177], v[196:199], v[54:57]
	v_mfma_f32_16x16x32_bf16 v[50:53], v[188:191], v[196:199], v[50:53]
	v_mfma_f32_16x16x32_bf16 v[38:41], v[174:177], v[204:207], v[38:41]
	v_mfma_f32_16x16x32_bf16 v[34:37], v[188:191], v[204:207], v[34:37]
	v_mfma_f32_16x16x32_bf16 v[22:25], v[174:177], v[212:215], v[22:25]
	v_mfma_f32_16x16x32_bf16 v[18:21], v[188:191], v[212:215], v[18:21]
	v_mfma_f32_16x16x32_bf16 v[6:9], v[174:177], v[220:223], v[6:9]
	v_mfma_f32_16x16x32_bf16 v[2:5], v[188:191], v[220:223], v[2:5]
	s_barrier
	s_add_i32 s94, s94, 2
	s_add_u32 s30, s30, 0x100
	s_addc_u32 s31, s31, 0
	s_add_u32 s92, s92, 0x100
	s_addc_u32 s93, s93, 0
	s_cmp_gt_u32 s94, 61
	s_cbranch_scc0 .LBB0_541
	s_and_b64 vcc, exec, s[20:21]
	s_cbranch_vccz .LBB0_544
	s_barrier

; #define PG8_STAGE(bufoff, gbase, voff) do { _Pragma("unroll") for (int _i = 0; _i < 2; ++_i) \
;         __builtin_amdgcn_global_load_lds((const unsigned*)((const char*)(gbase) + (voff)[_i]), (PG8_LAS unsigned*)(lds + (bufoff) + ldsw + _i * 8192), 16, 0, 0); } while (0)
; #define PG8_LDA(dst, b, h) do { _Pragma("unroll") for (int m = 0; m < 4; ++m) _Pragma("unroll") for (int k = 0; k < 2; ++k) dst[m][k] = *(const PG8_LAS bf16x8*)(lds + PG8_SA(b, h) + aoff + m * 2048 + k * 1024); } while (0)
; #define PG8_LDB(dst, b, h) do { _Pragma("unroll") for (int n = 0; n < 2; ++n) _Pragma("unroll") for (int k = 0; k < 2; ++k) dst[n][k] = *(const PG8_LAS bf16x8*)(lds + PG8_SB(b, h) + boff + n * 2048 + k * 1024); } while (0)
; #define PG8_MMA(ai, bj, At, Bt) do { __builtin_amdgcn_s_setprio(1); _Pragma("unroll") for (int m = 0; m < 4; ++m) _Pragma("unroll") for (int n = 0; n < 2; ++n) _Pragma("unroll") for (int k = 0; k < 2; ++k) \
;         acc[ai][bj][m][n] = mma_<I8>(Bt[n][k], At[m][k], acc[ai][bj][m][n]); __builtin_amdgcn_s_setprio(0); } while (0)
; #define PG8_WAIT_V(n) asm volatile("s_waitcnt vmcnt(" #n ")" ::: "memory")
; #define PG8_WAIT_L(n) asm volatile("s_waitcnt lgkmcnt(" #n ")" ::: "memory")
; #define PG8_BAR __builtin_amdgcn_s_barrier()
; template <class Epi, class Sched, bool ALIGN_EPI = false, bool SP2 = false, bool I8 = false>
; __device__ __forceinline__ void gemm_phase(PG8_LAS unsigned char* lds, const Gemm g, const Sched& S, const Epi& E) {
;     ...
;             const bool last = (t == nt - 2);
;             const char* a1 = cA + (size_t)(t + 1) * kstep;
;             const char* a2 = last ? nA : cA + (size_t)(t + 2) * kstep; const char* b2 = last ? nB : cB + (size_t)(t + 2) * kstep;
;             const char* a3 = a2 + kstep; const char* b3 = b2 + kstep;
;             if (last && has_next) S.a_ready(nxt);
;             if constexpr (SP2) {
;             PG8_LDB(B0, 0, 0); PG8_LDB(B1, 0, 1); PG8_SCHED; PG8_LDA(At, 0, 0); PG8_STAGE(PG8_SA(1, 1), a1 + hstepA, voffA);
;             PG8_WAIT_V(8); PG8_WAIT_L(0); PG8_BAR; PG8_MMA(0, 0, At, B0); PG8_MMA(0, 1, At, B1); PG8_BAR; PG8_SCHED;
;             PG8_LDA(At, 0, 1); PG8_STAGE(PG8_SB(0, 0), b2, voffB); PG8_STAGE(PG8_SB(0, 1), b2 + hstepB, voffB); PG8_STAGE(PG8_SA(0, 0), a2, voffA);
;             PG8_WAIT_V(8); PG8_WAIT_L(0); PG8_BAR; PG8_MMA(1, 0, At, B0); PG8_MMA(1, 1, At, B1); PG8_BAR; PG8_SCHED;
.LBB0_607:
	ds_read_b128 v[58:61], v177
	ds_read_b128 v[62:65], v177 offset:1024
	ds_read_b128 v[74:77], v177 offset:2048
	ds_read_b128 v[78:81], v177 offset:3072
	ds_read_b128 v[162:165], v178
	ds_read_b128 v[166:169], v178 offset:1024
	ds_read_b128 v[170:173], v178 offset:2048
	ds_read_b128 v[180:183], v178 offset:3072
	s_add_u32 s34, s2, 0xfff80080
	s_addc_u32 s35, s3, -1
	s_cmp_eq_u32 s39, 28
	s_cselect_b32 s37, s7, s35
	s_cselect_b32 s36, s9, s34
	s_cselect_b32 s35, s23, s38
	s_cselect_b32 s34, s25, s31
	s_add_i32 m0, s69, 0xc000
	ds_read_b128 v[184:187], v179
	ds_read_b128 v[188:191], v179 offset:1024
	ds_read_b128 v[192:195], v179 offset:2048
	ds_read_b128 v[196:199], v179 offset:3072
	ds_read_b128 v[200:203], v179 offset:4096
	ds_read_b128 v[204:207], v179 offset:5120
	ds_read_b128 v[208:211], v179 offset:6144
	ds_read_b128 v[212:215], v179 offset:7168
	global_load_lds_dwordx4 v154, s[2:3]
	s_add_i32 m0, s69, 0xe000
	s_nop 0
	global_load_lds_dwordx4 v156, s[2:3]
	s_waitcnt vmcnt(8) lgkmcnt(0)
	s_barrier
	v_mfma_i32_16x16x64_i8 v[142:145], v[58:61], v[184:187], v[142:145]
	v_mfma_i32_16x16x64_i8 v[138:141], v[74:77], v[184:187], v[138:141]
	v_mfma_i32_16x16x64_i8 v[126:129], v[58:61], v[192:195], v[126:129]
	v_mfma_i32_16x16x64_i8 v[122:125], v[74:77], v[192:195], v[122:125]
	v_mfma_i32_16x16x64_i8 v[110:113], v[58:61], v[200:203], v[110:113]
	v_mfma_i32_16x16x64_i8 v[106:109], v[74:77], v[200:203], v[106:109]
	v_mfma_i32_16x16x64_i8 v[94:97], v[58:61], v[208:211], v[94:97]
	v_mfma_i32_16x16x64_i8 v[90:93], v[74:77], v[208:211], v[90:93]
	v_mfma_i32_16x16x64_i8 v[142:145], v[62:65], v[188:191], v[142:145]
	v_mfma_i32_16x16x64_i8 v[138:141], v[78:81], v[188:191], v[138:141]
	v_mfma_i32_16x16x64_i8 v[126:129], v[62:65], v[196:199], v[126:129]
	v_mfma_i32_16x16x64_i8 v[122:125], v[78:81], v[196:199], v[122:125]
	v_mfma_i32_16x16x64_i8 v[110:113], v[62:65], v[204:207], v[110:113]
	v_mfma_i32_16x16x64_i8 v[106:109], v[78:81], v[204:207], v[106:109]
	v_mfma_i32_16x16x64_i8 v[94:97], v[62:65], v[212:215], v[94:97]
	v_mfma_i32_16x16x64_i8 v[90:93], v[78:81], v[212:215], v[90:93]
	v_mfma_i32_16x16x64_i8 v[134:137], v[162:165], v[184:187], v[134:137]
	v_mfma_i32_16x16x64_i8 v[130:133], v[170:173], v[184:187], v[130:133]
	v_mfma_i32_16x16x64_i8 v[118:121], v[162:165], v[192:195], v[118:121]
	v_mfma_i32_16x16x64_i8 v[114:117], v[170:173], v[192:195], v[114:117]
	v_mfma_i32_16x16x64_i8 v[102:105], v[162:165], v[200:203], v[102:105]
	v_mfma_i32_16x16x64_i8 v[98:101], v[170:173], v[200:203], v[98:101]
	v_mfma_i32_16x16x64_i8 v[86:89], v[162:165], v[208:211], v[86:89]
	v_mfma_i32_16x16x64_i8 v[82:85], v[170:173], v[208:211], v[82:85]
	v_mfma_i32_16x16x64_i8 v[134:137], v[166:169], v[188:191], v[134:137]
	v_mfma_i32_16x16x64_i8 v[130:133], v[180:183], v[188:191], v[130:133]
	v_mfma_i32_16x16x64_i8 v[118:121], v[166:169], v[196:199], v[118:121]
	v_mfma_i32_16x16x64_i8 v[114:117], v[180:183], v[196:199], v[114:117]
	v_mfma_i32_16x16x64_i8 v[102:105], v[166:169], v[204:207], v[102:105]
	v_mfma_i32_16x16x64_i8 v[98:101], v[180:183], v[204:207], v[98:101]
	v_mfma_i32_16x16x64_i8 v[86:89], v[166:169], v[212:215], v[86:89]
	v_mfma_i32_16x16x64_i8 v[82:85], v[180:183], v[212:215], v[82:85]
	s_barrier
	s_add_i32 s40, s33, s68
	s_mov_b64 s[98:99], s[34:35]
	s_mov_b32 m0, s40
	ds_read_b128 v[184:187], v179 offset:16384
	ds_read_b128 v[188:191], v179 offset:17408
	ds_read_b128 v[192:195], v179 offset:18432
	ds_read_b128 v[196:199], v179 offset:19456
	ds_read_b128 v[200:203], v179 offset:20480
	ds_read_b128 v[204:207], v179 offset:21504
	ds_read_b128 v[208:211], v179 offset:22528
	ds_read_b128 v[212:215], v179 offset:23552
	global_load_lds_dwordx4 v148, s[34:35]
	s_add_i32 m0, s40, 0x2000
	s_add_u32 s40, s34, 0x80000
	s_mov_b64 s[98:99], s[34:35]
	s_addc_u32 s41, s35, 0
	s_add_i32 vcc_lo, s8, s68
	global_load_lds_dwordx4 v152, s[34:35]
	s_mov_b32 m0, vcc_lo
	s_mov_b64 s[100:101], s[36:37]
	global_load_lds_dwordx4 v148, s[40:41]
	s_add_i32 m0, vcc_lo, 0x2000
	s_nop 0
	global_load_lds_dwordx4 v152, s[40:41]
	s_mov_b64 s[100:101], s[36:37]
	s_mov_b32 m0, s69
	s_nop 0
	global_load_lds_dwordx4 v146, s[36:37]
	s_mov_b32 m0, s70
	s_nop 0
	global_load_lds_dwordx4 v150, s[36:37]
	s_waitcnt vmcnt(8) lgkmcnt(0)
	s_barrier
	v_mfma_i32_16x16x64_i8 v[70:73], v[58:61], v[184:187], v[70:73]
	v_mfma_i32_16x16x64_i8 v[66:69], v[74:77], v[184:187], v[66:69]
	v_mfma_i32_16x16x64_i8 v[46:49], v[58:61], v[192:195], v[46:49]
	v_mfma_i32_16x16x64_i8 v[42:45], v[74:77], v[192:195], v[42:45]
	v_mfma_i32_16x16x64_i8 v[30:33], v[58:61], v[200:203], v[30:33]
	v_mfma_i32_16x16x64_i8 v[26:29], v[74:77], v[200:203], v[26:29]
	v_mfma_i32_16x16x64_i8 v[14:17], v[58:61], v[208:211], v[14:17]
	v_mfma_i32_16x16x64_i8 v[10:13], v[74:77], v[208:211], v[10:13]
	v_mfma_i32_16x16x64_i8 v[70:73], v[62:65], v[188:191], v[70:73]
	v_mfma_i32_16x16x64_i8 v[66:69], v[78:81], v[188:191], v[66:69]
	v_mfma_i32_16x16x64_i8 v[46:49], v[62:65], v[196:199], v[46:49]
	v_mfma_i32_16x16x64_i8 v[42:45], v[78:81], v[196:199], v[42:45]
	v_mfma_i32_16x16x64_i8 v[30:33], v[62:65], v[204:207], v[30:33]
	v_mfma_i32_16x16x64_i8 v[26:29], v[78:81], v[204:207], v[26:29]
	v_mfma_i32_16x16x64_i8 v[14:17], v[62:65], v[212:215], v[14:17]
	v_mfma_i32_16x16x64_i8 v[10:13], v[78:81], v[212:215], v[10:13]
	v_mfma_i32_16x16x64_i8 v[54:57], v[162:165], v[184:187], v[54:57]
	v_mfma_i32_16x16x64_i8 v[50:53], v[170:173], v[184:187], v[50:53]
	v_mfma_i32_16x16x64_i8 v[38:41], v[162:165], v[192:195], v[38:41]
	v_mfma_i32_16x16x64_i8 v[34:37], v[170:173], v[192:195], v[34:37]
	v_mfma_i32_16x16x64_i8 v[22:25], v[162:165], v[200:203], v[22:25]
	v_mfma_i32_16x16x64_i8 v[18:21], v[170:173], v[200:203], v[18:21]
	v_mfma_i32_16x16x64_i8 v[6:9], v[162:165], v[208:211], v[6:9]
	v_mfma_i32_16x16x64_i8 v[2:5], v[170:173], v[208:211], v[2:5]
	v_mfma_i32_16x16x64_i8 v[54:57], v[166:169], v[188:191], v[54:57]
	v_mfma_i32_16x16x64_i8 v[50:53], v[180:183], v[188:191], v[50:53]
	v_mfma_i32_16x16x64_i8 v[38:41], v[166:169], v[196:199], v[38:41]
	v_mfma_i32_16x16x64_i8 v[34:37], v[180:183], v[196:199], v[34:37]
	v_mfma_i32_16x16x64_i8 v[22:25], v[166:169], v[204:207], v[22:25]
	v_mfma_i32_16x16x64_i8 v[18:21], v[180:183], v[204:207], v[18:21]
	v_mfma_i32_16x16x64_i8 v[6:9], v[166:169], v[212:215], v[6:9]
	v_mfma_i32_16x16x64_i8 v[2:5], v[180:183], v[212:215], v[2:5]
	s_barrier
; #define PG8_STAGE(bufoff, gbase, voff) do { _Pragma("unroll") for (int _i = 0; _i < 2; ++_i) \
;         __builtin_amdgcn_global_load_lds((const unsigned*)((const char*)(gbase) + (voff)[_i]), (PG8_LAS unsigned*)(lds + (bufoff) + ldsw + _i * 8192), 16, 0, 0); } while (0)
; #define PG8_LDA(dst, b, h) do { _Pragma("unroll") for (int m = 0; m < 4; ++m) _Pragma("unroll") for (int k = 0; k < 2; ++k) dst[m][k] = *(const PG8_LAS bf16x8*)(lds + PG8_SA(b, h) + aoff + m * 2048 + k * 1024); } while (0)
; #define PG8_LDB(dst, b, h) do { _Pragma("unroll") for (int n = 0; n < 2; ++n) _Pragma("unroll") for (int k = 0; k < 2; ++k) dst[n][k] = *(const PG8_LAS bf16x8*)(lds + PG8_SB(b, h) + boff + n * 2048 + k * 1024); } while (0)
; #define PG8_MMA(ai, bj, At, Bt) do { __builtin_amdgcn_s_setprio(1); _Pragma("unroll") for (int m = 0; m < 4; ++m) _Pragma("unroll") for (int n = 0; n < 2; ++n) _Pragma("unroll") for (int k = 0; k < 2; ++k) \
;         acc[ai][bj][m][n] = mma_<I8>(Bt[n][k], At[m][k], acc[ai][bj][m][n]); __builtin_amdgcn_s_setprio(0); } while (0)
; #define PG8_WAIT_V(n) asm volatile("s_waitcnt vmcnt(" #n ")" ::: "memory")
; #define PG8_WAIT_L(n) asm volatile("s_waitcnt lgkmcnt(" #n ")" ::: "memory")
; #define PG8_BAR __builtin_amdgcn_s_barrier()
; #define PG8_SCHED __builtin_amdgcn_sched_barrier(0)
; template <class Epi, class Sched, bool ALIGN_EPI = false, bool SP2 = false, bool I8 = false>
; __device__ __forceinline__ void gemm_phase(PG8_LAS unsigned char* lds, const Gemm g, const Sched& S, const Epi& E) {
;     ...
;         for (int t = 0; t < nt; t += 2) {
;     ...
;             PG8_LDB(B0, 1, 0); PG8_LDB(B1, 1, 1); PG8_SCHED; PG8_LDA(At, 1, 0); PG8_STAGE(PG8_SA(0, 1), a2 + hstepA, voffA);
;             PG8_WAIT_V(8); PG8_WAIT_L(0); PG8_BAR; PG8_MMA(0, 0, At, B0); PG8_MMA(0, 1, At, B1); PG8_BAR; PG8_SCHED;
;             PG8_LDA(At, 1, 1); PG8_STAGE(PG8_SB(1, 0), b3, voffB); PG8_STAGE(PG8_SB(1, 1), b3 + hstepB, voffB); PG8_STAGE(PG8_SA(1, 0), a3, voffA);
;             PG8_WAIT_V(8); PG8_WAIT_L(0); PG8_BAR; PG8_MMA(1, 0, At, B0); PG8_MMA(1, 1, At, B1); PG8_BAR; PG8_SCHED;
	s_add_i32 s40, 0, 0x18000
	s_add_i32 s41, 0, 0x1c000
	v_add_u32_e32 v78, s40, v176
	v_add_u32_e32 v180, s41, v176
	ds_read_b128 v[58:61], v78
	ds_read_b128 v[62:65], v78 offset:1024
	ds_read_b128 v[74:77], v78 offset:2048
	ds_read_b128 v[78:81], v78 offset:3072
	ds_read_b128 v[162:165], v180
	ds_read_b128 v[166:169], v180 offset:1024
	ds_read_b128 v[170:173], v180 offset:2048
	ds_read_b128 v[180:183], v180 offset:3072
	s_add_u32 s36, s36, 0x80000
	s_addc_u32 s37, s37, 0
	s_mov_b32 m0, s71
	ds_read_b128 v[184:187], v179 offset:32768
	ds_read_b128 v[188:191], v179 offset:33792
	ds_read_b128 v[192:195], v179 offset:34816
	ds_read_b128 v[196:199], v179 offset:35840
	ds_read_b128 v[200:203], v179 offset:36864
	ds_read_b128 v[204:207], v179 offset:37888
	ds_read_b128 v[208:211], v179 offset:38912
	ds_read_b128 v[212:215], v179 offset:39936
	global_load_lds_dwordx4 v146, s[36:37]
	s_mov_b32 m0, s88
	s_nop 0
	global_load_lds_dwordx4 v150, s[36:37]
	s_waitcnt vmcnt(8) lgkmcnt(0)
	s_barrier
	v_mfma_i32_16x16x64_i8 v[142:145], v[58:61], v[184:187], v[142:145]
	v_mfma_i32_16x16x64_i8 v[138:141], v[74:77], v[184:187], v[138:141]
	v_mfma_i32_16x16x64_i8 v[126:129], v[58:61], v[192:195], v[126:129]
	v_mfma_i32_16x16x64_i8 v[122:125], v[74:77], v[192:195], v[122:125]
	v_mfma_i32_16x16x64_i8 v[110:113], v[58:61], v[200:203], v[110:113]
	v_mfma_i32_16x16x64_i8 v[106:109], v[74:77], v[200:203], v[106:109]
	v_mfma_i32_16x16x64_i8 v[94:97], v[58:61], v[208:211], v[94:97]
	v_mfma_i32_16x16x64_i8 v[90:93], v[74:77], v[208:211], v[90:93]
	v_mfma_i32_16x16x64_i8 v[142:145], v[62:65], v[188:191], v[142:145]
	v_mfma_i32_16x16x64_i8 v[138:141], v[78:81], v[188:191], v[138:141]
	v_mfma_i32_16x16x64_i8 v[126:129], v[62:65], v[196:199], v[126:129]
	v_mfma_i32_16x16x64_i8 v[122:125], v[78:81], v[196:199], v[122:125]
	v_mfma_i32_16x16x64_i8 v[110:113], v[62:65], v[204:207], v[110:113]
	v_mfma_i32_16x16x64_i8 v[106:109], v[78:81], v[204:207], v[106:109]
	v_mfma_i32_16x16x64_i8 v[94:97], v[62:65], v[212:215], v[94:97]
	v_mfma_i32_16x16x64_i8 v[90:93], v[78:81], v[212:215], v[90:93]
	v_mfma_i32_16x16x64_i8 v[134:137], v[162:165], v[184:187], v[134:137]
	v_mfma_i32_16x16x64_i8 v[130:133], v[170:173], v[184:187], v[130:133]
	v_mfma_i32_16x16x64_i8 v[118:121], v[162:165], v[192:195], v[118:121]
	v_mfma_i32_16x16x64_i8 v[114:117], v[170:173], v[192:195], v[114:117]
	v_mfma_i32_16x16x64_i8 v[102:105], v[162:165], v[200:203], v[102:105]
	v_mfma_i32_16x16x64_i8 v[98:101], v[170:173], v[200:203], v[98:101]
	v_mfma_i32_16x16x64_i8 v[86:89], v[162:165], v[208:211], v[86:89]
	v_mfma_i32_16x16x64_i8 v[82:85], v[170:173], v[208:211], v[82:85]
	v_mfma_i32_16x16x64_i8 v[134:137], v[166:169], v[188:191], v[134:137]
	v_mfma_i32_16x16x64_i8 v[130:133], v[180:183], v[188:191], v[130:133]
	v_mfma_i32_16x16x64_i8 v[118:121], v[166:169], v[196:199], v[118:121]
	v_mfma_i32_16x16x64_i8 v[114:117], v[180:183], v[196:199], v[114:117]
	v_mfma_i32_16x16x64_i8 v[102:105], v[166:169], v[204:207], v[102:105]
	v_mfma_i32_16x16x64_i8 v[98:101], v[180:183], v[204:207], v[98:101]
	v_mfma_i32_16x16x64_i8 v[86:89], v[166:169], v[212:215], v[86:89]
	v_mfma_i32_16x16x64_i8 v[82:85], v[180:183], v[212:215], v[82:85]
	s_barrier
	s_add_i32 s36, s40, s68
	s_add_i32 m0, s36, 0xffffff80
	ds_read_b128 v[184:187], v179 offset:49152
	ds_read_b128 v[188:191], v179 offset:50176
	ds_read_b128 v[192:195], v179 offset:51200
	ds_read_b128 v[196:199], v179 offset:52224
	ds_read_b128 v[200:203], v179 offset:53248
	ds_read_b128 v[204:207], v179 offset:54272
	ds_read_b128 v[208:211], v179 offset:55296
	ds_read_b128 v[212:215], v179 offset:56320
	global_load_lds_dwordx4 v148, s[98:99] offset:128
	s_add_i32 m0, s36, 0x1f80
	s_add_u32 s34, s34, 0x80080
	s_addc_u32 s35, s35, 0
	s_add_i32 s36, s41, s68
	global_load_lds_dwordx4 v152, s[98:99] offset:128
	s_mov_b32 m0, s36
	s_nop 0
	global_load_lds_dwordx4 v148, s[34:35]
	s_add_i32 m0, s36, 0x2000
	s_nop 0
	global_load_lds_dwordx4 v152, s[34:35]
	s_add_i32 m0, s92, 0xffffff80
	s_nop 0
	global_load_lds_dwordx4 v146, s[100:101] offset:128
	s_add_i32 m0, s93, 0xffffff80
	s_nop 0
	global_load_lds_dwordx4 v150, s[100:101] offset:128
	s_waitcnt vmcnt(8) lgkmcnt(0)
	s_barrier
	v_mfma_i32_16x16x64_i8 v[70:73], v[58:61], v[184:187], v[70:73]
	v_mfma_i32_16x16x64_i8 v[66:69], v[74:77], v[184:187], v[66:69]
	v_mfma_i32_16x16x64_i8 v[46:49], v[58:61], v[192:195], v[46:49]
	v_mfma_i32_16x16x64_i8 v[42:45], v[74:77], v[192:195], v[42:45]
	v_mfma_i32_16x16x64_i8 v[30:33], v[58:61], v[200:203], v[30:33]
	v_mfma_i32_16x16x64_i8 v[26:29], v[74:77], v[200:203], v[26:29]
	v_mfma_i32_16x16x64_i8 v[14:17], v[58:61], v[208:211], v[14:17]
	v_mfma_i32_16x16x64_i8 v[10:13], v[74:77], v[208:211], v[10:13]
	v_mfma_i32_16x16x64_i8 v[70:73], v[62:65], v[188:191], v[70:73]
	v_mfma_i32_16x16x64_i8 v[66:69], v[78:81], v[188:191], v[66:69]
	v_mfma_i32_16x16x64_i8 v[46:49], v[62:65], v[196:199], v[46:49]
	v_mfma_i32_16x16x64_i8 v[42:45], v[78:81], v[196:199], v[42:45]
	v_mfma_i32_16x16x64_i8 v[30:33], v[62:65], v[204:207], v[30:33]
	v_mfma_i32_16x16x64_i8 v[26:29], v[78:81], v[204:207], v[26:29]
	v_mfma_i32_16x16x64_i8 v[14:17], v[62:65], v[212:215], v[14:17]
	v_mfma_i32_16x16x64_i8 v[10:13], v[78:81], v[212:215], v[10:13]
	v_mfma_i32_16x16x64_i8 v[54:57], v[162:165], v[184:187], v[54:57]
	v_mfma_i32_16x16x64_i8 v[50:53], v[170:173], v[184:187], v[50:53]
	v_mfma_i32_16x16x64_i8 v[38:41], v[162:165], v[192:195], v[38:41]
	v_mfma_i32_16x16x64_i8 v[34:37], v[170:173], v[192:195], v[34:37]
	v_mfma_i32_16x16x64_i8 v[22:25], v[162:165], v[200:203], v[22:25]
	v_mfma_i32_16x16x64_i8 v[18:21], v[170:173], v[200:203], v[18:21]
	v_mfma_i32_16x16x64_i8 v[6:9], v[162:165], v[208:211], v[6:9]
	v_mfma_i32_16x16x64_i8 v[2:5], v[170:173], v[208:211], v[2:5]
	v_mfma_i32_16x16x64_i8 v[54:57], v[166:169], v[188:191], v[54:57]
	v_mfma_i32_16x16x64_i8 v[50:53], v[180:183], v[188:191], v[50:53]
	v_mfma_i32_16x16x64_i8 v[38:41], v[166:169], v[196:199], v[38:41]
	v_mfma_i32_16x16x64_i8 v[34:37], v[180:183], v[196:199], v[34:37]
	v_mfma_i32_16x16x64_i8 v[22:25], v[166:169], v[204:207], v[22:25]
	v_mfma_i32_16x16x64_i8 v[18:21], v[180:183], v[204:207], v[18:21]
	v_mfma_i32_16x16x64_i8 v[6:9], v[166:169], v[212:215], v[6:9]
	v_mfma_i32_16x16x64_i8 v[2:5], v[180:183], v[212:215], v[2:5]
	s_barrier
	s_add_i32 s39, s39, 2
	s_add_u32 s2, s2, 0x100
	s_addc_u32 s3, s3, 0
	s_add_u32 s31, s31, 0x100
	s_addc_u32 s38, s38, 0
	s_cmp_gt_u32 s39, 29
	s_cbranch_scc0 .LBB0_607
	s_and_b64 vcc, exec, s[20:21]
	s_cbranch_vccz .LBB0_610
	s_barrier

; #define PG8_STAGE(bufoff, gbase, voff) do { _Pragma("unroll") for (int _i = 0; _i < 2; ++_i) \
;         __builtin_amdgcn_global_load_lds((const unsigned*)((const char*)(gbase) + (voff)[_i]), (PG8_LAS unsigned*)(lds + (bufoff) + ldsw + _i * 8192), 16, 0, 0); } while (0)
; #define PG8_LDA(dst, b, h) do { _Pragma("unroll") for (int m = 0; m < 4; ++m) _Pragma("unroll") for (int k = 0; k < 2; ++k) dst[m][k] = *(const PG8_LAS bf16x8*)(lds + PG8_SA(b, h) + aoff + m * 2048 + k * 1024); } while (0)
; #define PG8_LDB(dst, b, h) do { _Pragma("unroll") for (int n = 0; n < 2; ++n) _Pragma("unroll") for (int k = 0; k < 2; ++k) dst[n][k] = *(const PG8_LAS bf16x8*)(lds + PG8_SB(b, h) + boff + n * 2048 + k * 1024); } while (0)
; #define PG8_MMA(ai, bj, At, Bt) do { __builtin_amdgcn_s_setprio(1); _Pragma("unroll") for (int m = 0; m < 4; ++m) _Pragma("unroll") for (int n = 0; n < 2; ++n) _Pragma("unroll") for (int k = 0; k < 2; ++k) \
;         acc[ai][bj][m][n] = mma_<I8>(Bt[n][k], At[m][k], acc[ai][bj][m][n]); __builtin_amdgcn_s_setprio(0); } while (0)
; #define PG8_WAIT_V(n) asm volatile("s_waitcnt vmcnt(" #n ")" ::: "memory")
; #define PG8_WAIT_L(n) asm volatile("s_waitcnt lgkmcnt(" #n ")" ::: "memory")
; #define PG8_BAR __builtin_amdgcn_s_barrier()
; template <class Epi, class Sched, bool ALIGN_EPI = false, bool SP2 = false, bool I8 = false>
; __device__ __forceinline__ void gemm_phase(PG8_LAS unsigned char* lds, const Gemm g, const Sched& S, const Epi& E) {
;     ...
;             const bool last = (t == nt - 2);
;             const char* a1 = cA + (size_t)(t + 1) * kstep;
;             const char* a2 = last ? nA : cA + (size_t)(t + 2) * kstep; const char* b2 = last ? nB : cB + (size_t)(t + 2) * kstep;
;             const char* a3 = a2 + kstep; const char* b3 = b2 + kstep;
;             if (last && has_next) S.a_ready(nxt);
;             if constexpr (SP2) {
;             PG8_LDB(B0, 0, 0); PG8_LDB(B1, 0, 1); PG8_SCHED; PG8_LDA(At, 0, 0); PG8_STAGE(PG8_SA(1, 1), a1 + hstepA, voffA);
;             PG8_WAIT_V(8); PG8_WAIT_L(0); PG8_BAR; PG8_MMA(0, 0, At, B0); PG8_MMA(0, 1, At, B1); PG8_BAR; PG8_SCHED;
;             PG8_LDA(At, 0, 1); PG8_STAGE(PG8_SB(0, 0), b2, voffB); PG8_STAGE(PG8_SB(0, 1), b2 + hstepB, voffB); PG8_STAGE(PG8_SA(0, 0), a2, voffA);
;             PG8_WAIT_V(8); PG8_WAIT_L(0); PG8_BAR; PG8_MMA(1, 0, At, B0); PG8_MMA(1, 1, At, B1); PG8_BAR; PG8_SCHED;
.LBB0_1092:
	ds_read_b128 v[58:61], v172
	ds_read_b128 v[62:65], v172 offset:1024
	ds_read_b128 v[74:77], v172 offset:2048
	ds_read_b128 v[78:81], v172 offset:3072
	ds_read_b128 v[164:167], v173
	ds_read_b128 v[168:171], v173 offset:1024
	ds_read_b128 v[176:179], v173 offset:2048
	ds_read_b128 v[180:183], v173 offset:3072
	s_add_i32 s47, s22, 2
	s_add_u32 s23, s8, 0xfffe0080
	s_addc_u32 s24, s9, -1
	s_cmp_eq_u32 s3, s22
	s_cselect_b32 s22, s20, s17
	s_cselect_b32 s25, s1, s24
	s_cselect_b32 s24, s0, s23
	s_cselect_b32 s23, s21, s19
	s_add_i32 m0, s33, 0xc000
	ds_read_b128 v[184:187], v174
	ds_read_b128 v[188:191], v174 offset:1024
	ds_read_b128 v[192:195], v174 offset:2048
	ds_read_b128 v[196:199], v174 offset:3072
	ds_read_b128 v[200:203], v174 offset:4096
	ds_read_b128 v[204:207], v174 offset:5120
	ds_read_b128 v[208:211], v174 offset:6144
	ds_read_b128 v[212:215], v174 offset:7168
	global_load_lds_dwordx4 v156, s[8:9]
	s_add_i32 m0, s33, 0xe000
	s_nop 0
	global_load_lds_dwordx4 v158, s[8:9]
	s_waitcnt vmcnt(8) lgkmcnt(0)
	s_barrier
	v_mfma_f32_16x16x32_bf16 v[142:145], v[58:61], v[184:187], v[142:145]
	v_mfma_f32_16x16x32_bf16 v[138:141], v[74:77], v[184:187], v[138:141]
	v_mfma_f32_16x16x32_bf16 v[126:129], v[58:61], v[192:195], v[126:129]
	v_mfma_f32_16x16x32_bf16 v[122:125], v[74:77], v[192:195], v[122:125]
	v_mfma_f32_16x16x32_bf16 v[110:113], v[58:61], v[200:203], v[110:113]
	v_mfma_f32_16x16x32_bf16 v[106:109], v[74:77], v[200:203], v[106:109]
	v_mfma_f32_16x16x32_bf16 v[94:97], v[58:61], v[208:211], v[94:97]
	v_mfma_f32_16x16x32_bf16 v[90:93], v[74:77], v[208:211], v[90:93]
	v_mfma_f32_16x16x32_bf16 v[142:145], v[62:65], v[188:191], v[142:145]
	v_mfma_f32_16x16x32_bf16 v[138:141], v[78:81], v[188:191], v[138:141]
	v_mfma_f32_16x16x32_bf16 v[126:129], v[62:65], v[196:199], v[126:129]
	v_mfma_f32_16x16x32_bf16 v[122:125], v[78:81], v[196:199], v[122:125]
	v_mfma_f32_16x16x32_bf16 v[110:113], v[62:65], v[204:207], v[110:113]
	v_mfma_f32_16x16x32_bf16 v[106:109], v[78:81], v[204:207], v[106:109]
	v_mfma_f32_16x16x32_bf16 v[94:97], v[62:65], v[212:215], v[94:97]
	v_mfma_f32_16x16x32_bf16 v[90:93], v[78:81], v[212:215], v[90:93]
	v_mfma_f32_16x16x32_bf16 v[134:137], v[164:167], v[184:187], v[134:137]
	v_mfma_f32_16x16x32_bf16 v[130:133], v[176:179], v[184:187], v[130:133]
	v_mfma_f32_16x16x32_bf16 v[118:121], v[164:167], v[192:195], v[118:121]
	v_mfma_f32_16x16x32_bf16 v[114:117], v[176:179], v[192:195], v[114:117]
	v_mfma_f32_16x16x32_bf16 v[102:105], v[164:167], v[200:203], v[102:105]
	v_mfma_f32_16x16x32_bf16 v[98:101], v[176:179], v[200:203], v[98:101]
	v_mfma_f32_16x16x32_bf16 v[86:89], v[164:167], v[208:211], v[86:89]
	v_mfma_f32_16x16x32_bf16 v[82:85], v[176:179], v[208:211], v[82:85]
	v_mfma_f32_16x16x32_bf16 v[134:137], v[168:171], v[188:191], v[134:137]
	v_mfma_f32_16x16x32_bf16 v[130:133], v[180:183], v[188:191], v[130:133]
	v_mfma_f32_16x16x32_bf16 v[118:121], v[168:171], v[196:199], v[118:121]
	v_mfma_f32_16x16x32_bf16 v[114:117], v[180:183], v[196:199], v[114:117]
	v_mfma_f32_16x16x32_bf16 v[102:105], v[168:171], v[204:207], v[102:105]
	v_mfma_f32_16x16x32_bf16 v[98:101], v[180:183], v[204:207], v[98:101]
	v_mfma_f32_16x16x32_bf16 v[86:89], v[168:171], v[212:215], v[86:89]
	v_mfma_f32_16x16x32_bf16 v[82:85], v[180:183], v[212:215], v[82:85]
	s_barrier
	s_add_i32 s56, s44, s30
	s_mov_b64 s[98:99], s[22:23]
	s_mov_b32 m0, s56
	ds_read_b128 v[184:187], v174 offset:16384
	ds_read_b128 v[188:191], v174 offset:17408
	ds_read_b128 v[192:195], v174 offset:18432
	ds_read_b128 v[196:199], v174 offset:19456
	ds_read_b128 v[200:203], v174 offset:20480
	ds_read_b128 v[204:207], v174 offset:21504
	ds_read_b128 v[208:211], v174 offset:22528
	ds_read_b128 v[212:215], v174 offset:23552
	global_load_lds_dwordx4 v148, s[22:23]
	s_add_i32 m0, s56, 0x2000
	s_add_u32 s56, s22, 0x20000
	s_mov_b64 s[98:99], s[22:23]
	s_addc_u32 s57, s23, 0
	s_add_i32 s58, s45, s30
	global_load_lds_dwordx4 v152, s[22:23]
	s_mov_b32 m0, s58
	s_mov_b64 s[100:101], s[24:25]
	global_load_lds_dwordx4 v148, s[56:57]
	s_add_i32 m0, s58, 0x2000
	s_nop 0
	global_load_lds_dwordx4 v152, s[56:57]
	s_mov_b64 s[100:101], s[24:25]
	s_mov_b32 m0, s33
	s_nop 0
	global_load_lds_dwordx4 v146, s[24:25]
	s_mov_b32 m0, s34
	s_nop 0
	global_load_lds_dwordx4 v150, s[24:25]
	s_waitcnt vmcnt(8) lgkmcnt(0)
	s_barrier
	v_mfma_f32_16x16x32_bf16 v[70:73], v[58:61], v[184:187], v[70:73]
	v_mfma_f32_16x16x32_bf16 v[66:69], v[74:77], v[184:187], v[66:69]
	v_mfma_f32_16x16x32_bf16 v[46:49], v[58:61], v[192:195], v[46:49]
	v_mfma_f32_16x16x32_bf16 v[42:45], v[74:77], v[192:195], v[42:45]
	v_mfma_f32_16x16x32_bf16 v[30:33], v[58:61], v[200:203], v[30:33]
	v_mfma_f32_16x16x32_bf16 v[26:29], v[74:77], v[200:203], v[26:29]
	v_mfma_f32_16x16x32_bf16 v[14:17], v[58:61], v[208:211], v[14:17]
	v_mfma_f32_16x16x32_bf16 v[10:13], v[74:77], v[208:211], v[10:13]
	v_mfma_f32_16x16x32_bf16 v[70:73], v[62:65], v[188:191], v[70:73]
	v_mfma_f32_16x16x32_bf16 v[66:69], v[78:81], v[188:191], v[66:69]
	v_mfma_f32_16x16x32_bf16 v[46:49], v[62:65], v[196:199], v[46:49]
	v_mfma_f32_16x16x32_bf16 v[42:45], v[78:81], v[196:199], v[42:45]
	v_mfma_f32_16x16x32_bf16 v[30:33], v[62:65], v[204:207], v[30:33]
	v_mfma_f32_16x16x32_bf16 v[26:29], v[78:81], v[204:207], v[26:29]
	v_mfma_f32_16x16x32_bf16 v[14:17], v[62:65], v[212:215], v[14:17]
	v_mfma_f32_16x16x32_bf16 v[10:13], v[78:81], v[212:215], v[10:13]
	v_mfma_f32_16x16x32_bf16 v[54:57], v[164:167], v[184:187], v[54:57]
	v_mfma_f32_16x16x32_bf16 v[50:53], v[176:179], v[184:187], v[50:53]
	v_mfma_f32_16x16x32_bf16 v[38:41], v[164:167], v[192:195], v[38:41]
	v_mfma_f32_16x16x32_bf16 v[34:37], v[176:179], v[192:195], v[34:37]
	v_mfma_f32_16x16x32_bf16 v[22:25], v[164:167], v[200:203], v[22:25]
	v_mfma_f32_16x16x32_bf16 v[18:21], v[176:179], v[200:203], v[18:21]
	v_mfma_f32_16x16x32_bf16 v[6:9], v[164:167], v[208:211], v[6:9]
	v_mfma_f32_16x16x32_bf16 v[2:5], v[176:179], v[208:211], v[2:5]
	v_mfma_f32_16x16x32_bf16 v[54:57], v[168:171], v[188:191], v[54:57]
	v_mfma_f32_16x16x32_bf16 v[50:53], v[180:183], v[188:191], v[50:53]
	v_mfma_f32_16x16x32_bf16 v[38:41], v[168:171], v[196:199], v[38:41]
	v_mfma_f32_16x16x32_bf16 v[34:37], v[180:183], v[196:199], v[34:37]
	v_mfma_f32_16x16x32_bf16 v[22:25], v[168:171], v[204:207], v[22:25]
	v_mfma_f32_16x16x32_bf16 v[18:21], v[180:183], v[204:207], v[18:21]
	v_mfma_f32_16x16x32_bf16 v[6:9], v[168:171], v[212:215], v[6:9]
	v_mfma_f32_16x16x32_bf16 v[2:5], v[180:183], v[212:215], v[2:5]
	s_barrier
; #define PG8_STAGE(bufoff, gbase, voff) do { _Pragma("unroll") for (int _i = 0; _i < 2; ++_i) \
;         __builtin_amdgcn_global_load_lds((const unsigned*)((const char*)(gbase) + (voff)[_i]), (PG8_LAS unsigned*)(lds + (bufoff) + ldsw + _i * 8192), 16, 0, 0); } while (0)
; #define PG8_LDA(dst, b, h) do { _Pragma("unroll") for (int m = 0; m < 4; ++m) _Pragma("unroll") for (int k = 0; k < 2; ++k) dst[m][k] = *(const PG8_LAS bf16x8*)(lds + PG8_SA(b, h) + aoff + m * 2048 + k * 1024); } while (0)
; #define PG8_LDB(dst, b, h) do { _Pragma("unroll") for (int n = 0; n < 2; ++n) _Pragma("unroll") for (int k = 0; k < 2; ++k) dst[n][k] = *(const PG8_LAS bf16x8*)(lds + PG8_SB(b, h) + boff + n * 2048 + k * 1024); } while (0)
; #define PG8_MMA(ai, bj, At, Bt) do { __builtin_amdgcn_s_setprio(1); _Pragma("unroll") for (int m = 0; m < 4; ++m) _Pragma("unroll") for (int n = 0; n < 2; ++n) _Pragma("unroll") for (int k = 0; k < 2; ++k) \
;         acc[ai][bj][m][n] = mma_<I8>(Bt[n][k], At[m][k], acc[ai][bj][m][n]); __builtin_amdgcn_s_setprio(0); } while (0)
; #define PG8_WAIT_V(n) asm volatile("s_waitcnt vmcnt(" #n ")" ::: "memory")
; #define PG8_WAIT_L(n) asm volatile("s_waitcnt lgkmcnt(" #n ")" ::: "memory")
; #define PG8_BAR __builtin_amdgcn_s_barrier()
; #define PG8_SCHED __builtin_amdgcn_sched_barrier(0)
; template <class Epi, class Sched, bool ALIGN_EPI = false, bool SP2 = false, bool I8 = false>
; __device__ __forceinline__ void gemm_phase(PG8_LAS unsigned char* lds, const Gemm g, const Sched& S, const Epi& E) {
;     ...
;         for (int t = 0; t < nt; t += 2) {
;     ...
;             PG8_LDB(B0, 1, 0); PG8_LDB(B1, 1, 1); PG8_SCHED; PG8_LDA(At, 1, 0); PG8_STAGE(PG8_SA(0, 1), a2 + hstepA, voffA);
;             PG8_WAIT_V(8); PG8_WAIT_L(0); PG8_BAR; PG8_MMA(0, 0, At, B0); PG8_MMA(0, 1, At, B1); PG8_BAR; PG8_SCHED;
;             PG8_LDA(At, 1, 1); PG8_STAGE(PG8_SB(1, 0), b3, voffB); PG8_STAGE(PG8_SB(1, 1), b3 + hstepB, voffB); PG8_STAGE(PG8_SA(1, 0), a3, voffA);
;             PG8_WAIT_V(8); PG8_WAIT_L(0); PG8_BAR; PG8_MMA(1, 0, At, B0); PG8_MMA(1, 1, At, B1); PG8_BAR; PG8_SCHED;
	s_add_i32 s56, 0, 0x18000
	s_add_i32 s57, 0, 0x1c000
	v_add_u32_e32 v78, s56, v1
	v_add_u32_e32 v154, s57, v1
	ds_read_b128 v[58:61], v78
	ds_read_b128 v[62:65], v78 offset:1024
	ds_read_b128 v[74:77], v78 offset:2048
	ds_read_b128 v[78:81], v78 offset:3072
	ds_read_b128 v[164:167], v154
	ds_read_b128 v[168:171], v154 offset:1024
	ds_read_b128 v[176:179], v154 offset:2048
	ds_read_b128 v[180:183], v154 offset:3072
	s_add_u32 s24, s24, 0x20000
	s_addc_u32 s25, s25, 0
	s_mov_b32 m0, s35
	ds_read_b128 v[184:187], v174 offset:32768
	ds_read_b128 v[188:191], v174 offset:33792
	ds_read_b128 v[192:195], v174 offset:34816
	ds_read_b128 v[196:199], v174 offset:35840
	ds_read_b128 v[200:203], v174 offset:36864
	ds_read_b128 v[204:207], v174 offset:37888
	ds_read_b128 v[208:211], v174 offset:38912
	ds_read_b128 v[212:215], v174 offset:39936
	global_load_lds_dwordx4 v146, s[24:25]
	s_mov_b32 m0, s36
	s_nop 0
	global_load_lds_dwordx4 v150, s[24:25]
	s_waitcnt vmcnt(8) lgkmcnt(0)
	s_barrier
	v_mfma_f32_16x16x32_bf16 v[142:145], v[58:61], v[184:187], v[142:145]
	v_mfma_f32_16x16x32_bf16 v[138:141], v[74:77], v[184:187], v[138:141]
	v_mfma_f32_16x16x32_bf16 v[126:129], v[58:61], v[192:195], v[126:129]
	v_mfma_f32_16x16x32_bf16 v[122:125], v[74:77], v[192:195], v[122:125]
	v_mfma_f32_16x16x32_bf16 v[110:113], v[58:61], v[200:203], v[110:113]
	v_mfma_f32_16x16x32_bf16 v[106:109], v[74:77], v[200:203], v[106:109]
	v_mfma_f32_16x16x32_bf16 v[94:97], v[58:61], v[208:211], v[94:97]
	v_mfma_f32_16x16x32_bf16 v[90:93], v[74:77], v[208:211], v[90:93]
	v_mfma_f32_16x16x32_bf16 v[142:145], v[62:65], v[188:191], v[142:145]
	v_mfma_f32_16x16x32_bf16 v[138:141], v[78:81], v[188:191], v[138:141]
	v_mfma_f32_16x16x32_bf16 v[126:129], v[62:65], v[196:199], v[126:129]
	v_mfma_f32_16x16x32_bf16 v[122:125], v[78:81], v[196:199], v[122:125]
	v_mfma_f32_16x16x32_bf16 v[110:113], v[62:65], v[204:207], v[110:113]
	v_mfma_f32_16x16x32_bf16 v[106:109], v[78:81], v[204:207], v[106:109]
	v_mfma_f32_16x16x32_bf16 v[94:97], v[62:65], v[212:215], v[94:97]
	v_mfma_f32_16x16x32_bf16 v[90:93], v[78:81], v[212:215], v[90:93]
	v_mfma_f32_16x16x32_bf16 v[134:137], v[164:167], v[184:187], v[134:137]
	v_mfma_f32_16x16x32_bf16 v[130:133], v[176:179], v[184:187], v[130:133]
	v_mfma_f32_16x16x32_bf16 v[118:121], v[164:167], v[192:195], v[118:121]
	v_mfma_f32_16x16x32_bf16 v[114:117], v[176:179], v[192:195], v[114:117]
	v_mfma_f32_16x16x32_bf16 v[102:105], v[164:167], v[200:203], v[102:105]
	v_mfma_f32_16x16x32_bf16 v[98:101], v[176:179], v[200:203], v[98:101]
	v_mfma_f32_16x16x32_bf16 v[86:89], v[164:167], v[208:211], v[86:89]
	v_mfma_f32_16x16x32_bf16 v[82:85], v[176:179], v[208:211], v[82:85]
	v_mfma_f32_16x16x32_bf16 v[134:137], v[168:171], v[188:191], v[134:137]
	v_mfma_f32_16x16x32_bf16 v[130:133], v[180:183], v[188:191], v[130:133]
	v_mfma_f32_16x16x32_bf16 v[118:121], v[168:171], v[196:199], v[118:121]
	v_mfma_f32_16x16x32_bf16 v[114:117], v[180:183], v[196:199], v[114:117]
	v_mfma_f32_16x16x32_bf16 v[102:105], v[168:171], v[204:207], v[102:105]
	v_mfma_f32_16x16x32_bf16 v[98:101], v[180:183], v[204:207], v[98:101]
	v_mfma_f32_16x16x32_bf16 v[86:89], v[168:171], v[212:215], v[86:89]
	v_mfma_f32_16x16x32_bf16 v[82:85], v[180:183], v[212:215], v[82:85]
	s_barrier
	s_add_i32 s24, s56, s30
	s_add_i32 m0, s24, 0xffffff80
	ds_read_b128 v[184:187], v174 offset:49152
	ds_read_b128 v[188:191], v174 offset:50176
	ds_read_b128 v[192:195], v174 offset:51200
	ds_read_b128 v[196:199], v174 offset:52224
	ds_read_b128 v[200:203], v174 offset:53248
	ds_read_b128 v[204:207], v174 offset:54272
	ds_read_b128 v[208:211], v174 offset:55296
	ds_read_b128 v[212:215], v174 offset:56320
	global_load_lds_dwordx4 v148, s[98:99] offset:128
	s_add_i32 m0, s24, 0x1f80
	s_add_u32 s22, s22, 0x20080
	s_addc_u32 s23, s23, 0
	s_add_i32 s24, s57, s30
	global_load_lds_dwordx4 v152, s[98:99] offset:128
	s_mov_b32 m0, s24
	s_nop 0
	global_load_lds_dwordx4 v148, s[22:23]
	s_add_i32 m0, s24, 0x2000
	s_nop 0
	global_load_lds_dwordx4 v152, s[22:23]
	s_add_i32 m0, s40, 0xffffff80
	s_nop 0
	global_load_lds_dwordx4 v146, s[100:101] offset:128
	s_add_i32 m0, s41, 0xffffff80
	s_nop 0
	global_load_lds_dwordx4 v150, s[100:101] offset:128
	s_waitcnt vmcnt(8) lgkmcnt(0)
	s_barrier
	v_mfma_f32_16x16x32_bf16 v[70:73], v[58:61], v[184:187], v[70:73]
	v_mfma_f32_16x16x32_bf16 v[66:69], v[74:77], v[184:187], v[66:69]
	v_mfma_f32_16x16x32_bf16 v[46:49], v[58:61], v[192:195], v[46:49]
	v_mfma_f32_16x16x32_bf16 v[42:45], v[74:77], v[192:195], v[42:45]
	v_mfma_f32_16x16x32_bf16 v[30:33], v[58:61], v[200:203], v[30:33]
	v_mfma_f32_16x16x32_bf16 v[26:29], v[74:77], v[200:203], v[26:29]
	v_mfma_f32_16x16x32_bf16 v[14:17], v[58:61], v[208:211], v[14:17]
	v_mfma_f32_16x16x32_bf16 v[10:13], v[74:77], v[208:211], v[10:13]
	v_mfma_f32_16x16x32_bf16 v[70:73], v[62:65], v[188:191], v[70:73]
	v_mfma_f32_16x16x32_bf16 v[66:69], v[78:81], v[188:191], v[66:69]
	v_mfma_f32_16x16x32_bf16 v[46:49], v[62:65], v[196:199], v[46:49]
	v_mfma_f32_16x16x32_bf16 v[42:45], v[78:81], v[196:199], v[42:45]
	v_mfma_f32_16x16x32_bf16 v[30:33], v[62:65], v[204:207], v[30:33]
	v_mfma_f32_16x16x32_bf16 v[26:29], v[78:81], v[204:207], v[26:29]
	v_mfma_f32_16x16x32_bf16 v[14:17], v[62:65], v[212:215], v[14:17]
	v_mfma_f32_16x16x32_bf16 v[10:13], v[78:81], v[212:215], v[10:13]
	v_mfma_f32_16x16x32_bf16 v[54:57], v[164:167], v[184:187], v[54:57]
	v_mfma_f32_16x16x32_bf16 v[50:53], v[176:179], v[184:187], v[50:53]
	v_mfma_f32_16x16x32_bf16 v[38:41], v[164:167], v[192:195], v[38:41]
	v_mfma_f32_16x16x32_bf16 v[34:37], v[176:179], v[192:195], v[34:37]
	v_mfma_f32_16x16x32_bf16 v[22:25], v[164:167], v[200:203], v[22:25]
	v_mfma_f32_16x16x32_bf16 v[18:21], v[176:179], v[200:203], v[18:21]
	v_mfma_f32_16x16x32_bf16 v[6:9], v[164:167], v[208:211], v[6:9]
	v_mfma_f32_16x16x32_bf16 v[2:5], v[176:179], v[208:211], v[2:5]
	v_mfma_f32_16x16x32_bf16 v[54:57], v[168:171], v[188:191], v[54:57]
	v_mfma_f32_16x16x32_bf16 v[50:53], v[180:183], v[188:191], v[50:53]
	v_mfma_f32_16x16x32_bf16 v[38:41], v[168:171], v[196:199], v[38:41]
	v_mfma_f32_16x16x32_bf16 v[34:37], v[180:183], v[196:199], v[34:37]
	v_mfma_f32_16x16x32_bf16 v[22:25], v[168:171], v[204:207], v[22:25]
	v_mfma_f32_16x16x32_bf16 v[18:21], v[180:183], v[204:207], v[18:21]
	v_mfma_f32_16x16x32_bf16 v[6:9], v[168:171], v[212:215], v[6:9]
	v_mfma_f32_16x16x32_bf16 v[2:5], v[180:183], v[212:215], v[2:5]
	s_barrier
	s_add_u32 s8, s8, 0x100
	s_addc_u32 s9, s9, 0
	s_add_u32 s17, s17, 0x100
	s_addc_u32 s19, s19, 0
	s_cmp_ge_u32 s47, s7
	s_mov_b32 s22, s47
	s_cbranch_scc0 .LBB0_1092
	s_and_b64 vcc, exec, s[14:15]
	s_cbranch_vccz .LBB0_1095
	s_barrier

; #define PG8_STAGE(bufoff, gbase, voff) do { _Pragma("unroll") for (int _i = 0; _i < 2; ++_i) \
;         __builtin_amdgcn_global_load_lds((const unsigned*)((const char*)(gbase) + (voff)[_i]), (PG8_LAS unsigned*)(lds + (bufoff) + ldsw + _i * 8192), 16, 0, 0); } while (0)
; #define PG8_LDA(dst, b, h) do { _Pragma("unroll") for (int m = 0; m < 4; ++m) _Pragma("unroll") for (int k = 0; k < 2; ++k) dst[m][k] = *(const PG8_LAS bf16x8*)(lds + PG8_SA(b, h) + aoff + m * 2048 + k * 1024); } while (0)
; #define PG8_LDB(dst, b, h) do { _Pragma("unroll") for (int n = 0; n < 2; ++n) _Pragma("unroll") for (int k = 0; k < 2; ++k) dst[n][k] = *(const PG8_LAS bf16x8*)(lds + PG8_SB(b, h) + boff + n * 2048 + k * 1024); } while (0)
; #define PG8_MMA(ai, bj, At, Bt) do { __builtin_amdgcn_s_setprio(1); _Pragma("unroll") for (int m = 0; m < 4; ++m) _Pragma("unroll") for (int n = 0; n < 2; ++n) _Pragma("unroll") for (int k = 0; k < 2; ++k) \
;         acc[ai][bj][m][n] = mma_<I8>(Bt[n][k], At[m][k], acc[ai][bj][m][n]); __builtin_amdgcn_s_setprio(0); } while (0)
; #define PG8_WAIT_V(n) asm volatile("s_waitcnt vmcnt(" #n ")" ::: "memory")
; #define PG8_WAIT_L(n) asm volatile("s_waitcnt lgkmcnt(" #n ")" ::: "memory")
; #define PG8_BAR __builtin_amdgcn_s_barrier()
; template <class Epi, class Sched, bool ALIGN_EPI = false, bool SP2 = false, bool I8 = false>
; __device__ __forceinline__ void gemm_phase(PG8_LAS unsigned char* lds, const Gemm g, const Sched& S, const Epi& E) {
;     ...
;             const bool last = (t == nt - 2);
;             const char* a1 = cA + (size_t)(t + 1) * kstep;
;             const char* a2 = last ? nA : cA + (size_t)(t + 2) * kstep; const char* b2 = last ? nB : cB + (size_t)(t + 2) * kstep;
;             const char* a3 = a2 + kstep; const char* b3 = b2 + kstep;
;             if (last && has_next) S.a_ready(nxt);
;             if constexpr (SP2) {
;             PG8_LDB(B0, 0, 0); PG8_LDB(B1, 0, 1); PG8_SCHED; PG8_LDA(At, 0, 0); PG8_STAGE(PG8_SA(1, 1), a1 + hstepA, voffA);
;             PG8_WAIT_V(8); PG8_WAIT_L(0); PG8_BAR; PG8_MMA(0, 0, At, B0); PG8_MMA(0, 1, At, B1); PG8_BAR; PG8_SCHED;
;             PG8_LDA(At, 0, 1); PG8_STAGE(PG8_SB(0, 0), b2, voffB); PG8_STAGE(PG8_SB(0, 1), b2 + hstepB, voffB); PG8_STAGE(PG8_SA(0, 0), a2, voffA);
;             PG8_WAIT_V(8); PG8_WAIT_L(0); PG8_BAR; PG8_MMA(1, 0, At, B0); PG8_MMA(1, 1, At, B1); PG8_BAR; PG8_SCHED;
.LBB0_1538:
	ds_read_b128 v[146:149], v154
	ds_read_b128 v[150:153], v154 offset:1024
	ds_read_b128 v[158:161], v154 offset:2048
	ds_read_b128 v[162:165], v154 offset:3072
	ds_read_b128 v[166:169], v155
	ds_read_b128 v[170:173], v155 offset:1024
	ds_read_b128 v[174:177], v155 offset:2048
	ds_read_b128 v[178:181], v155 offset:3072
	s_add_u32 s24, s22, 0xfffe0080
	s_addc_u32 s25, s23, -1
	s_cmp_eq_u32 s49, 4
	s_cselect_b32 s27, s15, s25
	s_cselect_b32 s26, s45, s24
	s_cselect_b32 s25, s13, s48
	s_cselect_b32 s24, s46, s47
	s_add_i32 m0, s21, 0xc000
	ds_read_b128 v[182:185], v156
	ds_read_b128 v[186:189], v156 offset:1024
	ds_read_b128 v[190:193], v156 offset:2048
	ds_read_b128 v[194:197], v156 offset:3072
	ds_read_b128 v[198:201], v156 offset:4096
	ds_read_b128 v[202:205], v156 offset:5120
	ds_read_b128 v[206:209], v156 offset:6144
	ds_read_b128 v[210:213], v156 offset:7168
	global_load_lds_dwordx4 v138, s[22:23]
	s_add_i32 m0, s21, 0xe000
	s_nop 0
	global_load_lds_dwordx4 v140, s[22:23]
	s_waitcnt vmcnt(8) lgkmcnt(0)
	s_barrier
	v_mfma_f32_16x16x32_bf16 v[126:129], v[146:149], v[182:185], v[126:129]
	v_mfma_f32_16x16x32_bf16 v[122:125], v[158:161], v[182:185], v[122:125]
	v_mfma_f32_16x16x32_bf16 v[114:117], v[146:149], v[190:193], v[114:117]
	v_mfma_f32_16x16x32_bf16 v[106:109], v[158:161], v[190:193], v[106:109]
	v_mfma_f32_16x16x32_bf16 v[94:97], v[146:149], v[198:201], v[94:97]
	v_mfma_f32_16x16x32_bf16 v[90:93], v[158:161], v[198:201], v[90:93]
	v_mfma_f32_16x16x32_bf16 v[86:89], v[146:149], v[206:209], v[86:89]
	v_mfma_f32_16x16x32_bf16 v[82:85], v[158:161], v[206:209], v[82:85]
	v_mfma_f32_16x16x32_bf16 v[126:129], v[150:153], v[186:189], v[126:129]
	v_mfma_f32_16x16x32_bf16 v[122:125], v[162:165], v[186:189], v[122:125]
	v_mfma_f32_16x16x32_bf16 v[114:117], v[150:153], v[194:197], v[114:117]
	v_mfma_f32_16x16x32_bf16 v[106:109], v[162:165], v[194:197], v[106:109]
	v_mfma_f32_16x16x32_bf16 v[94:97], v[150:153], v[202:205], v[94:97]
	v_mfma_f32_16x16x32_bf16 v[90:93], v[162:165], v[202:205], v[90:93]
	v_mfma_f32_16x16x32_bf16 v[86:89], v[150:153], v[210:213], v[86:89]
	v_mfma_f32_16x16x32_bf16 v[82:85], v[162:165], v[210:213], v[82:85]
	v_mfma_f32_16x16x32_bf16 v[118:121], v[166:169], v[182:185], v[118:121]
	v_mfma_f32_16x16x32_bf16 v[110:113], v[174:177], v[182:185], v[110:113]
	v_mfma_f32_16x16x32_bf16 v[102:105], v[166:169], v[190:193], v[102:105]
	v_mfma_f32_16x16x32_bf16 v[98:101], v[174:177], v[190:193], v[98:101]
	v_mfma_f32_16x16x32_bf16 v[78:81], v[166:169], v[198:201], v[78:81]
	v_mfma_f32_16x16x32_bf16 v[74:77], v[174:177], v[198:201], v[74:77]
	v_mfma_f32_16x16x32_bf16 v[70:73], v[166:169], v[206:209], v[70:73]
	v_mfma_f32_16x16x32_bf16 v[66:69], v[174:177], v[206:209], v[66:69]
	v_mfma_f32_16x16x32_bf16 v[118:121], v[170:173], v[186:189], v[118:121]
	v_mfma_f32_16x16x32_bf16 v[110:113], v[178:181], v[186:189], v[110:113]
	v_mfma_f32_16x16x32_bf16 v[102:105], v[170:173], v[194:197], v[102:105]
	v_mfma_f32_16x16x32_bf16 v[98:101], v[178:181], v[194:197], v[98:101]
	v_mfma_f32_16x16x32_bf16 v[78:81], v[170:173], v[202:205], v[78:81]
	v_mfma_f32_16x16x32_bf16 v[74:77], v[178:181], v[202:205], v[74:77]
	v_mfma_f32_16x16x32_bf16 v[70:73], v[170:173], v[210:213], v[70:73]
	v_mfma_f32_16x16x32_bf16 v[66:69], v[178:181], v[210:213], v[66:69]
	s_barrier
	s_add_i32 s50, s42, s34
	s_mov_b64 s[98:99], s[24:25]
	s_mov_b32 m0, s50
	ds_read_b128 v[182:185], v156 offset:16384
	ds_read_b128 v[186:189], v156 offset:17408
	ds_read_b128 v[190:193], v156 offset:18432
	ds_read_b128 v[194:197], v156 offset:19456
	ds_read_b128 v[198:201], v156 offset:20480
	ds_read_b128 v[202:205], v156 offset:21504
	ds_read_b128 v[206:209], v156 offset:22528
	ds_read_b128 v[210:213], v156 offset:23552
	global_load_lds_dwordx4 v132, s[24:25]
	s_add_i32 m0, s50, 0x2000
	s_add_u32 s50, s24, 0x20000
	s_mov_b64 s[98:99], s[24:25]
	s_addc_u32 s51, s25, 0
	s_add_i32 s52, s43, s34
	global_load_lds_dwordx4 v136, s[24:25]
	s_mov_b32 m0, s52
	s_mov_b64 s[100:101], s[26:27]
	global_load_lds_dwordx4 v132, s[50:51]
	s_add_i32 m0, s52, 0x2000
	s_nop 0
	global_load_lds_dwordx4 v136, s[50:51]
	s_mov_b64 s[100:101], s[26:27]
	s_mov_b32 m0, s21
	s_nop 0
	global_load_lds_dwordx4 v130, s[26:27]
	s_mov_b32 m0, s35
	s_nop 0
	global_load_lds_dwordx4 v134, s[26:27]
	s_waitcnt vmcnt(8) lgkmcnt(0)
	s_barrier
	v_mfma_f32_16x16x32_bf16 v[62:65], v[146:149], v[182:185], v[62:65]
	v_mfma_f32_16x16x32_bf16 v[58:61], v[158:161], v[182:185], v[58:61]
	v_mfma_f32_16x16x32_bf16 v[54:57], v[146:149], v[190:193], v[54:57]
	v_mfma_f32_16x16x32_bf16 v[50:53], v[158:161], v[190:193], v[50:53]
	v_mfma_f32_16x16x32_bf16 v[30:33], v[146:149], v[198:201], v[30:33]
	v_mfma_f32_16x16x32_bf16 v[26:29], v[158:161], v[198:201], v[26:29]
	v_mfma_f32_16x16x32_bf16 v[22:25], v[146:149], v[206:209], v[22:25]
	v_mfma_f32_16x16x32_bf16 v[10:13], v[158:161], v[206:209], v[10:13]
	v_mfma_f32_16x16x32_bf16 v[62:65], v[150:153], v[186:189], v[62:65]
	v_mfma_f32_16x16x32_bf16 v[58:61], v[162:165], v[186:189], v[58:61]
	v_mfma_f32_16x16x32_bf16 v[54:57], v[150:153], v[194:197], v[54:57]
	v_mfma_f32_16x16x32_bf16 v[50:53], v[162:165], v[194:197], v[50:53]
	v_mfma_f32_16x16x32_bf16 v[30:33], v[150:153], v[202:205], v[30:33]
	v_mfma_f32_16x16x32_bf16 v[26:29], v[162:165], v[202:205], v[26:29]
	v_mfma_f32_16x16x32_bf16 v[22:25], v[150:153], v[210:213], v[22:25]
	v_mfma_f32_16x16x32_bf16 v[10:13], v[162:165], v[210:213], v[10:13]
	v_mfma_f32_16x16x32_bf16 v[46:49], v[166:169], v[182:185], v[46:49]
	v_mfma_f32_16x16x32_bf16 v[42:45], v[174:177], v[182:185], v[42:45]
	v_mfma_f32_16x16x32_bf16 v[38:41], v[166:169], v[190:193], v[38:41]
	v_mfma_f32_16x16x32_bf16 v[34:37], v[174:177], v[190:193], v[34:37]
	v_mfma_f32_16x16x32_bf16 v[18:21], v[166:169], v[198:201], v[18:21]
	v_mfma_f32_16x16x32_bf16 v[14:17], v[174:177], v[198:201], v[14:17]
	v_mfma_f32_16x16x32_bf16 v[6:9], v[166:169], v[206:209], v[6:9]
	v_mfma_f32_16x16x32_bf16 v[2:5], v[174:177], v[206:209], v[2:5]
	v_mfma_f32_16x16x32_bf16 v[46:49], v[170:173], v[186:189], v[46:49]
	v_mfma_f32_16x16x32_bf16 v[42:45], v[178:181], v[186:189], v[42:45]
	v_mfma_f32_16x16x32_bf16 v[38:41], v[170:173], v[194:197], v[38:41]
	v_mfma_f32_16x16x32_bf16 v[34:37], v[178:181], v[194:197], v[34:37]
	v_mfma_f32_16x16x32_bf16 v[18:21], v[170:173], v[202:205], v[18:21]
	v_mfma_f32_16x16x32_bf16 v[14:17], v[178:181], v[202:205], v[14:17]
	v_mfma_f32_16x16x32_bf16 v[6:9], v[170:173], v[210:213], v[6:9]
	v_mfma_f32_16x16x32_bf16 v[2:5], v[178:181], v[210:213], v[2:5]
	s_barrier
; #define PG8_STAGE(bufoff, gbase, voff) do { _Pragma("unroll") for (int _i = 0; _i < 2; ++_i) \
;         __builtin_amdgcn_global_load_lds((const unsigned*)((const char*)(gbase) + (voff)[_i]), (PG8_LAS unsigned*)(lds + (bufoff) + ldsw + _i * 8192), 16, 0, 0); } while (0)
; #define PG8_LDA(dst, b, h) do { _Pragma("unroll") for (int m = 0; m < 4; ++m) _Pragma("unroll") for (int k = 0; k < 2; ++k) dst[m][k] = *(const PG8_LAS bf16x8*)(lds + PG8_SA(b, h) + aoff + m * 2048 + k * 1024); } while (0)
; #define PG8_LDB(dst, b, h) do { _Pragma("unroll") for (int n = 0; n < 2; ++n) _Pragma("unroll") for (int k = 0; k < 2; ++k) dst[n][k] = *(const PG8_LAS bf16x8*)(lds + PG8_SB(b, h) + boff + n * 2048 + k * 1024); } while (0)
; #define PG8_MMA(ai, bj, At, Bt) do { __builtin_amdgcn_s_setprio(1); _Pragma("unroll") for (int m = 0; m < 4; ++m) _Pragma("unroll") for (int n = 0; n < 2; ++n) _Pragma("unroll") for (int k = 0; k < 2; ++k) \
;         acc[ai][bj][m][n] = mma_<I8>(Bt[n][k], At[m][k], acc[ai][bj][m][n]); __builtin_amdgcn_s_setprio(0); } while (0)
; #define PG8_WAIT_V(n) asm volatile("s_waitcnt vmcnt(" #n ")" ::: "memory")
; #define PG8_WAIT_L(n) asm volatile("s_waitcnt lgkmcnt(" #n ")" ::: "memory")
; #define PG8_BAR __builtin_amdgcn_s_barrier()
; #define PG8_SCHED __builtin_amdgcn_sched_barrier(0)
; template <class Epi, class Sched, bool ALIGN_EPI = false, bool SP2 = false, bool I8 = false>
; __device__ __forceinline__ void gemm_phase(PG8_LAS unsigned char* lds, const Gemm g, const Sched& S, const Epi& E) {
;     ...
;         for (int t = 0; t < nt; t += 2) {
;     ...
;             PG8_LDB(B0, 1, 0); PG8_LDB(B1, 1, 1); PG8_SCHED; PG8_LDA(At, 1, 0); PG8_STAGE(PG8_SA(0, 1), a2 + hstepA, voffA);
;             PG8_WAIT_V(8); PG8_WAIT_L(0); PG8_BAR; PG8_MMA(0, 0, At, B0); PG8_MMA(0, 1, At, B1); PG8_BAR; PG8_SCHED;
;             PG8_LDA(At, 1, 1); PG8_STAGE(PG8_SB(1, 0), b3, voffB); PG8_STAGE(PG8_SB(1, 1), b3 + hstepB, voffB); PG8_STAGE(PG8_SA(1, 0), a3, voffA);
;             PG8_WAIT_V(8); PG8_WAIT_L(0); PG8_BAR; PG8_MMA(1, 0, At, B0); PG8_MMA(1, 1, At, B1); PG8_BAR; PG8_SCHED;
	s_add_i32 s50, 0, 0x18000
	v_add_u32_e32 v157, s50, v1
	s_add_i32 s51, 0, 0x1c000
	ds_read_b128 v[146:149], v157
	ds_read_b128 v[150:153], v157 offset:1024
	ds_read_b128 v[158:161], v157 offset:2048
	ds_read_b128 v[162:165], v157 offset:3072
	v_add_u32_e32 v157, s51, v1
	ds_read_b128 v[166:169], v157
	ds_read_b128 v[170:173], v157 offset:1024
	ds_read_b128 v[174:177], v157 offset:2048
	ds_read_b128 v[178:181], v157 offset:3072
	s_add_u32 s26, s26, 0x20000
	s_addc_u32 s27, s27, 0
	s_mov_b32 m0, s36
	ds_read_b128 v[182:185], v156 offset:32768
	ds_read_b128 v[186:189], v156 offset:33792
	ds_read_b128 v[190:193], v156 offset:34816
	ds_read_b128 v[194:197], v156 offset:35840
	ds_read_b128 v[198:201], v156 offset:36864
	ds_read_b128 v[202:205], v156 offset:37888
	ds_read_b128 v[206:209], v156 offset:38912
	ds_read_b128 v[210:213], v156 offset:39936
	global_load_lds_dwordx4 v130, s[26:27]
	s_mov_b32 m0, s37
	s_nop 0
	global_load_lds_dwordx4 v134, s[26:27]
	s_waitcnt vmcnt(8) lgkmcnt(0)
	s_barrier
	v_mfma_f32_16x16x32_bf16 v[126:129], v[146:149], v[182:185], v[126:129]
	v_mfma_f32_16x16x32_bf16 v[122:125], v[158:161], v[182:185], v[122:125]
	v_mfma_f32_16x16x32_bf16 v[114:117], v[146:149], v[190:193], v[114:117]
	v_mfma_f32_16x16x32_bf16 v[106:109], v[158:161], v[190:193], v[106:109]
	v_mfma_f32_16x16x32_bf16 v[94:97], v[146:149], v[198:201], v[94:97]
	v_mfma_f32_16x16x32_bf16 v[90:93], v[158:161], v[198:201], v[90:93]
	v_mfma_f32_16x16x32_bf16 v[86:89], v[146:149], v[206:209], v[86:89]
	v_mfma_f32_16x16x32_bf16 v[82:85], v[158:161], v[206:209], v[82:85]
	v_mfma_f32_16x16x32_bf16 v[126:129], v[150:153], v[186:189], v[126:129]
	v_mfma_f32_16x16x32_bf16 v[122:125], v[162:165], v[186:189], v[122:125]
	v_mfma_f32_16x16x32_bf16 v[114:117], v[150:153], v[194:197], v[114:117]
	v_mfma_f32_16x16x32_bf16 v[106:109], v[162:165], v[194:197], v[106:109]
	v_mfma_f32_16x16x32_bf16 v[94:97], v[150:153], v[202:205], v[94:97]
	v_mfma_f32_16x16x32_bf16 v[90:93], v[162:165], v[202:205], v[90:93]
	v_mfma_f32_16x16x32_bf16 v[86:89], v[150:153], v[210:213], v[86:89]
	v_mfma_f32_16x16x32_bf16 v[82:85], v[162:165], v[210:213], v[82:85]
	v_mfma_f32_16x16x32_bf16 v[118:121], v[166:169], v[182:185], v[118:121]
	v_mfma_f32_16x16x32_bf16 v[110:113], v[174:177], v[182:185], v[110:113]
	v_mfma_f32_16x16x32_bf16 v[102:105], v[166:169], v[190:193], v[102:105]
	v_mfma_f32_16x16x32_bf16 v[98:101], v[174:177], v[190:193], v[98:101]
	v_mfma_f32_16x16x32_bf16 v[78:81], v[166:169], v[198:201], v[78:81]
	v_mfma_f32_16x16x32_bf16 v[74:77], v[174:177], v[198:201], v[74:77]
	v_mfma_f32_16x16x32_bf16 v[70:73], v[166:169], v[206:209], v[70:73]
	v_mfma_f32_16x16x32_bf16 v[66:69], v[174:177], v[206:209], v[66:69]
	v_mfma_f32_16x16x32_bf16 v[118:121], v[170:173], v[186:189], v[118:121]
	v_mfma_f32_16x16x32_bf16 v[110:113], v[178:181], v[186:189], v[110:113]
	v_mfma_f32_16x16x32_bf16 v[102:105], v[170:173], v[194:197], v[102:105]
	v_mfma_f32_16x16x32_bf16 v[98:101], v[178:181], v[194:197], v[98:101]
	v_mfma_f32_16x16x32_bf16 v[78:81], v[170:173], v[202:205], v[78:81]
	v_mfma_f32_16x16x32_bf16 v[74:77], v[178:181], v[202:205], v[74:77]
	v_mfma_f32_16x16x32_bf16 v[70:73], v[170:173], v[210:213], v[70:73]
	v_mfma_f32_16x16x32_bf16 v[66:69], v[178:181], v[210:213], v[66:69]
	s_barrier
	s_add_i32 s26, s50, s34
	s_add_i32 m0, s26, 0xffffff80
	ds_read_b128 v[182:185], v156 offset:49152
	ds_read_b128 v[186:189], v156 offset:50176
	ds_read_b128 v[190:193], v156 offset:51200
	ds_read_b128 v[194:197], v156 offset:52224
	ds_read_b128 v[198:201], v156 offset:53248
	ds_read_b128 v[202:205], v156 offset:54272
	ds_read_b128 v[206:209], v156 offset:55296
	ds_read_b128 v[210:213], v156 offset:56320
	global_load_lds_dwordx4 v132, s[98:99] offset:128
	s_add_i32 m0, s26, 0x1f80
	s_add_u32 s24, s24, 0x20080
	s_addc_u32 s25, s25, 0
	s_add_i32 s26, s51, s34
	global_load_lds_dwordx4 v136, s[98:99] offset:128
	s_mov_b32 m0, s26
	s_nop 0
	global_load_lds_dwordx4 v132, s[24:25]
	s_add_i32 m0, s26, 0x2000
	s_nop 0
	global_load_lds_dwordx4 v136, s[24:25]
	s_add_i32 m0, s39, 0xffffff80
	s_nop 0
	global_load_lds_dwordx4 v130, s[100:101] offset:128
	s_add_i32 m0, s40, 0xffffff80
	s_nop 0
	global_load_lds_dwordx4 v134, s[100:101] offset:128
	s_waitcnt vmcnt(8) lgkmcnt(0)
	s_barrier
	v_mfma_f32_16x16x32_bf16 v[62:65], v[146:149], v[182:185], v[62:65]
	v_mfma_f32_16x16x32_bf16 v[58:61], v[158:161], v[182:185], v[58:61]
	v_mfma_f32_16x16x32_bf16 v[54:57], v[146:149], v[190:193], v[54:57]
	v_mfma_f32_16x16x32_bf16 v[50:53], v[158:161], v[190:193], v[50:53]
	v_mfma_f32_16x16x32_bf16 v[30:33], v[146:149], v[198:201], v[30:33]
	v_mfma_f32_16x16x32_bf16 v[26:29], v[158:161], v[198:201], v[26:29]
	v_mfma_f32_16x16x32_bf16 v[22:25], v[146:149], v[206:209], v[22:25]
	v_mfma_f32_16x16x32_bf16 v[10:13], v[158:161], v[206:209], v[10:13]
	v_mfma_f32_16x16x32_bf16 v[62:65], v[150:153], v[186:189], v[62:65]
	v_mfma_f32_16x16x32_bf16 v[58:61], v[162:165], v[186:189], v[58:61]
	v_mfma_f32_16x16x32_bf16 v[54:57], v[150:153], v[194:197], v[54:57]
	v_mfma_f32_16x16x32_bf16 v[50:53], v[162:165], v[194:197], v[50:53]
	v_mfma_f32_16x16x32_bf16 v[30:33], v[150:153], v[202:205], v[30:33]
	v_mfma_f32_16x16x32_bf16 v[26:29], v[162:165], v[202:205], v[26:29]
	v_mfma_f32_16x16x32_bf16 v[22:25], v[150:153], v[210:213], v[22:25]
	v_mfma_f32_16x16x32_bf16 v[10:13], v[162:165], v[210:213], v[10:13]
	v_mfma_f32_16x16x32_bf16 v[46:49], v[166:169], v[182:185], v[46:49]
	v_mfma_f32_16x16x32_bf16 v[42:45], v[174:177], v[182:185], v[42:45]
	v_mfma_f32_16x16x32_bf16 v[38:41], v[166:169], v[190:193], v[38:41]
	v_mfma_f32_16x16x32_bf16 v[34:37], v[174:177], v[190:193], v[34:37]
	v_mfma_f32_16x16x32_bf16 v[18:21], v[166:169], v[198:201], v[18:21]
	v_mfma_f32_16x16x32_bf16 v[14:17], v[174:177], v[198:201], v[14:17]
	v_mfma_f32_16x16x32_bf16 v[6:9], v[166:169], v[206:209], v[6:9]
	v_mfma_f32_16x16x32_bf16 v[2:5], v[174:177], v[206:209], v[2:5]
	v_mfma_f32_16x16x32_bf16 v[46:49], v[170:173], v[186:189], v[46:49]
	v_mfma_f32_16x16x32_bf16 v[42:45], v[178:181], v[186:189], v[42:45]
	v_mfma_f32_16x16x32_bf16 v[38:41], v[170:173], v[194:197], v[38:41]
	v_mfma_f32_16x16x32_bf16 v[34:37], v[178:181], v[194:197], v[34:37]
	v_mfma_f32_16x16x32_bf16 v[18:21], v[170:173], v[202:205], v[18:21]
	v_mfma_f32_16x16x32_bf16 v[14:17], v[178:181], v[202:205], v[14:17]
	v_mfma_f32_16x16x32_bf16 v[6:9], v[170:173], v[210:213], v[6:9]
	v_mfma_f32_16x16x32_bf16 v[2:5], v[178:181], v[210:213], v[2:5]
	s_barrier
	s_add_i32 s49, s49, 2
	s_add_u32 s22, s22, 0x100
	s_addc_u32 s23, s23, 0
	s_add_u32 s47, s47, 0x100
	s_addc_u32 s48, s48, 0
	s_cmp_gt_u32 s49, 5
	s_cbranch_scc0 .LBB0_1538
	s_and_b64 vcc, exec, s[10:11]
	s_cbranch_vccz .LBB0_1541
	s_barrier

; #define PG8_STAGE(bufoff, gbase, voff) do { _Pragma("unroll") for (int _i = 0; _i < 2; ++_i) \
;         __builtin_amdgcn_global_load_lds((const unsigned*)((const char*)(gbase) + (voff)[_i]), (PG8_LAS unsigned*)(lds + (bufoff) + ldsw + _i * 8192), 16, 0, 0); } while (0)
; #define PG8_LDA(dst, b, h) do { _Pragma("unroll") for (int m = 0; m < 4; ++m) _Pragma("unroll") for (int k = 0; k < 2; ++k) dst[m][k] = *(const PG8_LAS bf16x8*)(lds + PG8_SA(b, h) + aoff + m * 2048 + k * 1024); } while (0)
; #define PG8_LDB(dst, b, h) do { _Pragma("unroll") for (int n = 0; n < 2; ++n) _Pragma("unroll") for (int k = 0; k < 2; ++k) dst[n][k] = *(const PG8_LAS bf16x8*)(lds + PG8_SB(b, h) + boff + n * 2048 + k * 1024); } while (0)
; #define PG8_MMA(ai, bj, At, Bt) do { __builtin_amdgcn_s_setprio(1); _Pragma("unroll") for (int m = 0; m < 4; ++m) _Pragma("unroll") for (int n = 0; n < 2; ++n) _Pragma("unroll") for (int k = 0; k < 2; ++k) \
;         acc[ai][bj][m][n] = mma_<I8>(Bt[n][k], At[m][k], acc[ai][bj][m][n]); __builtin_amdgcn_s_setprio(0); } while (0)
; #define PG8_WAIT_V(n) asm volatile("s_waitcnt vmcnt(" #n ")" ::: "memory")
; #define PG8_WAIT_L(n) asm volatile("s_waitcnt lgkmcnt(" #n ")" ::: "memory")
; #define PG8_BAR __builtin_amdgcn_s_barrier()
; template <class Epi, class Sched, bool ALIGN_EPI = false, bool SP2 = false, bool I8 = false>
; __device__ __forceinline__ void gemm_phase(PG8_LAS unsigned char* lds, const Gemm g, const Sched& S, const Epi& E) {
;     ...
;             const bool last = (t == nt - 2);
;             const char* a1 = cA + (size_t)(t + 1) * kstep;
;             const char* a2 = last ? nA : cA + (size_t)(t + 2) * kstep; const char* b2 = last ? nB : cB + (size_t)(t + 2) * kstep;
;             const char* a3 = a2 + kstep; const char* b3 = b2 + kstep;
;             if (last && has_next) S.a_ready(nxt);
;             if constexpr (SP2) {
;             PG8_LDB(B0, 0, 0); PG8_LDB(B1, 0, 1); PG8_SCHED; PG8_LDA(At, 0, 0); PG8_STAGE(PG8_SA(1, 1), a1 + hstepA, voffA);
;             PG8_WAIT_V(8); PG8_WAIT_L(0); PG8_BAR; PG8_MMA(0, 0, At, B0); PG8_MMA(0, 1, At, B1); PG8_BAR; PG8_SCHED;
;             PG8_LDA(At, 0, 1); PG8_STAGE(PG8_SB(0, 0), b2, voffB); PG8_STAGE(PG8_SB(0, 1), b2 + hstepB, voffB); PG8_STAGE(PG8_SA(0, 0), a2, voffA);
;             PG8_WAIT_V(8); PG8_WAIT_L(0); PG8_BAR; PG8_MMA(1, 0, At, B0); PG8_MMA(1, 1, At, B1); PG8_BAR; PG8_SCHED;
.LBB0_1565:
	ds_read_b128 v[130:133], v176
	ds_read_b128 v[134:137], v176 offset:1024
	ds_read_b128 v[138:141], v176 offset:2048
	ds_read_b128 v[142:145], v176 offset:3072
	ds_read_b128 v[162:165], v177
	ds_read_b128 v[166:169], v177 offset:1024
	ds_read_b128 v[170:173], v177 offset:2048
	ds_read_b128 v[180:183], v177 offset:3072
	s_add_u32 s30, s28, 0xfff80080
	s_addc_u32 s31, s29, -1
	s_cmp_eq_u32 s54, 28
	s_cselect_b32 s35, s7, s31
	s_cselect_b32 s34, s21, s30
	s_cselect_b32 s31, s19, s53
	s_cselect_b32 s30, s27, s52
	s_add_i32 m0, s40, 0xc000
	ds_read_b128 v[184:187], v178
	ds_read_b128 v[188:191], v178 offset:1024
	ds_read_b128 v[192:195], v178 offset:2048
	ds_read_b128 v[196:199], v178 offset:3072
	ds_read_b128 v[200:203], v178 offset:4096
	ds_read_b128 v[204:207], v178 offset:5120
	ds_read_b128 v[208:211], v178 offset:6144
	ds_read_b128 v[212:215], v178 offset:7168
	global_load_lds_dwordx4 v154, s[28:29]
	s_add_i32 m0, s40, 0xe000
	s_nop 0
	global_load_lds_dwordx4 v156, s[28:29]
	s_waitcnt vmcnt(8) lgkmcnt(0)
	s_barrier
	v_mfma_f32_16x16x32_bf16 v[126:129], v[130:133], v[184:187], v[126:129]
	v_mfma_f32_16x16x32_bf16 v[122:125], v[138:141], v[184:187], v[122:125]
	v_mfma_f32_16x16x32_bf16 v[110:113], v[130:133], v[192:195], v[110:113]
	v_mfma_f32_16x16x32_bf16 v[106:109], v[138:141], v[192:195], v[106:109]
	v_mfma_f32_16x16x32_bf16 v[94:97], v[130:133], v[200:203], v[94:97]
	v_mfma_f32_16x16x32_bf16 v[90:93], v[138:141], v[200:203], v[90:93]
	v_mfma_f32_16x16x32_bf16 v[78:81], v[130:133], v[208:211], v[78:81]
	v_mfma_f32_16x16x32_bf16 v[74:77], v[138:141], v[208:211], v[74:77]
	v_mfma_f32_16x16x32_bf16 v[126:129], v[134:137], v[188:191], v[126:129]
	v_mfma_f32_16x16x32_bf16 v[122:125], v[142:145], v[188:191], v[122:125]
	v_mfma_f32_16x16x32_bf16 v[110:113], v[134:137], v[196:199], v[110:113]
	v_mfma_f32_16x16x32_bf16 v[106:109], v[142:145], v[196:199], v[106:109]
	v_mfma_f32_16x16x32_bf16 v[94:97], v[134:137], v[204:207], v[94:97]
	v_mfma_f32_16x16x32_bf16 v[90:93], v[142:145], v[204:207], v[90:93]
	v_mfma_f32_16x16x32_bf16 v[78:81], v[134:137], v[212:215], v[78:81]
	v_mfma_f32_16x16x32_bf16 v[74:77], v[142:145], v[212:215], v[74:77]
	v_mfma_f32_16x16x32_bf16 v[118:121], v[162:165], v[184:187], v[118:121]
	v_mfma_f32_16x16x32_bf16 v[114:117], v[170:173], v[184:187], v[114:117]
	v_mfma_f32_16x16x32_bf16 v[102:105], v[162:165], v[192:195], v[102:105]
	v_mfma_f32_16x16x32_bf16 v[98:101], v[170:173], v[192:195], v[98:101]
	v_mfma_f32_16x16x32_bf16 v[86:89], v[162:165], v[200:203], v[86:89]
	v_mfma_f32_16x16x32_bf16 v[82:85], v[170:173], v[200:203], v[82:85]
	v_mfma_f32_16x16x32_bf16 v[70:73], v[162:165], v[208:211], v[70:73]
	v_mfma_f32_16x16x32_bf16 v[66:69], v[170:173], v[208:211], v[66:69]
	v_mfma_f32_16x16x32_bf16 v[118:121], v[166:169], v[188:191], v[118:121]
	v_mfma_f32_16x16x32_bf16 v[114:117], v[180:183], v[188:191], v[114:117]
	v_mfma_f32_16x16x32_bf16 v[102:105], v[166:169], v[196:199], v[102:105]
	v_mfma_f32_16x16x32_bf16 v[98:101], v[180:183], v[196:199], v[98:101]
	v_mfma_f32_16x16x32_bf16 v[86:89], v[166:169], v[204:207], v[86:89]
	v_mfma_f32_16x16x32_bf16 v[82:85], v[180:183], v[204:207], v[82:85]
	v_mfma_f32_16x16x32_bf16 v[70:73], v[166:169], v[212:215], v[70:73]
	v_mfma_f32_16x16x32_bf16 v[66:69], v[180:183], v[212:215], v[66:69]
	s_barrier
	s_add_i32 s55, s50, s39
	s_mov_b64 s[98:99], s[30:31]
	s_mov_b32 m0, s55
	ds_read_b128 v[184:187], v178 offset:16384
	ds_read_b128 v[188:191], v178 offset:17408
	ds_read_b128 v[192:195], v178 offset:18432
	ds_read_b128 v[196:199], v178 offset:19456
	ds_read_b128 v[200:203], v178 offset:20480
	ds_read_b128 v[204:207], v178 offset:21504
	ds_read_b128 v[208:211], v178 offset:22528
	ds_read_b128 v[212:215], v178 offset:23552
	global_load_lds_dwordx4 v148, s[30:31]
	s_add_i32 m0, s55, 0x2000
	s_add_u32 s56, s30, 0x80000
	s_mov_b64 s[98:99], s[30:31]
	s_addc_u32 s57, s31, 0
	s_add_i32 s55, s51, s39
	global_load_lds_dwordx4 v152, s[30:31]
	s_mov_b32 m0, s55
	s_mov_b64 s[100:101], s[34:35]
	global_load_lds_dwordx4 v148, s[56:57]
	s_add_i32 m0, s55, 0x2000
	s_nop 0
	global_load_lds_dwordx4 v152, s[56:57]
	s_mov_b64 s[100:101], s[34:35]
	s_mov_b32 m0, s40
	s_nop 0
	global_load_lds_dwordx4 v146, s[34:35]
	s_mov_b32 m0, s41
	s_nop 0
	global_load_lds_dwordx4 v150, s[34:35]
	s_waitcnt vmcnt(8) lgkmcnt(0)
	s_barrier
	v_mfma_f32_16x16x32_bf16 v[62:65], v[130:133], v[184:187], v[62:65]
	v_mfma_f32_16x16x32_bf16 v[58:61], v[138:141], v[184:187], v[58:61]
	v_mfma_f32_16x16x32_bf16 v[46:49], v[130:133], v[192:195], v[46:49]
	v_mfma_f32_16x16x32_bf16 v[42:45], v[138:141], v[192:195], v[42:45]
	v_mfma_f32_16x16x32_bf16 v[30:33], v[130:133], v[200:203], v[30:33]
	v_mfma_f32_16x16x32_bf16 v[26:29], v[138:141], v[200:203], v[26:29]
	v_mfma_f32_16x16x32_bf16 v[14:17], v[130:133], v[208:211], v[14:17]
	v_mfma_f32_16x16x32_bf16 v[10:13], v[138:141], v[208:211], v[10:13]
	v_mfma_f32_16x16x32_bf16 v[62:65], v[134:137], v[188:191], v[62:65]
	v_mfma_f32_16x16x32_bf16 v[58:61], v[142:145], v[188:191], v[58:61]
	v_mfma_f32_16x16x32_bf16 v[46:49], v[134:137], v[196:199], v[46:49]
	v_mfma_f32_16x16x32_bf16 v[42:45], v[142:145], v[196:199], v[42:45]
	v_mfma_f32_16x16x32_bf16 v[30:33], v[134:137], v[204:207], v[30:33]
	v_mfma_f32_16x16x32_bf16 v[26:29], v[142:145], v[204:207], v[26:29]
	v_mfma_f32_16x16x32_bf16 v[14:17], v[134:137], v[212:215], v[14:17]
	v_mfma_f32_16x16x32_bf16 v[10:13], v[142:145], v[212:215], v[10:13]
	v_mfma_f32_16x16x32_bf16 v[54:57], v[162:165], v[184:187], v[54:57]
	v_mfma_f32_16x16x32_bf16 v[50:53], v[170:173], v[184:187], v[50:53]
	v_mfma_f32_16x16x32_bf16 v[38:41], v[162:165], v[192:195], v[38:41]
	v_mfma_f32_16x16x32_bf16 v[34:37], v[170:173], v[192:195], v[34:37]
	v_mfma_f32_16x16x32_bf16 v[22:25], v[162:165], v[200:203], v[22:25]
	v_mfma_f32_16x16x32_bf16 v[18:21], v[170:173], v[200:203], v[18:21]
	v_mfma_f32_16x16x32_bf16 v[6:9], v[162:165], v[208:211], v[6:9]
	v_mfma_f32_16x16x32_bf16 v[2:5], v[170:173], v[208:211], v[2:5]
	v_mfma_f32_16x16x32_bf16 v[54:57], v[166:169], v[188:191], v[54:57]
	v_mfma_f32_16x16x32_bf16 v[50:53], v[180:183], v[188:191], v[50:53]
	v_mfma_f32_16x16x32_bf16 v[38:41], v[166:169], v[196:199], v[38:41]
	v_mfma_f32_16x16x32_bf16 v[34:37], v[180:183], v[196:199], v[34:37]
	v_mfma_f32_16x16x32_bf16 v[22:25], v[166:169], v[204:207], v[22:25]
	v_mfma_f32_16x16x32_bf16 v[18:21], v[180:183], v[204:207], v[18:21]
	v_mfma_f32_16x16x32_bf16 v[6:9], v[166:169], v[212:215], v[6:9]
	v_mfma_f32_16x16x32_bf16 v[2:5], v[180:183], v[212:215], v[2:5]
	s_barrier
; #define PG8_STAGE(bufoff, gbase, voff) do { _Pragma("unroll") for (int _i = 0; _i < 2; ++_i) \
;         __builtin_amdgcn_global_load_lds((const unsigned*)((const char*)(gbase) + (voff)[_i]), (PG8_LAS unsigned*)(lds + (bufoff) + ldsw + _i * 8192), 16, 0, 0); } while (0)
; #define PG8_LDA(dst, b, h) do { _Pragma("unroll") for (int m = 0; m < 4; ++m) _Pragma("unroll") for (int k = 0; k < 2; ++k) dst[m][k] = *(const PG8_LAS bf16x8*)(lds + PG8_SA(b, h) + aoff + m * 2048 + k * 1024); } while (0)
; #define PG8_LDB(dst, b, h) do { _Pragma("unroll") for (int n = 0; n < 2; ++n) _Pragma("unroll") for (int k = 0; k < 2; ++k) dst[n][k] = *(const PG8_LAS bf16x8*)(lds + PG8_SB(b, h) + boff + n * 2048 + k * 1024); } while (0)
; #define PG8_MMA(ai, bj, At, Bt) do { __builtin_amdgcn_s_setprio(1); _Pragma("unroll") for (int m = 0; m < 4; ++m) _Pragma("unroll") for (int n = 0; n < 2; ++n) _Pragma("unroll") for (int k = 0; k < 2; ++k) \
;         acc[ai][bj][m][n] = mma_<I8>(Bt[n][k], At[m][k], acc[ai][bj][m][n]); __builtin_amdgcn_s_setprio(0); } while (0)
; #define PG8_WAIT_V(n) asm volatile("s_waitcnt vmcnt(" #n ")" ::: "memory")
; #define PG8_WAIT_L(n) asm volatile("s_waitcnt lgkmcnt(" #n ")" ::: "memory")
; #define PG8_BAR __builtin_amdgcn_s_barrier()
; #define PG8_SCHED __builtin_amdgcn_sched_barrier(0)
; template <class Epi, class Sched, bool ALIGN_EPI = false, bool SP2 = false, bool I8 = false>
; __device__ __forceinline__ void gemm_phase(PG8_LAS unsigned char* lds, const Gemm g, const Sched& S, const Epi& E) {
;     ...
;         for (int t = 0; t < nt; t += 2) {
;     ...
;             PG8_LDB(B0, 1, 0); PG8_LDB(B1, 1, 1); PG8_SCHED; PG8_LDA(At, 1, 0); PG8_STAGE(PG8_SA(0, 1), a2 + hstepA, voffA);
;             PG8_WAIT_V(8); PG8_WAIT_L(0); PG8_BAR; PG8_MMA(0, 0, At, B0); PG8_MMA(0, 1, At, B1); PG8_BAR; PG8_SCHED;
;             PG8_LDA(At, 1, 1); PG8_STAGE(PG8_SB(1, 0), b3, voffB); PG8_STAGE(PG8_SB(1, 1), b3 + hstepB, voffB); PG8_STAGE(PG8_SA(1, 0), a3, voffA);
;             PG8_WAIT_V(8); PG8_WAIT_L(0); PG8_BAR; PG8_MMA(1, 0, At, B0); PG8_MMA(1, 1, At, B1); PG8_BAR; PG8_SCHED;
	s_add_i32 s55, 0, 0x18000
	s_add_i32 s56, 0, 0x1c000
	v_add_u32_e32 v142, s55, v1
	v_add_u32_e32 v180, s56, v1
	ds_read_b128 v[130:133], v142
	ds_read_b128 v[134:137], v142 offset:1024
	ds_read_b128 v[138:141], v142 offset:2048
	ds_read_b128 v[142:145], v142 offset:3072
	ds_read_b128 v[162:165], v180
	ds_read_b128 v[166:169], v180 offset:1024
	ds_read_b128 v[170:173], v180 offset:2048
	ds_read_b128 v[180:183], v180 offset:3072
	s_add_u32 s34, s34, 0x80000
	s_addc_u32 s35, s35, 0
	s_mov_b32 m0, s42
	ds_read_b128 v[184:187], v178 offset:32768
	ds_read_b128 v[188:191], v178 offset:33792
	ds_read_b128 v[192:195], v178 offset:34816
	ds_read_b128 v[196:199], v178 offset:35840
	ds_read_b128 v[200:203], v178 offset:36864
	ds_read_b128 v[204:207], v178 offset:37888
	ds_read_b128 v[208:211], v178 offset:38912
	ds_read_b128 v[212:215], v178 offset:39936
	global_load_lds_dwordx4 v146, s[34:35]
	s_mov_b32 m0, s43
	s_nop 0
	global_load_lds_dwordx4 v150, s[34:35]
	s_waitcnt vmcnt(8) lgkmcnt(0)
	s_barrier
	v_mfma_f32_16x16x32_bf16 v[126:129], v[130:133], v[184:187], v[126:129]
	v_mfma_f32_16x16x32_bf16 v[122:125], v[138:141], v[184:187], v[122:125]
	v_mfma_f32_16x16x32_bf16 v[110:113], v[130:133], v[192:195], v[110:113]
	v_mfma_f32_16x16x32_bf16 v[106:109], v[138:141], v[192:195], v[106:109]
	v_mfma_f32_16x16x32_bf16 v[94:97], v[130:133], v[200:203], v[94:97]
	v_mfma_f32_16x16x32_bf16 v[90:93], v[138:141], v[200:203], v[90:93]
	v_mfma_f32_16x16x32_bf16 v[78:81], v[130:133], v[208:211], v[78:81]
	v_mfma_f32_16x16x32_bf16 v[74:77], v[138:141], v[208:211], v[74:77]
	v_mfma_f32_16x16x32_bf16 v[126:129], v[134:137], v[188:191], v[126:129]
	v_mfma_f32_16x16x32_bf16 v[122:125], v[142:145], v[188:191], v[122:125]
	v_mfma_f32_16x16x32_bf16 v[110:113], v[134:137], v[196:199], v[110:113]
	v_mfma_f32_16x16x32_bf16 v[106:109], v[142:145], v[196:199], v[106:109]
	v_mfma_f32_16x16x32_bf16 v[94:97], v[134:137], v[204:207], v[94:97]
	v_mfma_f32_16x16x32_bf16 v[90:93], v[142:145], v[204:207], v[90:93]
	v_mfma_f32_16x16x32_bf16 v[78:81], v[134:137], v[212:215], v[78:81]
	v_mfma_f32_16x16x32_bf16 v[74:77], v[142:145], v[212:215], v[74:77]
	v_mfma_f32_16x16x32_bf16 v[118:121], v[162:165], v[184:187], v[118:121]
	v_mfma_f32_16x16x32_bf16 v[114:117], v[170:173], v[184:187], v[114:117]
	v_mfma_f32_16x16x32_bf16 v[102:105], v[162:165], v[192:195], v[102:105]
	v_mfma_f32_16x16x32_bf16 v[98:101], v[170:173], v[192:195], v[98:101]
	v_mfma_f32_16x16x32_bf16 v[86:89], v[162:165], v[200:203], v[86:89]
	v_mfma_f32_16x16x32_bf16 v[82:85], v[170:173], v[200:203], v[82:85]
	v_mfma_f32_16x16x32_bf16 v[70:73], v[162:165], v[208:211], v[70:73]
	v_mfma_f32_16x16x32_bf16 v[66:69], v[170:173], v[208:211], v[66:69]
	v_mfma_f32_16x16x32_bf16 v[118:121], v[166:169], v[188:191], v[118:121]
	v_mfma_f32_16x16x32_bf16 v[114:117], v[180:183], v[188:191], v[114:117]
	v_mfma_f32_16x16x32_bf16 v[102:105], v[166:169], v[196:199], v[102:105]
	v_mfma_f32_16x16x32_bf16 v[98:101], v[180:183], v[196:199], v[98:101]
	v_mfma_f32_16x16x32_bf16 v[86:89], v[166:169], v[204:207], v[86:89]
	v_mfma_f32_16x16x32_bf16 v[82:85], v[180:183], v[204:207], v[82:85]
	v_mfma_f32_16x16x32_bf16 v[70:73], v[166:169], v[212:215], v[70:73]
	v_mfma_f32_16x16x32_bf16 v[66:69], v[180:183], v[212:215], v[66:69]
	s_barrier
	s_add_i32 s34, s55, s39
	s_add_i32 m0, s34, 0xffffff80
	ds_read_b128 v[184:187], v178 offset:49152
	ds_read_b128 v[188:191], v178 offset:50176
	ds_read_b128 v[192:195], v178 offset:51200
	ds_read_b128 v[196:199], v178 offset:52224
	ds_read_b128 v[200:203], v178 offset:53248
	ds_read_b128 v[204:207], v178 offset:54272
	ds_read_b128 v[208:211], v178 offset:55296
	ds_read_b128 v[212:215], v178 offset:56320
	global_load_lds_dwordx4 v148, s[98:99] offset:128
	s_add_i32 m0, s34, 0x1f80
	s_add_u32 s30, s30, 0x80080
	s_addc_u32 s31, s31, 0
	s_add_i32 s34, s56, s39
	global_load_lds_dwordx4 v152, s[98:99] offset:128
	s_mov_b32 m0, s34
	s_nop 0
	global_load_lds_dwordx4 v148, s[30:31]
	s_add_i32 m0, s34, 0x2000
	s_nop 0
	global_load_lds_dwordx4 v152, s[30:31]
	s_add_i32 m0, s46, 0xffffff80
	s_nop 0
	global_load_lds_dwordx4 v146, s[100:101] offset:128
	s_add_i32 m0, s47, 0xffffff80
	s_nop 0
	global_load_lds_dwordx4 v150, s[100:101] offset:128
	s_waitcnt vmcnt(8) lgkmcnt(0)
	s_barrier
	v_mfma_f32_16x16x32_bf16 v[62:65], v[130:133], v[184:187], v[62:65]
	v_mfma_f32_16x16x32_bf16 v[58:61], v[138:141], v[184:187], v[58:61]
	v_mfma_f32_16x16x32_bf16 v[46:49], v[130:133], v[192:195], v[46:49]
	v_mfma_f32_16x16x32_bf16 v[42:45], v[138:141], v[192:195], v[42:45]
	v_mfma_f32_16x16x32_bf16 v[30:33], v[130:133], v[200:203], v[30:33]
	v_mfma_f32_16x16x32_bf16 v[26:29], v[138:141], v[200:203], v[26:29]
	v_mfma_f32_16x16x32_bf16 v[14:17], v[130:133], v[208:211], v[14:17]
	v_mfma_f32_16x16x32_bf16 v[10:13], v[138:141], v[208:211], v[10:13]
	v_mfma_f32_16x16x32_bf16 v[62:65], v[134:137], v[188:191], v[62:65]
	v_mfma_f32_16x16x32_bf16 v[58:61], v[142:145], v[188:191], v[58:61]
	v_mfma_f32_16x16x32_bf16 v[46:49], v[134:137], v[196:199], v[46:49]
	v_mfma_f32_16x16x32_bf16 v[42:45], v[142:145], v[196:199], v[42:45]
	v_mfma_f32_16x16x32_bf16 v[30:33], v[134:137], v[204:207], v[30:33]
	v_mfma_f32_16x16x32_bf16 v[26:29], v[142:145], v[204:207], v[26:29]
	v_mfma_f32_16x16x32_bf16 v[14:17], v[134:137], v[212:215], v[14:17]
	v_mfma_f32_16x16x32_bf16 v[10:13], v[142:145], v[212:215], v[10:13]
	v_mfma_f32_16x16x32_bf16 v[54:57], v[162:165], v[184:187], v[54:57]
	v_mfma_f32_16x16x32_bf16 v[50:53], v[170:173], v[184:187], v[50:53]
	v_mfma_f32_16x16x32_bf16 v[38:41], v[162:165], v[192:195], v[38:41]
	v_mfma_f32_16x16x32_bf16 v[34:37], v[170:173], v[192:195], v[34:37]
	v_mfma_f32_16x16x32_bf16 v[22:25], v[162:165], v[200:203], v[22:25]
	v_mfma_f32_16x16x32_bf16 v[18:21], v[170:173], v[200:203], v[18:21]
	v_mfma_f32_16x16x32_bf16 v[6:9], v[162:165], v[208:211], v[6:9]
	v_mfma_f32_16x16x32_bf16 v[2:5], v[170:173], v[208:211], v[2:5]
	v_mfma_f32_16x16x32_bf16 v[54:57], v[166:169], v[188:191], v[54:57]
	v_mfma_f32_16x16x32_bf16 v[50:53], v[180:183], v[188:191], v[50:53]
	v_mfma_f32_16x16x32_bf16 v[38:41], v[166:169], v[196:199], v[38:41]
	v_mfma_f32_16x16x32_bf16 v[34:37], v[180:183], v[196:199], v[34:37]
	v_mfma_f32_16x16x32_bf16 v[22:25], v[166:169], v[204:207], v[22:25]
	v_mfma_f32_16x16x32_bf16 v[18:21], v[180:183], v[204:207], v[18:21]
	v_mfma_f32_16x16x32_bf16 v[6:9], v[166:169], v[212:215], v[6:9]
	v_mfma_f32_16x16x32_bf16 v[2:5], v[180:183], v[212:215], v[2:5]
	s_barrier
	s_add_i32 s54, s54, 2
	s_add_u32 s28, s28, 0x100
	s_addc_u32 s29, s29, 0
	s_add_u32 s52, s52, 0x100
	s_addc_u32 s53, s53, 0
	s_cmp_gt_u32 s54, 29
	s_cbranch_scc0 .LBB0_1565
	s_and_b64 vcc, exec, s[16:17]
	s_cbranch_vccz .LBB0_1568
	s_barrier

; #define PG8_STAGE(bufoff, gbase, voff) do { _Pragma("unroll") for (int _i = 0; _i < 2; ++_i) \
;         __builtin_amdgcn_global_load_lds((const unsigned*)((const char*)(gbase) + (voff)[_i]), (PG8_LAS unsigned*)(lds + (bufoff) + ldsw + _i * 8192), 16, 0, 0); } while (0)
; #define PG8_LDA(dst, b, h) do { _Pragma("unroll") for (int m = 0; m < 4; ++m) _Pragma("unroll") for (int k = 0; k < 2; ++k) dst[m][k] = *(const PG8_LAS bf16x8*)(lds + PG8_SA(b, h) + aoff + m * 2048 + k * 1024); } while (0)
; #define PG8_LDB(dst, b, h) do { _Pragma("unroll") for (int n = 0; n < 2; ++n) _Pragma("unroll") for (int k = 0; k < 2; ++k) dst[n][k] = *(const PG8_LAS bf16x8*)(lds + PG8_SB(b, h) + boff + n * 2048 + k * 1024); } while (0)
; #define PG8_MMA(ai, bj, At, Bt) do { __builtin_amdgcn_s_setprio(1); _Pragma("unroll") for (int m = 0; m < 4; ++m) _Pragma("unroll") for (int n = 0; n < 2; ++n) _Pragma("unroll") for (int k = 0; k < 2; ++k) \
;         acc[ai][bj][m][n] = mma_<I8>(Bt[n][k], At[m][k], acc[ai][bj][m][n]); __builtin_amdgcn_s_setprio(0); } while (0)
; #define PG8_WAIT_V(n) asm volatile("s_waitcnt vmcnt(" #n ")" ::: "memory")
; #define PG8_WAIT_L(n) asm volatile("s_waitcnt lgkmcnt(" #n ")" ::: "memory")
; #define PG8_BAR __builtin_amdgcn_s_barrier()
; template <class Epi, class Sched, bool ALIGN_EPI = false, bool SP2 = false, bool I8 = false>
; __device__ __forceinline__ void gemm_phase(PG8_LAS unsigned char* lds, const Gemm g, const Sched& S, const Epi& E) {
;     ...
;             const bool last = (t == nt - 2);
;             const char* a1 = cA + (size_t)(t + 1) * kstep;
;             const char* a2 = last ? nA : cA + (size_t)(t + 2) * kstep; const char* b2 = last ? nB : cB + (size_t)(t + 2) * kstep;
;             const char* a3 = a2 + kstep; const char* b3 = b2 + kstep;
;             if (last && has_next) S.a_ready(nxt);
;             if constexpr (SP2) {
;             PG8_LDB(B0, 0, 0); PG8_LDB(B1, 0, 1); PG8_SCHED; PG8_LDA(At, 0, 0); PG8_STAGE(PG8_SA(1, 1), a1 + hstepA, voffA);
;             PG8_WAIT_V(8); PG8_WAIT_L(0); PG8_BAR; PG8_MMA(0, 0, At, B0); PG8_MMA(0, 1, At, B1); PG8_BAR; PG8_SCHED;
;             PG8_LDA(At, 0, 1); PG8_STAGE(PG8_SB(0, 0), b2, voffB); PG8_STAGE(PG8_SB(0, 1), b2 + hstepB, voffB); PG8_STAGE(PG8_SA(0, 0), a2, voffA);
;             PG8_WAIT_V(8); PG8_WAIT_L(0); PG8_BAR; PG8_MMA(1, 0, At, B0); PG8_MMA(1, 1, At, B1); PG8_BAR; PG8_SCHED;
.LBB0_1721:
	ds_read_b128 v[34:37], v233
	ds_read_b128 v[38:41], v233 offset:1024
	ds_read_b128 v[42:45], v233 offset:2048
	ds_read_b128 v[62:65], v233 offset:3072
	ds_read_b128 v[146:149], v234
	ds_read_b128 v[150:153], v234 offset:1024
	ds_read_b128 v[154:157], v234 offset:2048
	ds_read_b128 v[158:161], v234 offset:3072
	s_add_u32 s34, s8, 0xfff80080
	s_addc_u32 s35, s9, -1
	s_cmp_eq_u32 s55, 28
	s_cselect_b32 s37, s3, s35
	s_cselect_b32 s36, s7, s34
	s_cselect_b32 s35, s25, s54
	s_cselect_b32 s34, s27, s33
	s_add_i32 m0, s43, 0xc000
	ds_read_b128 v[162:165], v235
	ds_read_b128 v[166:169], v235 offset:1024
	ds_read_b128 v[170:173], v235 offset:2048
	ds_read_b128 v[186:189], v235 offset:3072
	ds_read_b128 v[190:193], v235 offset:4096
	ds_read_b128 v[194:197], v235 offset:5120
	ds_read_b128 v[198:201], v235 offset:6144
	ds_read_b128 v[202:205], v235 offset:7168
	global_load_lds_dwordx4 v178, s[8:9]
	s_add_i32 m0, s43, 0xe000
	s_nop 0
	global_load_lds_dwordx4 v180, s[8:9]
	s_waitcnt vmcnt(8) lgkmcnt(0)
	s_barrier
	v_mfma_i32_16x16x64_i8 v[142:145], v[34:37], v[162:165], v[142:145]
	v_mfma_i32_16x16x64_i8 v[138:141], v[42:45], v[162:165], v[138:141]
	v_mfma_i32_16x16x64_i8 v[126:129], v[34:37], v[170:173], v[126:129]
	v_mfma_i32_16x16x64_i8 v[122:125], v[42:45], v[170:173], v[122:125]
	v_mfma_i32_16x16x64_i8 v[110:113], v[34:37], v[190:193], v[110:113]
	v_mfma_i32_16x16x64_i8 v[106:109], v[42:45], v[190:193], v[106:109]
	v_mfma_i32_16x16x64_i8 v[94:97], v[34:37], v[198:201], v[94:97]
	v_mfma_i32_16x16x64_i8 v[90:93], v[42:45], v[198:201], v[90:93]
	v_mfma_i32_16x16x64_i8 v[142:145], v[38:41], v[166:169], v[142:145]
	v_mfma_i32_16x16x64_i8 v[138:141], v[62:65], v[166:169], v[138:141]
	v_mfma_i32_16x16x64_i8 v[126:129], v[38:41], v[186:189], v[126:129]
	v_mfma_i32_16x16x64_i8 v[122:125], v[62:65], v[186:189], v[122:125]
	v_mfma_i32_16x16x64_i8 v[110:113], v[38:41], v[194:197], v[110:113]
	v_mfma_i32_16x16x64_i8 v[106:109], v[62:65], v[194:197], v[106:109]
	v_mfma_i32_16x16x64_i8 v[94:97], v[38:41], v[202:205], v[94:97]
	v_mfma_i32_16x16x64_i8 v[90:93], v[62:65], v[202:205], v[90:93]
	v_mfma_i32_16x16x64_i8 v[134:137], v[146:149], v[162:165], v[134:137]
	v_mfma_i32_16x16x64_i8 v[130:133], v[154:157], v[162:165], v[130:133]
	v_mfma_i32_16x16x64_i8 v[118:121], v[146:149], v[170:173], v[118:121]
	v_mfma_i32_16x16x64_i8 v[114:117], v[154:157], v[170:173], v[114:117]
	v_mfma_i32_16x16x64_i8 v[102:105], v[146:149], v[190:193], v[102:105]
	v_mfma_i32_16x16x64_i8 v[98:101], v[154:157], v[190:193], v[98:101]
	v_mfma_i32_16x16x64_i8 v[86:89], v[146:149], v[198:201], v[86:89]
	v_mfma_i32_16x16x64_i8 v[82:85], v[154:157], v[198:201], v[82:85]
	v_mfma_i32_16x16x64_i8 v[134:137], v[150:153], v[166:169], v[134:137]
	v_mfma_i32_16x16x64_i8 v[130:133], v[158:161], v[166:169], v[130:133]
	v_mfma_i32_16x16x64_i8 v[118:121], v[150:153], v[186:189], v[118:121]
	v_mfma_i32_16x16x64_i8 v[114:117], v[158:161], v[186:189], v[114:117]
	v_mfma_i32_16x16x64_i8 v[102:105], v[150:153], v[194:197], v[102:105]
	v_mfma_i32_16x16x64_i8 v[98:101], v[158:161], v[194:197], v[98:101]
	v_mfma_i32_16x16x64_i8 v[86:89], v[150:153], v[202:205], v[86:89]
	v_mfma_i32_16x16x64_i8 v[82:85], v[158:161], v[202:205], v[82:85]
	s_barrier
	s_add_i32 s56, s52, s40
	s_mov_b64 s[98:99], s[34:35]
	s_mov_b32 m0, s56
	ds_read_b128 v[162:165], v235 offset:16384
	ds_read_b128 v[166:169], v235 offset:17408
	ds_read_b128 v[170:173], v235 offset:18432
	ds_read_b128 v[186:189], v235 offset:19456
	ds_read_b128 v[190:193], v235 offset:20480
	ds_read_b128 v[194:197], v235 offset:21504
	ds_read_b128 v[198:201], v235 offset:22528
	ds_read_b128 v[202:205], v235 offset:23552
	global_load_lds_dwordx4 v174, s[34:35]
	s_add_i32 m0, s56, 0x2000
	s_add_u32 s56, s34, 0x80000
	s_mov_b64 s[98:99], s[34:35]
	s_addc_u32 s57, s35, 0
	s_add_i32 s58, s53, s40
	global_load_lds_dwordx4 v176, s[34:35]
	s_mov_b32 m0, s58
	s_mov_b64 s[100:101], s[36:37]
	global_load_lds_dwordx4 v174, s[56:57]
	s_add_i32 m0, s58, 0x2000
	s_nop 0
	global_load_lds_dwordx4 v176, s[56:57]
	s_mov_b64 s[100:101], s[36:37]
	s_mov_b32 m0, s43
	s_nop 0
	global_load_lds_dwordx4 v174, s[36:37]
	s_mov_b32 m0, s44
	s_nop 0
	global_load_lds_dwordx4 v176, s[36:37]
	s_waitcnt vmcnt(8) lgkmcnt(0)
	s_barrier
	v_mfma_i32_16x16x64_i8 v[78:81], v[34:37], v[162:165], v[78:81]
	v_mfma_i32_16x16x64_i8 v[74:77], v[42:45], v[162:165], v[74:77]
	v_mfma_i32_16x16x64_i8 v[58:61], v[34:37], v[170:173], v[58:61]
	v_mfma_i32_16x16x64_i8 v[54:57], v[42:45], v[170:173], v[54:57]
	v_mfma_i32_16x16x64_i8 v[30:33], v[34:37], v[190:193], v[30:33]
	v_mfma_i32_16x16x64_i8 v[26:29], v[42:45], v[190:193], v[26:29]
	v_mfma_i32_16x16x64_i8 v[14:17], v[34:37], v[198:201], v[14:17]
	v_mfma_i32_16x16x64_i8 v[10:13], v[42:45], v[198:201], v[10:13]
	v_mfma_i32_16x16x64_i8 v[78:81], v[38:41], v[166:169], v[78:81]
	v_mfma_i32_16x16x64_i8 v[74:77], v[62:65], v[166:169], v[74:77]
	v_mfma_i32_16x16x64_i8 v[58:61], v[38:41], v[186:189], v[58:61]
	v_mfma_i32_16x16x64_i8 v[54:57], v[62:65], v[186:189], v[54:57]
	v_mfma_i32_16x16x64_i8 v[30:33], v[38:41], v[194:197], v[30:33]
	v_mfma_i32_16x16x64_i8 v[26:29], v[62:65], v[194:197], v[26:29]
	v_mfma_i32_16x16x64_i8 v[14:17], v[38:41], v[202:205], v[14:17]
	v_mfma_i32_16x16x64_i8 v[10:13], v[62:65], v[202:205], v[10:13]
	v_mfma_i32_16x16x64_i8 v[46:49], v[154:157], v[170:173], v[46:49]
	v_mfma_i32_16x16x64_i8 v[22:25], v[146:149], v[190:193], v[22:25]
	v_mfma_i32_16x16x64_i8 v[18:21], v[154:157], v[190:193], v[18:21]
	v_mfma_i32_16x16x64_i8 v[6:9], v[146:149], v[198:201], v[6:9]
	v_mfma_i32_16x16x64_i8 v[2:5], v[154:157], v[198:201], v[2:5]
	v_mfma_i32_16x16x64_i8 v[34:37], v[146:149], v[162:165], v[70:73]
	v_mfma_i32_16x16x64_i8 v[38:41], v[154:157], v[162:165], v[66:69]
	v_mfma_i32_16x16x64_i8 v[42:45], v[146:149], v[170:173], v[50:53]
	v_mfma_i32_16x16x64_i8 v[46:49], v[158:161], v[186:189], v[46:49]
	v_mfma_i32_16x16x64_i8 v[22:25], v[150:153], v[194:197], v[22:25]
	v_mfma_i32_16x16x64_i8 v[18:21], v[158:161], v[194:197], v[18:21]
	v_mfma_i32_16x16x64_i8 v[6:9], v[150:153], v[202:205], v[6:9]
	v_mfma_i32_16x16x64_i8 v[2:5], v[158:161], v[202:205], v[2:5]
	v_mfma_i32_16x16x64_i8 v[34:37], v[150:153], v[166:169], v[34:37]
	v_mfma_i32_16x16x64_i8 v[38:41], v[158:161], v[166:169], v[38:41]
	v_mfma_i32_16x16x64_i8 v[42:45], v[150:153], v[186:189], v[42:45]
	s_barrier
; #define PG8_STAGE(bufoff, gbase, voff) do { _Pragma("unroll") for (int _i = 0; _i < 2; ++_i) \
;         __builtin_amdgcn_global_load_lds((const unsigned*)((const char*)(gbase) + (voff)[_i]), (PG8_LAS unsigned*)(lds + (bufoff) + ldsw + _i * 8192), 16, 0, 0); } while (0)
; #define PG8_LDA(dst, b, h) do { _Pragma("unroll") for (int m = 0; m < 4; ++m) _Pragma("unroll") for (int k = 0; k < 2; ++k) dst[m][k] = *(const PG8_LAS bf16x8*)(lds + PG8_SA(b, h) + aoff + m * 2048 + k * 1024); } while (0)
; #define PG8_LDB(dst, b, h) do { _Pragma("unroll") for (int n = 0; n < 2; ++n) _Pragma("unroll") for (int k = 0; k < 2; ++k) dst[n][k] = *(const PG8_LAS bf16x8*)(lds + PG8_SB(b, h) + boff + n * 2048 + k * 1024); } while (0)
; #define PG8_MMA(ai, bj, At, Bt) do { __builtin_amdgcn_s_setprio(1); _Pragma("unroll") for (int m = 0; m < 4; ++m) _Pragma("unroll") for (int n = 0; n < 2; ++n) _Pragma("unroll") for (int k = 0; k < 2; ++k) \
;         acc[ai][bj][m][n] = mma_<I8>(Bt[n][k], At[m][k], acc[ai][bj][m][n]); __builtin_amdgcn_s_setprio(0); } while (0)
; #define PG8_WAIT_V(n) asm volatile("s_waitcnt vmcnt(" #n ")" ::: "memory")
; #define PG8_WAIT_L(n) asm volatile("s_waitcnt lgkmcnt(" #n ")" ::: "memory")
; #define PG8_BAR __builtin_amdgcn_s_barrier()
; #define PG8_SCHED __builtin_amdgcn_sched_barrier(0)
; template <class Epi, class Sched, bool ALIGN_EPI = false, bool SP2 = false, bool I8 = false>
; __device__ __forceinline__ void gemm_phase(PG8_LAS unsigned char* lds, const Gemm g, const Sched& S, const Epi& E) {
;     ...
;         for (int t = 0; t < nt; t += 2) {
;     ...
;             PG8_LDB(B0, 1, 0); PG8_LDB(B1, 1, 1); PG8_SCHED; PG8_LDA(At, 1, 0); PG8_STAGE(PG8_SA(0, 1), a2 + hstepA, voffA);
;             PG8_WAIT_V(8); PG8_WAIT_L(0); PG8_BAR; PG8_MMA(0, 0, At, B0); PG8_MMA(0, 1, At, B1); PG8_BAR; PG8_SCHED;
;             PG8_LDA(At, 1, 1); PG8_STAGE(PG8_SB(1, 0), b3, voffB); PG8_STAGE(PG8_SB(1, 1), b3 + hstepB, voffB); PG8_STAGE(PG8_SA(1, 0), a3, voffA);
;             PG8_WAIT_V(8); PG8_WAIT_L(0); PG8_BAR; PG8_MMA(1, 0, At, B0); PG8_MMA(1, 1, At, B1); PG8_BAR; PG8_SCHED;
	s_add_i32 s56, 0, 0x18000
	s_add_i32 s57, 0, 0x1c000
	v_add_u32_e32 v70, s56, v1
	v_add_u32_e32 v158, s57, v1
	ds_read_b128 v[50:53], v70
	ds_read_b128 v[62:65], v70 offset:1024
	ds_read_b128 v[66:69], v70 offset:2048
	ds_read_b128 v[70:73], v70 offset:3072
	ds_read_b128 v[146:149], v158
	ds_read_b128 v[150:153], v158 offset:1024
	ds_read_b128 v[154:157], v158 offset:2048
	ds_read_b128 v[158:161], v158 offset:3072
	s_add_u32 s36, s36, 0x80000
	s_addc_u32 s37, s37, 0
	s_mov_b32 m0, s45
	ds_read_b128 v[162:165], v235 offset:32768
	ds_read_b128 v[166:169], v235 offset:33792
	ds_read_b128 v[170:173], v235 offset:34816
	ds_read_b128 v[186:189], v235 offset:35840
	ds_read_b128 v[190:193], v235 offset:36864
	ds_read_b128 v[194:197], v235 offset:37888
	ds_read_b128 v[198:201], v235 offset:38912
	ds_read_b128 v[202:205], v235 offset:39936
	global_load_lds_dwordx4 v174, s[36:37]
	s_mov_b32 m0, s46
	s_nop 0
	global_load_lds_dwordx4 v176, s[36:37]
	s_waitcnt vmcnt(8) lgkmcnt(0)
	s_barrier
	v_mfma_i32_16x16x64_i8 v[142:145], v[50:53], v[162:165], v[142:145]
	v_mfma_i32_16x16x64_i8 v[138:141], v[66:69], v[162:165], v[138:141]
	v_mfma_i32_16x16x64_i8 v[126:129], v[50:53], v[170:173], v[126:129]
	v_mfma_i32_16x16x64_i8 v[122:125], v[66:69], v[170:173], v[122:125]
	v_mfma_i32_16x16x64_i8 v[110:113], v[50:53], v[190:193], v[110:113]
	v_mfma_i32_16x16x64_i8 v[106:109], v[66:69], v[190:193], v[106:109]
	v_mfma_i32_16x16x64_i8 v[94:97], v[50:53], v[198:201], v[94:97]
	v_mfma_i32_16x16x64_i8 v[90:93], v[66:69], v[198:201], v[90:93]
	v_mfma_i32_16x16x64_i8 v[142:145], v[62:65], v[166:169], v[142:145]
	v_mfma_i32_16x16x64_i8 v[138:141], v[70:73], v[166:169], v[138:141]
	v_mfma_i32_16x16x64_i8 v[126:129], v[62:65], v[186:189], v[126:129]
	v_mfma_i32_16x16x64_i8 v[122:125], v[70:73], v[186:189], v[122:125]
	v_mfma_i32_16x16x64_i8 v[110:113], v[62:65], v[194:197], v[110:113]
	v_mfma_i32_16x16x64_i8 v[106:109], v[70:73], v[194:197], v[106:109]
	v_mfma_i32_16x16x64_i8 v[94:97], v[62:65], v[202:205], v[94:97]
	v_mfma_i32_16x16x64_i8 v[90:93], v[70:73], v[202:205], v[90:93]
	v_mfma_i32_16x16x64_i8 v[134:137], v[146:149], v[162:165], v[134:137]
	v_mfma_i32_16x16x64_i8 v[130:133], v[154:157], v[162:165], v[130:133]
	v_mfma_i32_16x16x64_i8 v[118:121], v[146:149], v[170:173], v[118:121]
	v_mfma_i32_16x16x64_i8 v[114:117], v[154:157], v[170:173], v[114:117]
	v_mfma_i32_16x16x64_i8 v[102:105], v[146:149], v[190:193], v[102:105]
	v_mfma_i32_16x16x64_i8 v[98:101], v[154:157], v[190:193], v[98:101]
	v_mfma_i32_16x16x64_i8 v[86:89], v[146:149], v[198:201], v[86:89]
	v_mfma_i32_16x16x64_i8 v[82:85], v[154:157], v[198:201], v[82:85]
	v_mfma_i32_16x16x64_i8 v[134:137], v[150:153], v[166:169], v[134:137]
	v_mfma_i32_16x16x64_i8 v[130:133], v[158:161], v[166:169], v[130:133]
	v_mfma_i32_16x16x64_i8 v[118:121], v[150:153], v[186:189], v[118:121]
	v_mfma_i32_16x16x64_i8 v[114:117], v[158:161], v[186:189], v[114:117]
	v_mfma_i32_16x16x64_i8 v[102:105], v[150:153], v[194:197], v[102:105]
	v_mfma_i32_16x16x64_i8 v[98:101], v[158:161], v[194:197], v[98:101]
	v_mfma_i32_16x16x64_i8 v[86:89], v[150:153], v[202:205], v[86:89]
	v_mfma_i32_16x16x64_i8 v[82:85], v[158:161], v[202:205], v[82:85]
	s_barrier
	s_add_i32 s36, s56, s40
	s_add_i32 m0, s36, 0xffffff80
	ds_read_b128 v[162:165], v235 offset:49152
	ds_read_b128 v[166:169], v235 offset:50176
	ds_read_b128 v[170:173], v235 offset:51200
	ds_read_b128 v[186:189], v235 offset:52224
	ds_read_b128 v[190:193], v235 offset:53248
	ds_read_b128 v[194:197], v235 offset:54272
	ds_read_b128 v[198:201], v235 offset:55296
	ds_read_b128 v[202:205], v235 offset:56320
	global_load_lds_dwordx4 v174, s[98:99] offset:128
	s_add_i32 m0, s36, 0x1f80
	s_add_u32 s34, s34, 0x80080
	s_addc_u32 s35, s35, 0
	s_add_i32 s36, s57, s40
	global_load_lds_dwordx4 v176, s[98:99] offset:128
	s_mov_b32 m0, s36
	s_nop 0
	global_load_lds_dwordx4 v174, s[34:35]
	s_add_i32 m0, s36, 0x2000
	s_nop 0
	global_load_lds_dwordx4 v176, s[34:35]
	s_add_i32 m0, s48, 0xffffff80
	s_nop 0
	global_load_lds_dwordx4 v174, s[100:101] offset:128
	s_add_i32 m0, s49, 0xffffff80
	s_nop 0
	global_load_lds_dwordx4 v176, s[100:101] offset:128
	s_waitcnt vmcnt(8) lgkmcnt(0)
	s_barrier
	v_mfma_i32_16x16x64_i8 v[78:81], v[50:53], v[162:165], v[78:81]
	v_mfma_i32_16x16x64_i8 v[74:77], v[66:69], v[162:165], v[74:77]
	v_mfma_i32_16x16x64_i8 v[58:61], v[50:53], v[170:173], v[58:61]
	v_mfma_i32_16x16x64_i8 v[54:57], v[66:69], v[170:173], v[54:57]
	v_mfma_i32_16x16x64_i8 v[30:33], v[50:53], v[190:193], v[30:33]
	v_mfma_i32_16x16x64_i8 v[26:29], v[66:69], v[190:193], v[26:29]
	v_mfma_i32_16x16x64_i8 v[14:17], v[50:53], v[198:201], v[14:17]
	v_mfma_i32_16x16x64_i8 v[10:13], v[66:69], v[198:201], v[10:13]
	v_mfma_i32_16x16x64_i8 v[78:81], v[62:65], v[166:169], v[78:81]
	v_mfma_i32_16x16x64_i8 v[74:77], v[70:73], v[166:169], v[74:77]
	v_mfma_i32_16x16x64_i8 v[58:61], v[62:65], v[186:189], v[58:61]
	v_mfma_i32_16x16x64_i8 v[54:57], v[70:73], v[186:189], v[54:57]
	v_mfma_i32_16x16x64_i8 v[30:33], v[62:65], v[194:197], v[30:33]
	v_mfma_i32_16x16x64_i8 v[26:29], v[70:73], v[194:197], v[26:29]
	v_mfma_i32_16x16x64_i8 v[14:17], v[62:65], v[202:205], v[14:17]
	v_mfma_i32_16x16x64_i8 v[10:13], v[70:73], v[202:205], v[10:13]
	v_mfma_i32_16x16x64_i8 v[34:37], v[146:149], v[162:165], v[34:37]
	v_mfma_i32_16x16x64_i8 v[70:73], v[150:153], v[166:169], v[34:37]
	v_mfma_i32_16x16x64_i8 v[34:37], v[154:157], v[162:165], v[38:41]
	v_mfma_i32_16x16x64_i8 v[66:69], v[158:161], v[166:169], v[34:37]
	v_mfma_i32_16x16x64_i8 v[34:37], v[146:149], v[170:173], v[42:45]
	v_mfma_i32_16x16x64_i8 v[50:53], v[150:153], v[186:189], v[34:37]
	v_mfma_i32_16x16x64_i8 v[34:37], v[154:157], v[170:173], v[46:49]
	v_mfma_i32_16x16x64_i8 v[22:25], v[146:149], v[190:193], v[22:25]
	v_mfma_i32_16x16x64_i8 v[18:21], v[154:157], v[190:193], v[18:21]
	v_mfma_i32_16x16x64_i8 v[6:9], v[146:149], v[198:201], v[6:9]
	v_mfma_i32_16x16x64_i8 v[2:5], v[154:157], v[198:201], v[2:5]
	v_mfma_i32_16x16x64_i8 v[46:49], v[158:161], v[186:189], v[34:37]
	v_mfma_i32_16x16x64_i8 v[22:25], v[150:153], v[194:197], v[22:25]
	v_mfma_i32_16x16x64_i8 v[18:21], v[158:161], v[194:197], v[18:21]
	v_mfma_i32_16x16x64_i8 v[6:9], v[150:153], v[202:205], v[6:9]
	v_mfma_i32_16x16x64_i8 v[2:5], v[158:161], v[202:205], v[2:5]
	s_barrier
	s_add_i32 s55, s55, 2
	s_add_u32 s8, s8, 0x100
	s_addc_u32 s9, s9, 0
	s_add_u32 s33, s33, 0x100
	s_addc_u32 s54, s54, 0
	s_cmp_gt_u32 s55, 29
	s_cbranch_scc0 .LBB0_1721
	s_and_b64 vcc, exec, s[20:21]
	s_cbranch_vccz .LBB0_1724
	s_barrier

; #define PG8_STAGE(bufoff, gbase, voff) do { _Pragma("unroll") for (int _i = 0; _i < 2; ++_i) \
;         __builtin_amdgcn_global_load_lds((const unsigned*)((const char*)(gbase) + (voff)[_i]), (PG8_LAS unsigned*)(lds + (bufoff) + ldsw + _i * 8192), 16, 0, 0); } while (0)
; #define PG8_LDA(dst, b, h) do { _Pragma("unroll") for (int m = 0; m < 4; ++m) _Pragma("unroll") for (int k = 0; k < 2; ++k) dst[m][k] = *(const PG8_LAS bf16x8*)(lds + PG8_SA(b, h) + aoff + m * 2048 + k * 1024); } while (0)
; #define PG8_LDB(dst, b, h) do { _Pragma("unroll") for (int n = 0; n < 2; ++n) _Pragma("unroll") for (int k = 0; k < 2; ++k) dst[n][k] = *(const PG8_LAS bf16x8*)(lds + PG8_SB(b, h) + boff + n * 2048 + k * 1024); } while (0)
; #define PG8_MMA(ai, bj, At, Bt) do { __builtin_amdgcn_s_setprio(1); _Pragma("unroll") for (int m = 0; m < 4; ++m) _Pragma("unroll") for (int n = 0; n < 2; ++n) _Pragma("unroll") for (int k = 0; k < 2; ++k) \
;         acc[ai][bj][m][n] = mma_<I8>(Bt[n][k], At[m][k], acc[ai][bj][m][n]); __builtin_amdgcn_s_setprio(0); } while (0)
; #define PG8_WAIT_V(n) asm volatile("s_waitcnt vmcnt(" #n ")" ::: "memory")
; #define PG8_WAIT_L(n) asm volatile("s_waitcnt lgkmcnt(" #n ")" ::: "memory")
; #define PG8_BAR __builtin_amdgcn_s_barrier()
; template <class Epi, class Sched, bool ALIGN_EPI = false, bool SP2 = false, bool I8 = false>
; __device__ __forceinline__ void gemm_phase(PG8_LAS unsigned char* lds, const Gemm g, const Sched& S, const Epi& E) {
;     ...
;             const bool last = (t == nt - 2);
;             const char* a1 = cA + (size_t)(t + 1) * kstep;
;             const char* a2 = last ? nA : cA + (size_t)(t + 2) * kstep; const char* b2 = last ? nB : cB + (size_t)(t + 2) * kstep;
;             const char* a3 = a2 + kstep; const char* b3 = b2 + kstep;
;             if (last && has_next) S.a_ready(nxt);
;             if constexpr (SP2) {
;             PG8_LDB(B0, 0, 0); PG8_LDB(B1, 0, 1); PG8_SCHED; PG8_LDA(At, 0, 0); PG8_STAGE(PG8_SA(1, 1), a1 + hstepA, voffA);
;             PG8_WAIT_V(8); PG8_WAIT_L(0); PG8_BAR; PG8_MMA(0, 0, At, B0); PG8_MMA(0, 1, At, B1); PG8_BAR; PG8_SCHED;
;             PG8_LDA(At, 0, 1); PG8_STAGE(PG8_SB(0, 0), b2, voffB); PG8_STAGE(PG8_SB(0, 1), b2 + hstepB, voffB); PG8_STAGE(PG8_SA(0, 0), a2, voffA);
;             PG8_WAIT_V(8); PG8_WAIT_L(0); PG8_BAR; PG8_MMA(1, 0, At, B0); PG8_MMA(1, 1, At, B1); PG8_BAR; PG8_SCHED;
.LBB0_2014:
	ds_read_b128 v[118:121], v163
	ds_read_b128 v[126:129], v163 offset:1024
	ds_read_b128 v[130:133], v163 offset:2048
	ds_read_b128 v[134:137], v163 offset:3072
	ds_read_b128 v[168:171], v167
	ds_read_b128 v[176:179], v167 offset:1024
	ds_read_b128 v[180:183], v167 offset:2048
	ds_read_b128 v[184:187], v167 offset:3072
	s_add_u32 s38, s36, 0xfff80080
	s_addc_u32 s39, s37, -1
	s_cmp_eq_u32 s65, 28
	s_cselect_b32 s41, s27, s39
	s_cselect_b32 s40, s61, s38
	s_cselect_b32 s39, s25, s64
	s_cselect_b32 s38, s62, s63
	s_add_i32 m0, s35, 0xc000
	ds_read_b128 v[188:191], v173
	ds_read_b128 v[192:195], v173 offset:1024
	ds_read_b128 v[196:199], v173 offset:2048
	ds_read_b128 v[200:203], v173 offset:3072
	ds_read_b128 v[204:207], v173 offset:4096
	ds_read_b128 v[208:211], v173 offset:5120
	ds_read_b128 v[212:215], v173 offset:6144
	ds_read_b128 v[216:219], v173 offset:7168
	global_load_lds_dwordx4 v154, s[36:37]
	s_add_i32 m0, s35, 0xe000
	s_nop 0
	global_load_lds_dwordx4 v156, s[36:37]
	s_waitcnt vmcnt(8) lgkmcnt(0)
	s_barrier
	v_mfma_i32_16x16x64_i8 v[142:145], v[118:121], v[188:191], v[142:145]
	v_mfma_i32_16x16x64_i8 v[138:141], v[130:133], v[188:191], v[138:141]
	v_mfma_i32_16x16x64_i8 v[110:113], v[118:121], v[196:199], v[110:113]
	v_mfma_i32_16x16x64_i8 v[106:109], v[130:133], v[196:199], v[106:109]
	v_mfma_i32_16x16x64_i8 v[94:97], v[118:121], v[204:207], v[94:97]
	v_mfma_i32_16x16x64_i8 v[90:93], v[130:133], v[204:207], v[90:93]
	v_mfma_i32_16x16x64_i8 v[78:81], v[118:121], v[212:215], v[78:81]
	v_mfma_i32_16x16x64_i8 v[74:77], v[130:133], v[212:215], v[74:77]
	v_mfma_i32_16x16x64_i8 v[142:145], v[126:129], v[192:195], v[142:145]
	v_mfma_i32_16x16x64_i8 v[138:141], v[134:137], v[192:195], v[138:141]
	v_mfma_i32_16x16x64_i8 v[110:113], v[126:129], v[200:203], v[110:113]
	v_mfma_i32_16x16x64_i8 v[106:109], v[134:137], v[200:203], v[106:109]
	v_mfma_i32_16x16x64_i8 v[94:97], v[126:129], v[208:211], v[94:97]
	v_mfma_i32_16x16x64_i8 v[90:93], v[134:137], v[208:211], v[90:93]
	v_mfma_i32_16x16x64_i8 v[78:81], v[126:129], v[216:219], v[78:81]
	v_mfma_i32_16x16x64_i8 v[74:77], v[134:137], v[216:219], v[74:77]
	v_mfma_i32_16x16x64_i8 v[122:125], v[168:171], v[188:191], v[122:125]
	v_mfma_i32_16x16x64_i8 v[114:117], v[180:183], v[188:191], v[114:117]
	v_mfma_i32_16x16x64_i8 v[102:105], v[168:171], v[196:199], v[102:105]
	v_mfma_i32_16x16x64_i8 v[98:101], v[180:183], v[196:199], v[98:101]
	v_mfma_i32_16x16x64_i8 v[86:89], v[168:171], v[204:207], v[86:89]
	v_mfma_i32_16x16x64_i8 v[82:85], v[180:183], v[204:207], v[82:85]
	v_mfma_i32_16x16x64_i8 v[70:73], v[168:171], v[212:215], v[70:73]
	v_mfma_i32_16x16x64_i8 v[66:69], v[180:183], v[212:215], v[66:69]
	v_mfma_i32_16x16x64_i8 v[122:125], v[176:179], v[192:195], v[122:125]
	v_mfma_i32_16x16x64_i8 v[114:117], v[184:187], v[192:195], v[114:117]
	v_mfma_i32_16x16x64_i8 v[102:105], v[176:179], v[200:203], v[102:105]
	v_mfma_i32_16x16x64_i8 v[98:101], v[184:187], v[200:203], v[98:101]
	v_mfma_i32_16x16x64_i8 v[86:89], v[176:179], v[208:211], v[86:89]
	v_mfma_i32_16x16x64_i8 v[82:85], v[184:187], v[208:211], v[82:85]
	v_mfma_i32_16x16x64_i8 v[70:73], v[176:179], v[216:219], v[70:73]
	v_mfma_i32_16x16x64_i8 v[66:69], v[184:187], v[216:219], v[66:69]
	s_barrier
	s_add_i32 s66, s54, s46
	s_mov_b64 s[98:99], s[38:39]
	s_mov_b32 m0, s66
	ds_read_b128 v[188:191], v173 offset:16384
	ds_read_b128 v[192:195], v173 offset:17408
	ds_read_b128 v[196:199], v173 offset:18432
	ds_read_b128 v[200:203], v173 offset:19456
	ds_read_b128 v[204:207], v173 offset:20480
	ds_read_b128 v[208:211], v173 offset:21504
	ds_read_b128 v[212:215], v173 offset:22528
	ds_read_b128 v[216:219], v173 offset:23552
	global_load_lds_dwordx4 v148, s[38:39]
	s_add_i32 m0, s66, 0x2000
	s_add_u32 s66, s38, 0x80000
	s_mov_b64 s[98:99], s[38:39]
	s_addc_u32 s67, s39, 0
	s_add_i32 s68, s55, s46
	global_load_lds_dwordx4 v152, s[38:39]
	s_mov_b32 m0, s68
	s_mov_b64 s[100:101], s[40:41]
	global_load_lds_dwordx4 v148, s[66:67]
	s_add_i32 m0, s68, 0x2000
	s_nop 0
	global_load_lds_dwordx4 v152, s[66:67]
	s_mov_b64 s[100:101], s[40:41]
	s_mov_b32 m0, s35
	s_nop 0
	global_load_lds_dwordx4 v146, s[40:41]
	s_mov_b32 m0, s47
	s_nop 0
	global_load_lds_dwordx4 v150, s[40:41]
	s_waitcnt vmcnt(8) lgkmcnt(0)
	s_barrier
	v_mfma_i32_16x16x64_i8 v[62:65], v[118:121], v[188:191], v[62:65]
	v_mfma_i32_16x16x64_i8 v[58:61], v[130:133], v[188:191], v[58:61]
	v_mfma_i32_16x16x64_i8 v[46:49], v[118:121], v[196:199], v[46:49]
	v_mfma_i32_16x16x64_i8 v[42:45], v[130:133], v[196:199], v[42:45]
	v_mfma_i32_16x16x64_i8 v[30:33], v[118:121], v[204:207], v[30:33]
	v_mfma_i32_16x16x64_i8 v[26:29], v[130:133], v[204:207], v[26:29]
	v_mfma_i32_16x16x64_i8 v[14:17], v[118:121], v[212:215], v[14:17]
	v_mfma_i32_16x16x64_i8 v[10:13], v[130:133], v[212:215], v[10:13]
	v_mfma_i32_16x16x64_i8 v[62:65], v[126:129], v[192:195], v[62:65]
	v_mfma_i32_16x16x64_i8 v[58:61], v[134:137], v[192:195], v[58:61]
	v_mfma_i32_16x16x64_i8 v[46:49], v[126:129], v[200:203], v[46:49]
	v_mfma_i32_16x16x64_i8 v[42:45], v[134:137], v[200:203], v[42:45]
	v_mfma_i32_16x16x64_i8 v[30:33], v[126:129], v[208:211], v[30:33]
	v_mfma_i32_16x16x64_i8 v[26:29], v[134:137], v[208:211], v[26:29]
	v_mfma_i32_16x16x64_i8 v[14:17], v[126:129], v[216:219], v[14:17]
	v_mfma_i32_16x16x64_i8 v[10:13], v[134:137], v[216:219], v[10:13]
	v_mfma_i32_16x16x64_i8 v[54:57], v[168:171], v[188:191], v[54:57]
	v_mfma_i32_16x16x64_i8 v[50:53], v[180:183], v[188:191], v[50:53]
	v_mfma_i32_16x16x64_i8 v[38:41], v[168:171], v[196:199], v[38:41]
	v_mfma_i32_16x16x64_i8 v[34:37], v[180:183], v[196:199], v[34:37]
	v_mfma_i32_16x16x64_i8 v[22:25], v[168:171], v[204:207], v[22:25]
	v_mfma_i32_16x16x64_i8 v[18:21], v[180:183], v[204:207], v[18:21]
	v_mfma_i32_16x16x64_i8 v[6:9], v[168:171], v[212:215], v[6:9]
	v_mfma_i32_16x16x64_i8 v[2:5], v[180:183], v[212:215], v[2:5]
	v_mfma_i32_16x16x64_i8 v[54:57], v[176:179], v[192:195], v[54:57]
	v_mfma_i32_16x16x64_i8 v[50:53], v[184:187], v[192:195], v[50:53]
	v_mfma_i32_16x16x64_i8 v[38:41], v[176:179], v[200:203], v[38:41]
	v_mfma_i32_16x16x64_i8 v[34:37], v[184:187], v[200:203], v[34:37]
	v_mfma_i32_16x16x64_i8 v[22:25], v[176:179], v[208:211], v[22:25]
	v_mfma_i32_16x16x64_i8 v[18:21], v[184:187], v[208:211], v[18:21]
	v_mfma_i32_16x16x64_i8 v[6:9], v[176:179], v[216:219], v[6:9]
	v_mfma_i32_16x16x64_i8 v[2:5], v[184:187], v[216:219], v[2:5]
	s_barrier
; #define PG8_STAGE(bufoff, gbase, voff) do { _Pragma("unroll") for (int _i = 0; _i < 2; ++_i) \
;         __builtin_amdgcn_global_load_lds((const unsigned*)((const char*)(gbase) + (voff)[_i]), (PG8_LAS unsigned*)(lds + (bufoff) + ldsw + _i * 8192), 16, 0, 0); } while (0)
; #define PG8_LDA(dst, b, h) do { _Pragma("unroll") for (int m = 0; m < 4; ++m) _Pragma("unroll") for (int k = 0; k < 2; ++k) dst[m][k] = *(const PG8_LAS bf16x8*)(lds + PG8_SA(b, h) + aoff + m * 2048 + k * 1024); } while (0)
; #define PG8_LDB(dst, b, h) do { _Pragma("unroll") for (int n = 0; n < 2; ++n) _Pragma("unroll") for (int k = 0; k < 2; ++k) dst[n][k] = *(const PG8_LAS bf16x8*)(lds + PG8_SB(b, h) + boff + n * 2048 + k * 1024); } while (0)
; #define PG8_MMA(ai, bj, At, Bt) do { __builtin_amdgcn_s_setprio(1); _Pragma("unroll") for (int m = 0; m < 4; ++m) _Pragma("unroll") for (int n = 0; n < 2; ++n) _Pragma("unroll") for (int k = 0; k < 2; ++k) \
;         acc[ai][bj][m][n] = mma_<I8>(Bt[n][k], At[m][k], acc[ai][bj][m][n]); __builtin_amdgcn_s_setprio(0); } while (0)
; #define PG8_WAIT_V(n) asm volatile("s_waitcnt vmcnt(" #n ")" ::: "memory")
; #define PG8_WAIT_L(n) asm volatile("s_waitcnt lgkmcnt(" #n ")" ::: "memory")
; #define PG8_BAR __builtin_amdgcn_s_barrier()
; #define PG8_SCHED __builtin_amdgcn_sched_barrier(0)
; template <class Epi, class Sched, bool ALIGN_EPI = false, bool SP2 = false, bool I8 = false>
; __device__ __forceinline__ void gemm_phase(PG8_LAS unsigned char* lds, const Gemm g, const Sched& S, const Epi& E) {
;     ...
;         for (int t = 0; t < nt; t += 2) {
;     ...
;             PG8_LDB(B0, 1, 0); PG8_LDB(B1, 1, 1); PG8_SCHED; PG8_LDA(At, 1, 0); PG8_STAGE(PG8_SA(0, 1), a2 + hstepA, voffA);
;             PG8_WAIT_V(8); PG8_WAIT_L(0); PG8_BAR; PG8_MMA(0, 0, At, B0); PG8_MMA(0, 1, At, B1); PG8_BAR; PG8_SCHED;
;             PG8_LDA(At, 1, 1); PG8_STAGE(PG8_SB(1, 0), b3, voffB); PG8_STAGE(PG8_SB(1, 1), b3 + hstepB, voffB); PG8_STAGE(PG8_SA(1, 0), a3, voffA);
;             PG8_WAIT_V(8); PG8_WAIT_L(0); PG8_BAR; PG8_MMA(1, 0, At, B0); PG8_MMA(1, 1, At, B1); PG8_BAR; PG8_SCHED;
	s_add_i32 s66, 0, 0x18000
	s_add_i32 s67, 0, 0x1c000
	v_add_u32_e32 v134, s66, v1
	v_add_u32_e32 v162, s67, v1
	ds_read_b128 v[118:121], v134
	ds_read_b128 v[126:129], v134 offset:1024
	ds_read_b128 v[130:133], v134 offset:2048
	ds_read_b128 v[134:137], v134 offset:3072
	ds_read_b128 v[168:171], v162
	ds_read_b128 v[176:179], v162 offset:1024
	ds_read_b128 v[180:183], v162 offset:2048
	ds_read_b128 v[184:187], v162 offset:3072
	s_add_u32 s40, s40, 0x80000
	s_addc_u32 s41, s41, 0
	s_mov_b32 m0, s48
	ds_read_b128 v[188:191], v173 offset:32768
	ds_read_b128 v[192:195], v173 offset:33792
	ds_read_b128 v[196:199], v173 offset:34816
	ds_read_b128 v[200:203], v173 offset:35840
	ds_read_b128 v[204:207], v173 offset:36864
	ds_read_b128 v[208:211], v173 offset:37888
	ds_read_b128 v[212:215], v173 offset:38912
	ds_read_b128 v[216:219], v173 offset:39936
	global_load_lds_dwordx4 v146, s[40:41]
	s_mov_b32 m0, s49
	s_nop 0
	global_load_lds_dwordx4 v150, s[40:41]
	s_waitcnt vmcnt(8) lgkmcnt(0)
	s_barrier
	v_mfma_i32_16x16x64_i8 v[142:145], v[118:121], v[188:191], v[142:145]
	v_mfma_i32_16x16x64_i8 v[138:141], v[130:133], v[188:191], v[138:141]
	v_mfma_i32_16x16x64_i8 v[110:113], v[118:121], v[196:199], v[110:113]
	v_mfma_i32_16x16x64_i8 v[106:109], v[130:133], v[196:199], v[106:109]
	v_mfma_i32_16x16x64_i8 v[94:97], v[118:121], v[204:207], v[94:97]
	v_mfma_i32_16x16x64_i8 v[90:93], v[130:133], v[204:207], v[90:93]
	v_mfma_i32_16x16x64_i8 v[78:81], v[118:121], v[212:215], v[78:81]
	v_mfma_i32_16x16x64_i8 v[74:77], v[130:133], v[212:215], v[74:77]
	v_mfma_i32_16x16x64_i8 v[142:145], v[126:129], v[192:195], v[142:145]
	v_mfma_i32_16x16x64_i8 v[138:141], v[134:137], v[192:195], v[138:141]
	v_mfma_i32_16x16x64_i8 v[110:113], v[126:129], v[200:203], v[110:113]
	v_mfma_i32_16x16x64_i8 v[106:109], v[134:137], v[200:203], v[106:109]
	v_mfma_i32_16x16x64_i8 v[94:97], v[126:129], v[208:211], v[94:97]
	v_mfma_i32_16x16x64_i8 v[90:93], v[134:137], v[208:211], v[90:93]
	v_mfma_i32_16x16x64_i8 v[78:81], v[126:129], v[216:219], v[78:81]
	v_mfma_i32_16x16x64_i8 v[74:77], v[134:137], v[216:219], v[74:77]
	v_mfma_i32_16x16x64_i8 v[122:125], v[168:171], v[188:191], v[122:125]
	v_mfma_i32_16x16x64_i8 v[114:117], v[180:183], v[188:191], v[114:117]
	v_mfma_i32_16x16x64_i8 v[102:105], v[168:171], v[196:199], v[102:105]
	v_mfma_i32_16x16x64_i8 v[98:101], v[180:183], v[196:199], v[98:101]
	v_mfma_i32_16x16x64_i8 v[86:89], v[168:171], v[204:207], v[86:89]
	v_mfma_i32_16x16x64_i8 v[82:85], v[180:183], v[204:207], v[82:85]
	v_mfma_i32_16x16x64_i8 v[70:73], v[168:171], v[212:215], v[70:73]
	v_mfma_i32_16x16x64_i8 v[66:69], v[180:183], v[212:215], v[66:69]
	v_mfma_i32_16x16x64_i8 v[122:125], v[176:179], v[192:195], v[122:125]
	v_mfma_i32_16x16x64_i8 v[114:117], v[184:187], v[192:195], v[114:117]
	v_mfma_i32_16x16x64_i8 v[102:105], v[176:179], v[200:203], v[102:105]
	v_mfma_i32_16x16x64_i8 v[98:101], v[184:187], v[200:203], v[98:101]
	v_mfma_i32_16x16x64_i8 v[86:89], v[176:179], v[208:211], v[86:89]
	v_mfma_i32_16x16x64_i8 v[82:85], v[184:187], v[208:211], v[82:85]
	v_mfma_i32_16x16x64_i8 v[70:73], v[176:179], v[216:219], v[70:73]
	v_mfma_i32_16x16x64_i8 v[66:69], v[184:187], v[216:219], v[66:69]
	s_barrier
	s_add_i32 s40, s66, s46
	s_add_i32 m0, s40, 0xffffff80
	ds_read_b128 v[188:191], v173 offset:49152
	ds_read_b128 v[192:195], v173 offset:50176
	ds_read_b128 v[196:199], v173 offset:51200
	ds_read_b128 v[200:203], v173 offset:52224
	ds_read_b128 v[204:207], v173 offset:53248
	ds_read_b128 v[208:211], v173 offset:54272
	ds_read_b128 v[212:215], v173 offset:55296
	ds_read_b128 v[216:219], v173 offset:56320
	global_load_lds_dwordx4 v148, s[98:99] offset:128
	s_add_i32 m0, s40, 0x1f80
	s_add_u32 s38, s38, 0x80080
	s_addc_u32 s39, s39, 0
	s_add_i32 s40, s67, s46
	global_load_lds_dwordx4 v152, s[98:99] offset:128
	s_mov_b32 m0, s40
	s_nop 0
	global_load_lds_dwordx4 v148, s[38:39]
	s_add_i32 m0, s40, 0x2000
	s_nop 0
	global_load_lds_dwordx4 v152, s[38:39]
	s_add_i32 m0, s51, 0xffffff80
	s_nop 0
	global_load_lds_dwordx4 v146, s[100:101] offset:128
	s_add_i32 m0, s52, 0xffffff80
	s_nop 0
	global_load_lds_dwordx4 v150, s[100:101] offset:128
	s_waitcnt vmcnt(8) lgkmcnt(0)
	s_barrier
	v_mfma_i32_16x16x64_i8 v[62:65], v[118:121], v[188:191], v[62:65]
	v_mfma_i32_16x16x64_i8 v[58:61], v[130:133], v[188:191], v[58:61]
	v_mfma_i32_16x16x64_i8 v[46:49], v[118:121], v[196:199], v[46:49]
	v_mfma_i32_16x16x64_i8 v[42:45], v[130:133], v[196:199], v[42:45]
	v_mfma_i32_16x16x64_i8 v[30:33], v[118:121], v[204:207], v[30:33]
	v_mfma_i32_16x16x64_i8 v[26:29], v[130:133], v[204:207], v[26:29]
	v_mfma_i32_16x16x64_i8 v[14:17], v[118:121], v[212:215], v[14:17]
	v_mfma_i32_16x16x64_i8 v[10:13], v[130:133], v[212:215], v[10:13]
	v_mfma_i32_16x16x64_i8 v[62:65], v[126:129], v[192:195], v[62:65]
	v_mfma_i32_16x16x64_i8 v[58:61], v[134:137], v[192:195], v[58:61]
	v_mfma_i32_16x16x64_i8 v[46:49], v[126:129], v[200:203], v[46:49]
	v_mfma_i32_16x16x64_i8 v[42:45], v[134:137], v[200:203], v[42:45]
	v_mfma_i32_16x16x64_i8 v[30:33], v[126:129], v[208:211], v[30:33]
	v_mfma_i32_16x16x64_i8 v[26:29], v[134:137], v[208:211], v[26:29]
	v_mfma_i32_16x16x64_i8 v[14:17], v[126:129], v[216:219], v[14:17]
	v_mfma_i32_16x16x64_i8 v[10:13], v[134:137], v[216:219], v[10:13]
	v_mfma_i32_16x16x64_i8 v[54:57], v[168:171], v[188:191], v[54:57]
	v_mfma_i32_16x16x64_i8 v[50:53], v[180:183], v[188:191], v[50:53]
	v_mfma_i32_16x16x64_i8 v[38:41], v[168:171], v[196:199], v[38:41]
	v_mfma_i32_16x16x64_i8 v[34:37], v[180:183], v[196:199], v[34:37]
	v_mfma_i32_16x16x64_i8 v[22:25], v[168:171], v[204:207], v[22:25]
	v_mfma_i32_16x16x64_i8 v[18:21], v[180:183], v[204:207], v[18:21]
	v_mfma_i32_16x16x64_i8 v[6:9], v[168:171], v[212:215], v[6:9]
	v_mfma_i32_16x16x64_i8 v[2:5], v[180:183], v[212:215], v[2:5]
	v_mfma_i32_16x16x64_i8 v[54:57], v[176:179], v[192:195], v[54:57]
	v_mfma_i32_16x16x64_i8 v[50:53], v[184:187], v[192:195], v[50:53]
	v_mfma_i32_16x16x64_i8 v[38:41], v[176:179], v[200:203], v[38:41]
	v_mfma_i32_16x16x64_i8 v[34:37], v[184:187], v[200:203], v[34:37]
	v_mfma_i32_16x16x64_i8 v[22:25], v[176:179], v[208:211], v[22:25]
	v_mfma_i32_16x16x64_i8 v[18:21], v[184:187], v[208:211], v[18:21]
	v_mfma_i32_16x16x64_i8 v[6:9], v[176:179], v[216:219], v[6:9]
	v_mfma_i32_16x16x64_i8 v[2:5], v[184:187], v[216:219], v[2:5]
	s_barrier
	s_add_i32 s65, s65, 2
	s_add_u32 s36, s36, 0x100
	s_addc_u32 s37, s37, 0
	s_add_u32 s63, s63, 0x100
	s_addc_u32 s64, s64, 0
	s_cmp_gt_u32 s65, 29
	s_cbranch_scc0 .LBB0_2014
	s_and_b64 vcc, exec, s[14:15]
	s_cbranch_vccz .LBB0_2017
	s_barrier

; #define PG8_STAGE(bufoff, gbase, voff) do { _Pragma("unroll") for (int _i = 0; _i < 2; ++_i) \
;         __builtin_amdgcn_global_load_lds((const unsigned*)((const char*)(gbase) + (voff)[_i]), (PG8_LAS unsigned*)(lds + (bufoff) + ldsw + _i * 8192), 16, 0, 0); } while (0)
; #define PG8_LDA(dst, b, h) do { _Pragma("unroll") for (int m = 0; m < 4; ++m) _Pragma("unroll") for (int k = 0; k < 2; ++k) dst[m][k] = *(const PG8_LAS bf16x8*)(lds + PG8_SA(b, h) + aoff + m * 2048 + k * 1024); } while (0)
; #define PG8_LDB(dst, b, h) do { _Pragma("unroll") for (int n = 0; n < 2; ++n) _Pragma("unroll") for (int k = 0; k < 2; ++k) dst[n][k] = *(const PG8_LAS bf16x8*)(lds + PG8_SB(b, h) + boff + n * 2048 + k * 1024); } while (0)
; #define PG8_MMA(ai, bj, At, Bt) do { __builtin_amdgcn_s_setprio(1); _Pragma("unroll") for (int m = 0; m < 4; ++m) _Pragma("unroll") for (int n = 0; n < 2; ++n) _Pragma("unroll") for (int k = 0; k < 2; ++k) \
;         acc[ai][bj][m][n] = mma_<I8>(Bt[n][k], At[m][k], acc[ai][bj][m][n]); __builtin_amdgcn_s_setprio(0); } while (0)
; #define PG8_WAIT_V(n) asm volatile("s_waitcnt vmcnt(" #n ")" ::: "memory")
; #define PG8_WAIT_L(n) asm volatile("s_waitcnt lgkmcnt(" #n ")" ::: "memory")
; #define PG8_BAR __builtin_amdgcn_s_barrier()
; template <class Epi, class Sched, bool ALIGN_EPI = false, bool SP2 = false, bool I8 = false>
; __device__ __forceinline__ void gemm_phase(PG8_LAS unsigned char* lds, const Gemm g, const Sched& S, const Epi& E) {
;     ...
;             const bool last = (t == nt - 2);
;             const char* a1 = cA + (size_t)(t + 1) * kstep;
;             const char* a2 = last ? nA : cA + (size_t)(t + 2) * kstep; const char* b2 = last ? nB : cB + (size_t)(t + 2) * kstep;
;             const char* a3 = a2 + kstep; const char* b3 = b2 + kstep;
;             if (last && has_next) S.a_ready(nxt);
;             if constexpr (SP2) {
;             PG8_LDB(B0, 0, 0); PG8_LDB(B1, 0, 1); PG8_SCHED; PG8_LDA(At, 0, 0); PG8_STAGE(PG8_SA(1, 1), a1 + hstepA, voffA);
;             PG8_WAIT_V(8); PG8_WAIT_L(0); PG8_BAR; PG8_MMA(0, 0, At, B0); PG8_MMA(0, 1, At, B1); PG8_BAR; PG8_SCHED;
;             PG8_LDA(At, 0, 1); PG8_STAGE(PG8_SB(0, 0), b2, voffB); PG8_STAGE(PG8_SB(0, 1), b2 + hstepB, voffB); PG8_STAGE(PG8_SA(0, 0), a2, voffA);
;             PG8_WAIT_V(8); PG8_WAIT_L(0); PG8_BAR; PG8_MMA(1, 0, At, B0); PG8_MMA(1, 1, At, B1); PG8_BAR; PG8_SCHED;
.LBB0_2092:
	ds_read_b128 v[130:133], v192
	ds_read_b128 v[134:137], v192 offset:1024
	ds_read_b128 v[138:141], v192 offset:2048
	ds_read_b128 v[142:145], v192 offset:3072
	ds_read_b128 v[146:149], v193
	ds_read_b128 v[150:153], v193 offset:1024
	ds_read_b128 v[154:157], v193 offset:2048
	ds_read_b128 v[158:161], v193 offset:3072
	s_add_u32 s28, s8, 0xffc00080
	s_addc_u32 s29, s9, -1
	s_cmpk_eq_i32 s51, 0xfc
	s_cselect_b32 s31, s3, s29
	s_cselect_b32 s30, s7, s28
	s_cselect_b32 s29, s21, s50
	s_cselect_b32 s28, s23, s49
	s_add_i32 m0, s38, 0xc000
	ds_read_b128 v[162:165], v194
	ds_read_b128 v[166:169], v194 offset:1024
	ds_read_b128 v[182:185], v194 offset:2048
	ds_read_b128 v[186:189], v194 offset:3072
	ds_read_b128 v[196:199], v194 offset:4096
	ds_read_b128 v[200:203], v194 offset:5120
	ds_read_b128 v[204:207], v194 offset:6144
	ds_read_b128 v[208:211], v194 offset:7168
	global_load_lds_dwordx4 v174, s[8:9]
	s_add_i32 m0, s38, 0xe000
	s_nop 0
	global_load_lds_dwordx4 v176, s[8:9]
	s_waitcnt vmcnt(8) lgkmcnt(0)
	s_barrier
	v_mfma_f32_16x16x32_bf16 v[126:129], v[130:133], v[162:165], v[126:129]
	v_mfma_f32_16x16x32_bf16 v[122:125], v[138:141], v[162:165], v[122:125]
	v_mfma_f32_16x16x32_bf16 v[110:113], v[130:133], v[182:185], v[110:113]
	v_mfma_f32_16x16x32_bf16 v[106:109], v[138:141], v[182:185], v[106:109]
	v_mfma_f32_16x16x32_bf16 v[94:97], v[130:133], v[196:199], v[94:97]
	v_mfma_f32_16x16x32_bf16 v[90:93], v[138:141], v[196:199], v[90:93]
	v_mfma_f32_16x16x32_bf16 v[78:81], v[130:133], v[204:207], v[78:81]
	v_mfma_f32_16x16x32_bf16 v[74:77], v[138:141], v[204:207], v[74:77]
	v_mfma_f32_16x16x32_bf16 v[126:129], v[134:137], v[166:169], v[126:129]
	v_mfma_f32_16x16x32_bf16 v[122:125], v[142:145], v[166:169], v[122:125]
	v_mfma_f32_16x16x32_bf16 v[110:113], v[134:137], v[186:189], v[110:113]
	v_mfma_f32_16x16x32_bf16 v[106:109], v[142:145], v[186:189], v[106:109]
	v_mfma_f32_16x16x32_bf16 v[94:97], v[134:137], v[200:203], v[94:97]
	v_mfma_f32_16x16x32_bf16 v[90:93], v[142:145], v[200:203], v[90:93]
	v_mfma_f32_16x16x32_bf16 v[78:81], v[134:137], v[208:211], v[78:81]
	v_mfma_f32_16x16x32_bf16 v[74:77], v[142:145], v[208:211], v[74:77]
	v_mfma_f32_16x16x32_bf16 v[118:121], v[146:149], v[162:165], v[118:121]
	v_mfma_f32_16x16x32_bf16 v[114:117], v[154:157], v[162:165], v[114:117]
	v_mfma_f32_16x16x32_bf16 v[102:105], v[146:149], v[182:185], v[102:105]
	v_mfma_f32_16x16x32_bf16 v[98:101], v[154:157], v[182:185], v[98:101]
	v_mfma_f32_16x16x32_bf16 v[86:89], v[146:149], v[196:199], v[86:89]
	v_mfma_f32_16x16x32_bf16 v[82:85], v[154:157], v[196:199], v[82:85]
	v_mfma_f32_16x16x32_bf16 v[70:73], v[146:149], v[204:207], v[70:73]
	v_mfma_f32_16x16x32_bf16 v[66:69], v[154:157], v[204:207], v[66:69]
	v_mfma_f32_16x16x32_bf16 v[118:121], v[150:153], v[166:169], v[118:121]
	v_mfma_f32_16x16x32_bf16 v[114:117], v[158:161], v[166:169], v[114:117]
	v_mfma_f32_16x16x32_bf16 v[102:105], v[150:153], v[186:189], v[102:105]
	v_mfma_f32_16x16x32_bf16 v[98:101], v[158:161], v[186:189], v[98:101]
	v_mfma_f32_16x16x32_bf16 v[86:89], v[150:153], v[200:203], v[86:89]
	v_mfma_f32_16x16x32_bf16 v[82:85], v[158:161], v[200:203], v[82:85]
	v_mfma_f32_16x16x32_bf16 v[70:73], v[150:153], v[208:211], v[70:73]
	v_mfma_f32_16x16x32_bf16 v[66:69], v[158:161], v[208:211], v[66:69]
	s_barrier
	s_add_i32 s52, s47, s33
	s_mov_b64 s[98:99], s[28:29]
	s_mov_b32 m0, s52
	ds_read_b128 v[162:165], v194 offset:16384
	ds_read_b128 v[166:169], v194 offset:17408
	ds_read_b128 v[182:185], v194 offset:18432
	ds_read_b128 v[186:189], v194 offset:19456
	ds_read_b128 v[196:199], v194 offset:20480
	ds_read_b128 v[200:203], v194 offset:21504
	ds_read_b128 v[204:207], v194 offset:22528
	ds_read_b128 v[208:211], v194 offset:23552
	global_load_lds_dwordx4 v170, s[28:29]
	s_add_i32 m0, s52, 0x2000
	s_add_u32 s52, s28, 0x400000
	s_mov_b64 s[98:99], s[28:29]
	s_addc_u32 s53, s29, 0
	s_add_i32 s54, s48, s33
	global_load_lds_dwordx4 v172, s[28:29]
	s_mov_b32 m0, s54
	s_mov_b64 s[100:101], s[30:31]
	global_load_lds_dwordx4 v170, s[52:53]
	s_add_i32 m0, s54, 0x2000
	s_nop 0
	global_load_lds_dwordx4 v172, s[52:53]
	s_mov_b64 s[100:101], s[30:31]
	s_mov_b32 m0, s38
	s_nop 0
	global_load_lds_dwordx4 v170, s[30:31]
	s_mov_b32 m0, s39
	s_nop 0
	global_load_lds_dwordx4 v172, s[30:31]
	s_waitcnt vmcnt(8) lgkmcnt(0)
	s_barrier
	v_mfma_f32_16x16x32_bf16 v[62:65], v[130:133], v[162:165], v[62:65]
	v_mfma_f32_16x16x32_bf16 v[58:61], v[138:141], v[162:165], v[58:61]
	v_mfma_f32_16x16x32_bf16 v[46:49], v[130:133], v[182:185], v[46:49]
	v_mfma_f32_16x16x32_bf16 v[42:45], v[138:141], v[182:185], v[42:45]
	v_mfma_f32_16x16x32_bf16 v[30:33], v[130:133], v[196:199], v[30:33]
	v_mfma_f32_16x16x32_bf16 v[26:29], v[138:141], v[196:199], v[26:29]
	v_mfma_f32_16x16x32_bf16 v[22:25], v[130:133], v[204:207], v[22:25]
	v_mfma_f32_16x16x32_bf16 v[10:13], v[138:141], v[204:207], v[10:13]
	v_mfma_f32_16x16x32_bf16 v[62:65], v[134:137], v[166:169], v[62:65]
	v_mfma_f32_16x16x32_bf16 v[58:61], v[142:145], v[166:169], v[58:61]
	v_mfma_f32_16x16x32_bf16 v[46:49], v[134:137], v[186:189], v[46:49]
	v_mfma_f32_16x16x32_bf16 v[42:45], v[142:145], v[186:189], v[42:45]
	v_mfma_f32_16x16x32_bf16 v[30:33], v[134:137], v[200:203], v[30:33]
	v_mfma_f32_16x16x32_bf16 v[26:29], v[142:145], v[200:203], v[26:29]
	v_mfma_f32_16x16x32_bf16 v[22:25], v[134:137], v[208:211], v[22:25]
	v_mfma_f32_16x16x32_bf16 v[10:13], v[142:145], v[208:211], v[10:13]
	v_mfma_f32_16x16x32_bf16 v[54:57], v[146:149], v[162:165], v[54:57]
	v_mfma_f32_16x16x32_bf16 v[50:53], v[154:157], v[162:165], v[50:53]
	v_mfma_f32_16x16x32_bf16 v[38:41], v[146:149], v[182:185], v[38:41]
	v_mfma_f32_16x16x32_bf16 v[34:37], v[154:157], v[182:185], v[34:37]
	v_mfma_f32_16x16x32_bf16 v[18:21], v[146:149], v[196:199], v[18:21]
	v_mfma_f32_16x16x32_bf16 v[14:17], v[154:157], v[196:199], v[14:17]
	v_mfma_f32_16x16x32_bf16 v[6:9], v[146:149], v[204:207], v[6:9]
	v_mfma_f32_16x16x32_bf16 v[2:5], v[154:157], v[204:207], v[2:5]
	v_mfma_f32_16x16x32_bf16 v[54:57], v[150:153], v[166:169], v[54:57]
	v_mfma_f32_16x16x32_bf16 v[50:53], v[158:161], v[166:169], v[50:53]
	v_mfma_f32_16x16x32_bf16 v[38:41], v[150:153], v[186:189], v[38:41]
	v_mfma_f32_16x16x32_bf16 v[34:37], v[158:161], v[186:189], v[34:37]
	v_mfma_f32_16x16x32_bf16 v[18:21], v[150:153], v[200:203], v[18:21]
	v_mfma_f32_16x16x32_bf16 v[14:17], v[158:161], v[200:203], v[14:17]
	v_mfma_f32_16x16x32_bf16 v[6:9], v[150:153], v[208:211], v[6:9]
	v_mfma_f32_16x16x32_bf16 v[2:5], v[158:161], v[208:211], v[2:5]
	s_barrier
; #define PG8_STAGE(bufoff, gbase, voff) do { _Pragma("unroll") for (int _i = 0; _i < 2; ++_i) \
;         __builtin_amdgcn_global_load_lds((const unsigned*)((const char*)(gbase) + (voff)[_i]), (PG8_LAS unsigned*)(lds + (bufoff) + ldsw + _i * 8192), 16, 0, 0); } while (0)
; #define PG8_LDA(dst, b, h) do { _Pragma("unroll") for (int m = 0; m < 4; ++m) _Pragma("unroll") for (int k = 0; k < 2; ++k) dst[m][k] = *(const PG8_LAS bf16x8*)(lds + PG8_SA(b, h) + aoff + m * 2048 + k * 1024); } while (0)
; #define PG8_LDB(dst, b, h) do { _Pragma("unroll") for (int n = 0; n < 2; ++n) _Pragma("unroll") for (int k = 0; k < 2; ++k) dst[n][k] = *(const PG8_LAS bf16x8*)(lds + PG8_SB(b, h) + boff + n * 2048 + k * 1024); } while (0)
; #define PG8_MMA(ai, bj, At, Bt) do { __builtin_amdgcn_s_setprio(1); _Pragma("unroll") for (int m = 0; m < 4; ++m) _Pragma("unroll") for (int n = 0; n < 2; ++n) _Pragma("unroll") for (int k = 0; k < 2; ++k) \
;         acc[ai][bj][m][n] = mma_<I8>(Bt[n][k], At[m][k], acc[ai][bj][m][n]); __builtin_amdgcn_s_setprio(0); } while (0)
; #define PG8_WAIT_V(n) asm volatile("s_waitcnt vmcnt(" #n ")" ::: "memory")
; #define PG8_WAIT_L(n) asm volatile("s_waitcnt lgkmcnt(" #n ")" ::: "memory")
; #define PG8_BAR __builtin_amdgcn_s_barrier()
; #define PG8_SCHED __builtin_amdgcn_sched_barrier(0)
; template <class Epi, class Sched, bool ALIGN_EPI = false, bool SP2 = false, bool I8 = false>
; __device__ __forceinline__ void gemm_phase(PG8_LAS unsigned char* lds, const Gemm g, const Sched& S, const Epi& E) {
;     ...
;         for (int t = 0; t < nt; t += 2) {
;     ...
;             PG8_LDB(B0, 1, 0); PG8_LDB(B1, 1, 1); PG8_SCHED; PG8_LDA(At, 1, 0); PG8_STAGE(PG8_SA(0, 1), a2 + hstepA, voffA);
;             PG8_WAIT_V(8); PG8_WAIT_L(0); PG8_BAR; PG8_MMA(0, 0, At, B0); PG8_MMA(0, 1, At, B1); PG8_BAR; PG8_SCHED;
;             PG8_LDA(At, 1, 1); PG8_STAGE(PG8_SB(1, 0), b3, voffB); PG8_STAGE(PG8_SB(1, 1), b3 + hstepB, voffB); PG8_STAGE(PG8_SA(1, 0), a3, voffA);
;             PG8_WAIT_V(8); PG8_WAIT_L(0); PG8_BAR; PG8_MMA(1, 0, At, B0); PG8_MMA(1, 1, At, B1); PG8_BAR; PG8_SCHED;
	s_add_i32 s52, 0, 0x18000
	s_add_i32 s53, 0, 0x1c000
	v_add_u32_e32 v142, s52, v1
	v_add_u32_e32 v158, s53, v1
	ds_read_b128 v[130:133], v142
	ds_read_b128 v[134:137], v142 offset:1024
	ds_read_b128 v[138:141], v142 offset:2048
	ds_read_b128 v[142:145], v142 offset:3072
	ds_read_b128 v[146:149], v158
	ds_read_b128 v[150:153], v158 offset:1024
	ds_read_b128 v[154:157], v158 offset:2048
	ds_read_b128 v[158:161], v158 offset:3072
	s_add_u32 s30, s30, 0x400000
	s_addc_u32 s31, s31, 0
	s_mov_b32 m0, s40
	ds_read_b128 v[162:165], v194 offset:32768
	ds_read_b128 v[166:169], v194 offset:33792
	ds_read_b128 v[182:185], v194 offset:34816
	ds_read_b128 v[186:189], v194 offset:35840
	ds_read_b128 v[196:199], v194 offset:36864
	ds_read_b128 v[200:203], v194 offset:37888
	ds_read_b128 v[204:207], v194 offset:38912
	ds_read_b128 v[208:211], v194 offset:39936
	global_load_lds_dwordx4 v170, s[30:31]
	s_mov_b32 m0, s41
	s_nop 0
	global_load_lds_dwordx4 v172, s[30:31]
	s_waitcnt vmcnt(8) lgkmcnt(0)
	s_barrier
	v_mfma_f32_16x16x32_bf16 v[126:129], v[130:133], v[162:165], v[126:129]
	v_mfma_f32_16x16x32_bf16 v[122:125], v[138:141], v[162:165], v[122:125]
	v_mfma_f32_16x16x32_bf16 v[110:113], v[130:133], v[182:185], v[110:113]
	v_mfma_f32_16x16x32_bf16 v[106:109], v[138:141], v[182:185], v[106:109]
	v_mfma_f32_16x16x32_bf16 v[94:97], v[130:133], v[196:199], v[94:97]
	v_mfma_f32_16x16x32_bf16 v[90:93], v[138:141], v[196:199], v[90:93]
	v_mfma_f32_16x16x32_bf16 v[78:81], v[130:133], v[204:207], v[78:81]
	v_mfma_f32_16x16x32_bf16 v[74:77], v[138:141], v[204:207], v[74:77]
	v_mfma_f32_16x16x32_bf16 v[126:129], v[134:137], v[166:169], v[126:129]
	v_mfma_f32_16x16x32_bf16 v[122:125], v[142:145], v[166:169], v[122:125]
	v_mfma_f32_16x16x32_bf16 v[110:113], v[134:137], v[186:189], v[110:113]
	v_mfma_f32_16x16x32_bf16 v[106:109], v[142:145], v[186:189], v[106:109]
	v_mfma_f32_16x16x32_bf16 v[94:97], v[134:137], v[200:203], v[94:97]
	v_mfma_f32_16x16x32_bf16 v[90:93], v[142:145], v[200:203], v[90:93]
	v_mfma_f32_16x16x32_bf16 v[78:81], v[134:137], v[208:211], v[78:81]
	v_mfma_f32_16x16x32_bf16 v[74:77], v[142:145], v[208:211], v[74:77]
	v_mfma_f32_16x16x32_bf16 v[118:121], v[146:149], v[162:165], v[118:121]
	v_mfma_f32_16x16x32_bf16 v[114:117], v[154:157], v[162:165], v[114:117]
	v_mfma_f32_16x16x32_bf16 v[102:105], v[146:149], v[182:185], v[102:105]
	v_mfma_f32_16x16x32_bf16 v[98:101], v[154:157], v[182:185], v[98:101]
	v_mfma_f32_16x16x32_bf16 v[86:89], v[146:149], v[196:199], v[86:89]
	v_mfma_f32_16x16x32_bf16 v[82:85], v[154:157], v[196:199], v[82:85]
	v_mfma_f32_16x16x32_bf16 v[70:73], v[146:149], v[204:207], v[70:73]
	v_mfma_f32_16x16x32_bf16 v[66:69], v[154:157], v[204:207], v[66:69]
	v_mfma_f32_16x16x32_bf16 v[118:121], v[150:153], v[166:169], v[118:121]
	v_mfma_f32_16x16x32_bf16 v[114:117], v[158:161], v[166:169], v[114:117]
	v_mfma_f32_16x16x32_bf16 v[102:105], v[150:153], v[186:189], v[102:105]
	v_mfma_f32_16x16x32_bf16 v[98:101], v[158:161], v[186:189], v[98:101]
	v_mfma_f32_16x16x32_bf16 v[86:89], v[150:153], v[200:203], v[86:89]
	v_mfma_f32_16x16x32_bf16 v[82:85], v[158:161], v[200:203], v[82:85]
	v_mfma_f32_16x16x32_bf16 v[70:73], v[150:153], v[208:211], v[70:73]
	v_mfma_f32_16x16x32_bf16 v[66:69], v[158:161], v[208:211], v[66:69]
	s_barrier
	s_add_i32 s30, s52, s33
	s_add_i32 m0, s30, 0xffffff80
	ds_read_b128 v[162:165], v194 offset:49152
	ds_read_b128 v[166:169], v194 offset:50176
	ds_read_b128 v[182:185], v194 offset:51200
	ds_read_b128 v[186:189], v194 offset:52224
	ds_read_b128 v[196:199], v194 offset:53248
	ds_read_b128 v[200:203], v194 offset:54272
	ds_read_b128 v[204:207], v194 offset:55296
	ds_read_b128 v[208:211], v194 offset:56320
	global_load_lds_dwordx4 v170, s[98:99] offset:128
	s_add_i32 m0, s30, 0x1f80
	s_add_u32 s28, s28, 0x400080
	s_addc_u32 s29, s29, 0
	s_add_i32 s30, s53, s33
	global_load_lds_dwordx4 v172, s[98:99] offset:128
	s_mov_b32 m0, s30
	s_nop 0
	global_load_lds_dwordx4 v170, s[28:29]
	s_add_i32 m0, s30, 0x2000
	s_nop 0
	global_load_lds_dwordx4 v172, s[28:29]
	s_add_i32 m0, s43, 0xffffff80
	s_nop 0
	global_load_lds_dwordx4 v170, s[100:101] offset:128
	s_add_i32 m0, s44, 0xffffff80
	s_nop 0
	global_load_lds_dwordx4 v172, s[100:101] offset:128
	s_waitcnt vmcnt(8) lgkmcnt(0)
	s_barrier
	v_mfma_f32_16x16x32_bf16 v[62:65], v[130:133], v[162:165], v[62:65]
	v_mfma_f32_16x16x32_bf16 v[58:61], v[138:141], v[162:165], v[58:61]
	v_mfma_f32_16x16x32_bf16 v[46:49], v[130:133], v[182:185], v[46:49]
	v_mfma_f32_16x16x32_bf16 v[42:45], v[138:141], v[182:185], v[42:45]
	v_mfma_f32_16x16x32_bf16 v[30:33], v[130:133], v[196:199], v[30:33]
	v_mfma_f32_16x16x32_bf16 v[26:29], v[138:141], v[196:199], v[26:29]
	v_mfma_f32_16x16x32_bf16 v[22:25], v[130:133], v[204:207], v[22:25]
	v_mfma_f32_16x16x32_bf16 v[10:13], v[138:141], v[204:207], v[10:13]
	v_mfma_f32_16x16x32_bf16 v[62:65], v[134:137], v[166:169], v[62:65]
	v_mfma_f32_16x16x32_bf16 v[58:61], v[142:145], v[166:169], v[58:61]
	v_mfma_f32_16x16x32_bf16 v[46:49], v[134:137], v[186:189], v[46:49]
	v_mfma_f32_16x16x32_bf16 v[42:45], v[142:145], v[186:189], v[42:45]
	v_mfma_f32_16x16x32_bf16 v[30:33], v[134:137], v[200:203], v[30:33]
	v_mfma_f32_16x16x32_bf16 v[26:29], v[142:145], v[200:203], v[26:29]
	v_mfma_f32_16x16x32_bf16 v[22:25], v[134:137], v[208:211], v[22:25]
	v_mfma_f32_16x16x32_bf16 v[10:13], v[142:145], v[208:211], v[10:13]
	v_mfma_f32_16x16x32_bf16 v[54:57], v[146:149], v[162:165], v[54:57]
	v_mfma_f32_16x16x32_bf16 v[50:53], v[154:157], v[162:165], v[50:53]
	v_mfma_f32_16x16x32_bf16 v[38:41], v[146:149], v[182:185], v[38:41]
	v_mfma_f32_16x16x32_bf16 v[34:37], v[154:157], v[182:185], v[34:37]
	v_mfma_f32_16x16x32_bf16 v[18:21], v[146:149], v[196:199], v[18:21]
	v_mfma_f32_16x16x32_bf16 v[14:17], v[154:157], v[196:199], v[14:17]
	v_mfma_f32_16x16x32_bf16 v[6:9], v[146:149], v[204:207], v[6:9]
	v_mfma_f32_16x16x32_bf16 v[2:5], v[154:157], v[204:207], v[2:5]
	v_mfma_f32_16x16x32_bf16 v[54:57], v[150:153], v[166:169], v[54:57]
	v_mfma_f32_16x16x32_bf16 v[50:53], v[158:161], v[166:169], v[50:53]
	v_mfma_f32_16x16x32_bf16 v[38:41], v[150:153], v[186:189], v[38:41]
	v_mfma_f32_16x16x32_bf16 v[34:37], v[158:161], v[186:189], v[34:37]
	v_mfma_f32_16x16x32_bf16 v[18:21], v[150:153], v[200:203], v[18:21]
	v_mfma_f32_16x16x32_bf16 v[14:17], v[158:161], v[200:203], v[14:17]
	v_mfma_f32_16x16x32_bf16 v[6:9], v[150:153], v[208:211], v[6:9]
	v_mfma_f32_16x16x32_bf16 v[2:5], v[158:161], v[208:211], v[2:5]
	s_barrier
	s_add_i32 s51, s51, 2
	s_add_u32 s8, s8, 0x100
	s_addc_u32 s9, s9, 0
	s_add_u32 s49, s49, 0x100
	s_addc_u32 s50, s50, 0
	s_cmpk_gt_u32 s51, 0xfd
	s_cbranch_scc0 .LBB0_2092
	s_and_b64 vcc, exec, s[16:17]
	s_cbranch_vccz .LBB0_2095
	s_barrier

; #define PG8_STAGE(bufoff, gbase, voff) do { _Pragma("unroll") for (int _i = 0; _i < 2; ++_i) \
;         __builtin_amdgcn_global_load_lds((const unsigned*)((const char*)(gbase) + (voff)[_i]), (PG8_LAS unsigned*)(lds + (bufoff) + ldsw + _i * 8192), 16, 0, 0); } while (0)
; #define PG8_LDA(dst, b, h) do { _Pragma("unroll") for (int m = 0; m < 4; ++m) _Pragma("unroll") for (int k = 0; k < 2; ++k) dst[m][k] = *(const PG8_LAS bf16x8*)(lds + PG8_SA(b, h) + aoff + m * 2048 + k * 1024); } while (0)
; #define PG8_LDB(dst, b, h) do { _Pragma("unroll") for (int n = 0; n < 2; ++n) _Pragma("unroll") for (int k = 0; k < 2; ++k) dst[n][k] = *(const PG8_LAS bf16x8*)(lds + PG8_SB(b, h) + boff + n * 2048 + k * 1024); } while (0)
; #define PG8_MMA(ai, bj, At, Bt) do { __builtin_amdgcn_s_setprio(1); _Pragma("unroll") for (int m = 0; m < 4; ++m) _Pragma("unroll") for (int n = 0; n < 2; ++n) _Pragma("unroll") for (int k = 0; k < 2; ++k) \
;         acc[ai][bj][m][n] = mma_<I8>(Bt[n][k], At[m][k], acc[ai][bj][m][n]); __builtin_amdgcn_s_setprio(0); } while (0)
; #define PG8_WAIT_V(n) asm volatile("s_waitcnt vmcnt(" #n ")" ::: "memory")
; #define PG8_WAIT_L(n) asm volatile("s_waitcnt lgkmcnt(" #n ")" ::: "memory")
; #define PG8_BAR __builtin_amdgcn_s_barrier()
; #define PG8_SCHED __builtin_amdgcn_sched_barrier(0)
; template <class Epi, class Sched, bool ALIGN_EPI = false, bool SP2 = false, bool I8 = false>
; __device__ __forceinline__ void gemm_phase(PG8_LAS unsigned char* lds, const Gemm g, const Sched& S, const Epi& E) {
;     ...
;             PG8_LDB(B0, 0, 0); PG8_LDB(B1, 0, 1); PG8_SCHED; PG8_LDA(At, 0, 0); PG8_STAGE(PG8_SA(1, 1), a1 + hstepA, voffA);
;             PG8_WAIT_V(8); PG8_WAIT_L(0); PG8_BAR; PG8_MMA(0, 0, At, B0); PG8_MMA(0, 1, At, B1); PG8_BAR; PG8_SCHED;
;             PG8_LDA(At, 0, 1); PG8_STAGE(PG8_SB(0, 0), b2, voffB); PG8_STAGE(PG8_SB(0, 1), b2 + hstepB, voffB); PG8_STAGE(PG8_SA(0, 0), a2, voffA);
;             PG8_WAIT_V(8); PG8_WAIT_L(0); PG8_BAR; PG8_MMA(1, 0, At, B0); PG8_MMA(1, 1, At, B1); PG8_BAR; PG8_SCHED;
.LBB0_2322:
	ds_read_b128 v[58:61], v183
	ds_read_b128 v[66:69], v183 offset:1024
	ds_read_b128 v[74:77], v183 offset:2048
	ds_read_b128 v[78:81], v183 offset:3072
	ds_read_b128 v[146:149], v189
	ds_read_b128 v[150:153], v189 offset:1024
	ds_read_b128 v[154:157], v189 offset:2048
	ds_read_b128 v[158:161], v189 offset:3072
	s_add_u32 s28, s26, 0xfff80080
	s_addc_u32 s29, s27, -1
	s_cmp_eq_u32 s53, 28
	s_cselect_b32 s31, s21, s29
	s_cselect_b32 s30, s49, s28
	s_cselect_b32 s29, s19, s52
	s_cselect_b32 s28, s50, s51
	s_add_i32 m0, s3, 0xc000
	ds_read_b128 v[162:165], v193
	ds_read_b128 v[178:181], v193 offset:1024
	ds_read_b128 v[184:187], v193 offset:2048
	ds_read_b128 v[198:201], v193 offset:3072
	ds_read_b128 v[202:205], v193 offset:4096
	ds_read_b128 v[206:209], v193 offset:5120
	ds_read_b128 v[210:213], v193 offset:6144
	ds_read_b128 v[214:217], v193 offset:7168
	global_load_lds_dwordx4 v170, s[26:27]
	s_add_i32 m0, s3, 0xe000
	s_nop 0
	global_load_lds_dwordx4 v172, s[26:27]
	s_waitcnt vmcnt(8) lgkmcnt(0)
	s_barrier
	v_mfma_i32_16x16x64_i8 v[142:145], v[58:61], v[162:165], v[142:145]
	v_mfma_i32_16x16x64_i8 v[138:141], v[74:77], v[162:165], v[138:141]
	v_mfma_i32_16x16x64_i8 v[126:129], v[58:61], v[184:187], v[126:129]
	v_mfma_i32_16x16x64_i8 v[122:125], v[74:77], v[184:187], v[122:125]
	v_mfma_i32_16x16x64_i8 v[110:113], v[58:61], v[202:205], v[110:113]
	v_mfma_i32_16x16x64_i8 v[106:109], v[74:77], v[202:205], v[106:109]
	v_mfma_i32_16x16x64_i8 v[94:97], v[58:61], v[210:213], v[94:97]
	v_mfma_i32_16x16x64_i8 v[90:93], v[74:77], v[210:213], v[90:93]
	v_mfma_i32_16x16x64_i8 v[142:145], v[66:69], v[178:181], v[142:145]
	v_mfma_i32_16x16x64_i8 v[138:141], v[78:81], v[178:181], v[138:141]
	v_mfma_i32_16x16x64_i8 v[126:129], v[66:69], v[198:201], v[126:129]
	v_mfma_i32_16x16x64_i8 v[122:125], v[78:81], v[198:201], v[122:125]
	v_mfma_i32_16x16x64_i8 v[110:113], v[66:69], v[206:209], v[110:113]
	v_mfma_i32_16x16x64_i8 v[106:109], v[78:81], v[206:209], v[106:109]
	v_mfma_i32_16x16x64_i8 v[94:97], v[66:69], v[214:217], v[94:97]
	v_mfma_i32_16x16x64_i8 v[90:93], v[78:81], v[214:217], v[90:93]
	v_mfma_i32_16x16x64_i8 v[134:137], v[146:149], v[162:165], v[134:137]
	v_mfma_i32_16x16x64_i8 v[130:133], v[154:157], v[162:165], v[130:133]
	v_mfma_i32_16x16x64_i8 v[118:121], v[146:149], v[184:187], v[118:121]
	v_mfma_i32_16x16x64_i8 v[114:117], v[154:157], v[184:187], v[114:117]
	v_mfma_i32_16x16x64_i8 v[102:105], v[146:149], v[202:205], v[102:105]
	v_mfma_i32_16x16x64_i8 v[98:101], v[154:157], v[202:205], v[98:101]
	v_mfma_i32_16x16x64_i8 v[86:89], v[146:149], v[210:213], v[86:89]
	v_mfma_i32_16x16x64_i8 v[82:85], v[154:157], v[210:213], v[82:85]
	v_mfma_i32_16x16x64_i8 v[134:137], v[150:153], v[178:181], v[134:137]
	v_mfma_i32_16x16x64_i8 v[130:133], v[158:161], v[178:181], v[130:133]
	v_mfma_i32_16x16x64_i8 v[118:121], v[150:153], v[198:201], v[118:121]
	v_mfma_i32_16x16x64_i8 v[114:117], v[158:161], v[198:201], v[114:117]
	v_mfma_i32_16x16x64_i8 v[102:105], v[150:153], v[206:209], v[102:105]
	v_mfma_i32_16x16x64_i8 v[98:101], v[158:161], v[206:209], v[98:101]
	v_mfma_i32_16x16x64_i8 v[86:89], v[150:153], v[214:217], v[86:89]
	v_mfma_i32_16x16x64_i8 v[82:85], v[158:161], v[214:217], v[82:85]
	s_barrier
	s_add_i32 s54, s46, s38
	s_mov_b64 s[98:99], s[28:29]
	s_mov_b32 m0, s54
	ds_read_b128 v[162:165], v193 offset:16384
	ds_read_b128 v[178:181], v193 offset:17408
	ds_read_b128 v[184:187], v193 offset:18432
	ds_read_b128 v[198:201], v193 offset:19456
	ds_read_b128 v[202:205], v193 offset:20480
	ds_read_b128 v[206:209], v193 offset:21504
	ds_read_b128 v[210:213], v193 offset:22528
	ds_read_b128 v[214:217], v193 offset:23552
	global_load_lds_dwordx4 v166, s[28:29]
	s_add_i32 m0, s54, 0x2000
	s_add_u32 s54, s28, 0x80000
	s_mov_b64 s[98:99], s[28:29]
	s_addc_u32 s55, s29, 0
	s_add_i32 s56, s47, s38
	global_load_lds_dwordx4 v168, s[28:29]
	s_mov_b32 m0, s56
	s_mov_b64 s[100:101], s[30:31]
	global_load_lds_dwordx4 v166, s[54:55]
	s_add_i32 m0, s56, 0x2000
	s_nop 0
	global_load_lds_dwordx4 v168, s[54:55]
	s_mov_b64 s[100:101], s[30:31]
	s_mov_b32 m0, s3
	s_nop 0
	global_load_lds_dwordx4 v166, s[30:31]
	s_mov_b32 m0, s39
	s_nop 0
	global_load_lds_dwordx4 v168, s[30:31]
	s_waitcnt vmcnt(8) lgkmcnt(0)
	s_barrier
	v_mfma_i32_16x16x64_i8 v[70:73], v[58:61], v[162:165], v[70:73]
	v_mfma_i32_16x16x64_i8 v[62:65], v[74:77], v[162:165], v[62:65]
	v_mfma_i32_16x16x64_i8 v[46:49], v[58:61], v[184:187], v[46:49]
	v_mfma_i32_16x16x64_i8 v[42:45], v[74:77], v[184:187], v[42:45]
	v_mfma_i32_16x16x64_i8 v[30:33], v[58:61], v[202:205], v[30:33]
	v_mfma_i32_16x16x64_i8 v[26:29], v[74:77], v[202:205], v[26:29]
	v_mfma_i32_16x16x64_i8 v[14:17], v[58:61], v[210:213], v[14:17]
	v_mfma_i32_16x16x64_i8 v[10:13], v[74:77], v[210:213], v[10:13]
	v_mfma_i32_16x16x64_i8 v[70:73], v[66:69], v[178:181], v[70:73]
	v_mfma_i32_16x16x64_i8 v[62:65], v[78:81], v[178:181], v[62:65]
	v_mfma_i32_16x16x64_i8 v[46:49], v[66:69], v[198:201], v[46:49]
	v_mfma_i32_16x16x64_i8 v[42:45], v[78:81], v[198:201], v[42:45]
	v_mfma_i32_16x16x64_i8 v[30:33], v[66:69], v[206:209], v[30:33]
	v_mfma_i32_16x16x64_i8 v[26:29], v[78:81], v[206:209], v[26:29]
	v_mfma_i32_16x16x64_i8 v[14:17], v[66:69], v[214:217], v[14:17]
	v_mfma_i32_16x16x64_i8 v[10:13], v[78:81], v[214:217], v[10:13]
	v_mfma_i32_16x16x64_i8 v[54:57], v[146:149], v[162:165], v[54:57]
	v_mfma_i32_16x16x64_i8 v[50:53], v[154:157], v[162:165], v[50:53]
	v_mfma_i32_16x16x64_i8 v[38:41], v[146:149], v[184:187], v[38:41]
	v_mfma_i32_16x16x64_i8 v[34:37], v[154:157], v[184:187], v[34:37]
	v_mfma_i32_16x16x64_i8 v[22:25], v[146:149], v[202:205], v[22:25]
	v_mfma_i32_16x16x64_i8 v[18:21], v[154:157], v[202:205], v[18:21]
	v_mfma_i32_16x16x64_i8 v[6:9], v[146:149], v[210:213], v[6:9]
	v_mfma_i32_16x16x64_i8 v[2:5], v[154:157], v[210:213], v[2:5]
	v_mfma_i32_16x16x64_i8 v[54:57], v[150:153], v[178:181], v[54:57]
	v_mfma_i32_16x16x64_i8 v[50:53], v[158:161], v[178:181], v[50:53]
	v_mfma_i32_16x16x64_i8 v[38:41], v[150:153], v[198:201], v[38:41]
	v_mfma_i32_16x16x64_i8 v[34:37], v[158:161], v[198:201], v[34:37]
	v_mfma_i32_16x16x64_i8 v[22:25], v[150:153], v[206:209], v[22:25]
	v_mfma_i32_16x16x64_i8 v[18:21], v[158:161], v[206:209], v[18:21]
	v_mfma_i32_16x16x64_i8 v[6:9], v[150:153], v[214:217], v[6:9]
	v_mfma_i32_16x16x64_i8 v[2:5], v[158:161], v[214:217], v[2:5]
	s_barrier
; #define PG8_STAGE(bufoff, gbase, voff) do { _Pragma("unroll") for (int _i = 0; _i < 2; ++_i) \
;         __builtin_amdgcn_global_load_lds((const unsigned*)((const char*)(gbase) + (voff)[_i]), (PG8_LAS unsigned*)(lds + (bufoff) + ldsw + _i * 8192), 16, 0, 0); } while (0)
; #define PG8_LDA(dst, b, h) do { _Pragma("unroll") for (int m = 0; m < 4; ++m) _Pragma("unroll") for (int k = 0; k < 2; ++k) dst[m][k] = *(const PG8_LAS bf16x8*)(lds + PG8_SA(b, h) + aoff + m * 2048 + k * 1024); } while (0)
; #define PG8_LDB(dst, b, h) do { _Pragma("unroll") for (int n = 0; n < 2; ++n) _Pragma("unroll") for (int k = 0; k < 2; ++k) dst[n][k] = *(const PG8_LAS bf16x8*)(lds + PG8_SB(b, h) + boff + n * 2048 + k * 1024); } while (0)
; #define PG8_MMA(ai, bj, At, Bt) do { __builtin_amdgcn_s_setprio(1); _Pragma("unroll") for (int m = 0; m < 4; ++m) _Pragma("unroll") for (int n = 0; n < 2; ++n) _Pragma("unroll") for (int k = 0; k < 2; ++k) \
;         acc[ai][bj][m][n] = mma_<I8>(Bt[n][k], At[m][k], acc[ai][bj][m][n]); __builtin_amdgcn_s_setprio(0); } while (0)
; #define PG8_WAIT_V(n) asm volatile("s_waitcnt vmcnt(" #n ")" ::: "memory")
; #define PG8_WAIT_L(n) asm volatile("s_waitcnt lgkmcnt(" #n ")" ::: "memory")
; #define PG8_BAR __builtin_amdgcn_s_barrier()
; #define PG8_SCHED __builtin_amdgcn_sched_barrier(0)
; template <class Epi, class Sched, bool ALIGN_EPI = false, bool SP2 = false, bool I8 = false>
; __device__ __forceinline__ void gemm_phase(PG8_LAS unsigned char* lds, const Gemm g, const Sched& S, const Epi& E) {
;     ...
;         for (int t = 0; t < nt; t += 2) {
;             const bool last = (t == nt - 2);
;             const char* a1 = cA + (size_t)(t + 1) * kstep;
;             const char* a2 = last ? nA : cA + (size_t)(t + 2) * kstep; const char* b2 = last ? nB : cB + (size_t)(t + 2) * kstep;
;             const char* a3 = a2 + kstep; const char* b3 = b2 + kstep;
;     ...
;             PG8_LDB(B0, 1, 0); PG8_LDB(B1, 1, 1); PG8_SCHED; PG8_LDA(At, 1, 0); PG8_STAGE(PG8_SA(0, 1), a2 + hstepA, voffA);
;             PG8_WAIT_V(8); PG8_WAIT_L(0); PG8_BAR; PG8_MMA(0, 0, At, B0); PG8_MMA(0, 1, At, B1); PG8_BAR; PG8_SCHED;
;             PG8_LDA(At, 1, 1); PG8_STAGE(PG8_SB(1, 0), b3, voffB); PG8_STAGE(PG8_SB(1, 1), b3 + hstepB, voffB); PG8_STAGE(PG8_SA(1, 0), a3, voffA);
;             PG8_WAIT_V(8); PG8_WAIT_L(0); PG8_BAR; PG8_MMA(1, 0, At, B0); PG8_MMA(1, 1, At, B1); PG8_BAR; PG8_SCHED;
	s_add_i32 s54, 0, 0x18000
	s_add_i32 s55, 0, 0x1c000
	v_add_u32_e32 v78, s54, v1
	v_add_u32_e32 v158, s55, v1
	ds_read_b128 v[58:61], v78
	ds_read_b128 v[66:69], v78 offset:1024
	ds_read_b128 v[74:77], v78 offset:2048
	ds_read_b128 v[78:81], v78 offset:3072
	ds_read_b128 v[146:149], v158
	ds_read_b128 v[150:153], v158 offset:1024
	ds_read_b128 v[154:157], v158 offset:2048
	ds_read_b128 v[158:161], v158 offset:3072
	s_add_u32 s30, s30, 0x80000
	s_addc_u32 s31, s31, 0
	s_mov_b32 m0, s40
	ds_read_b128 v[162:165], v193 offset:32768
	ds_read_b128 v[178:181], v193 offset:33792
	ds_read_b128 v[184:187], v193 offset:34816
	ds_read_b128 v[198:201], v193 offset:35840
	ds_read_b128 v[202:205], v193 offset:36864
	ds_read_b128 v[206:209], v193 offset:37888
	ds_read_b128 v[210:213], v193 offset:38912
	ds_read_b128 v[214:217], v193 offset:39936
	global_load_lds_dwordx4 v166, s[30:31]
	s_mov_b32 m0, s41
	s_nop 0
	global_load_lds_dwordx4 v168, s[30:31]
	s_waitcnt vmcnt(8) lgkmcnt(0)
	s_barrier
	v_mfma_i32_16x16x64_i8 v[142:145], v[58:61], v[162:165], v[142:145]
	v_mfma_i32_16x16x64_i8 v[138:141], v[74:77], v[162:165], v[138:141]
	v_mfma_i32_16x16x64_i8 v[126:129], v[58:61], v[184:187], v[126:129]
	v_mfma_i32_16x16x64_i8 v[122:125], v[74:77], v[184:187], v[122:125]
	v_mfma_i32_16x16x64_i8 v[110:113], v[58:61], v[202:205], v[110:113]
	v_mfma_i32_16x16x64_i8 v[106:109], v[74:77], v[202:205], v[106:109]
	v_mfma_i32_16x16x64_i8 v[94:97], v[58:61], v[210:213], v[94:97]
	v_mfma_i32_16x16x64_i8 v[90:93], v[74:77], v[210:213], v[90:93]
	v_mfma_i32_16x16x64_i8 v[142:145], v[66:69], v[178:181], v[142:145]
	v_mfma_i32_16x16x64_i8 v[138:141], v[78:81], v[178:181], v[138:141]
	v_mfma_i32_16x16x64_i8 v[126:129], v[66:69], v[198:201], v[126:129]
	v_mfma_i32_16x16x64_i8 v[122:125], v[78:81], v[198:201], v[122:125]
	v_mfma_i32_16x16x64_i8 v[110:113], v[66:69], v[206:209], v[110:113]
	v_mfma_i32_16x16x64_i8 v[106:109], v[78:81], v[206:209], v[106:109]
	v_mfma_i32_16x16x64_i8 v[94:97], v[66:69], v[214:217], v[94:97]
	v_mfma_i32_16x16x64_i8 v[90:93], v[78:81], v[214:217], v[90:93]
	v_mfma_i32_16x16x64_i8 v[134:137], v[146:149], v[162:165], v[134:137]
	v_mfma_i32_16x16x64_i8 v[130:133], v[154:157], v[162:165], v[130:133]
	v_mfma_i32_16x16x64_i8 v[118:121], v[146:149], v[184:187], v[118:121]
	v_mfma_i32_16x16x64_i8 v[114:117], v[154:157], v[184:187], v[114:117]
	v_mfma_i32_16x16x64_i8 v[102:105], v[146:149], v[202:205], v[102:105]
	v_mfma_i32_16x16x64_i8 v[98:101], v[154:157], v[202:205], v[98:101]
	v_mfma_i32_16x16x64_i8 v[86:89], v[146:149], v[210:213], v[86:89]
	v_mfma_i32_16x16x64_i8 v[82:85], v[154:157], v[210:213], v[82:85]
	v_mfma_i32_16x16x64_i8 v[134:137], v[150:153], v[178:181], v[134:137]
	v_mfma_i32_16x16x64_i8 v[130:133], v[158:161], v[178:181], v[130:133]
	v_mfma_i32_16x16x64_i8 v[118:121], v[150:153], v[198:201], v[118:121]
	v_mfma_i32_16x16x64_i8 v[114:117], v[158:161], v[198:201], v[114:117]
	v_mfma_i32_16x16x64_i8 v[102:105], v[150:153], v[206:209], v[102:105]
	v_mfma_i32_16x16x64_i8 v[98:101], v[158:161], v[206:209], v[98:101]
	v_mfma_i32_16x16x64_i8 v[86:89], v[150:153], v[214:217], v[86:89]
	v_mfma_i32_16x16x64_i8 v[82:85], v[158:161], v[214:217], v[82:85]
	s_barrier
	s_add_i32 s30, s54, s38
	s_add_i32 m0, s30, 0xffffff80
	ds_read_b128 v[162:165], v193 offset:49152
	ds_read_b128 v[178:181], v193 offset:50176
	ds_read_b128 v[184:187], v193 offset:51200
	ds_read_b128 v[198:201], v193 offset:52224
	ds_read_b128 v[202:205], v193 offset:53248
	ds_read_b128 v[206:209], v193 offset:54272
	ds_read_b128 v[210:213], v193 offset:55296
	ds_read_b128 v[214:217], v193 offset:56320
	global_load_lds_dwordx4 v166, s[98:99] offset:128
	s_add_i32 m0, s30, 0x1f80
	s_add_u32 s28, s28, 0x80080
	s_addc_u32 s29, s29, 0
	s_add_i32 s30, s55, s38
	global_load_lds_dwordx4 v168, s[98:99] offset:128
	s_mov_b32 m0, s30
	s_nop 0
	global_load_lds_dwordx4 v166, s[28:29]
	s_add_i32 m0, s30, 0x2000
	s_nop 0
	global_load_lds_dwordx4 v168, s[28:29]
	s_add_i32 m0, s43, 0xffffff80
	s_nop 0
	global_load_lds_dwordx4 v166, s[100:101] offset:128
	s_add_i32 m0, s44, 0xffffff80
	s_nop 0
	global_load_lds_dwordx4 v168, s[100:101] offset:128
	s_waitcnt vmcnt(8) lgkmcnt(0)
	s_barrier
	v_mfma_i32_16x16x64_i8 v[70:73], v[58:61], v[162:165], v[70:73]
	v_mfma_i32_16x16x64_i8 v[62:65], v[74:77], v[162:165], v[62:65]
	v_mfma_i32_16x16x64_i8 v[46:49], v[58:61], v[184:187], v[46:49]
	v_mfma_i32_16x16x64_i8 v[42:45], v[74:77], v[184:187], v[42:45]
	v_mfma_i32_16x16x64_i8 v[30:33], v[58:61], v[202:205], v[30:33]
	v_mfma_i32_16x16x64_i8 v[26:29], v[74:77], v[202:205], v[26:29]
	v_mfma_i32_16x16x64_i8 v[14:17], v[58:61], v[210:213], v[14:17]
	v_mfma_i32_16x16x64_i8 v[10:13], v[74:77], v[210:213], v[10:13]
	v_mfma_i32_16x16x64_i8 v[70:73], v[66:69], v[178:181], v[70:73]
	v_mfma_i32_16x16x64_i8 v[62:65], v[78:81], v[178:181], v[62:65]
	v_mfma_i32_16x16x64_i8 v[46:49], v[66:69], v[198:201], v[46:49]
	v_mfma_i32_16x16x64_i8 v[42:45], v[78:81], v[198:201], v[42:45]
	v_mfma_i32_16x16x64_i8 v[30:33], v[66:69], v[206:209], v[30:33]
	v_mfma_i32_16x16x64_i8 v[26:29], v[78:81], v[206:209], v[26:29]
	v_mfma_i32_16x16x64_i8 v[14:17], v[66:69], v[214:217], v[14:17]
	v_mfma_i32_16x16x64_i8 v[10:13], v[78:81], v[214:217], v[10:13]
	v_mfma_i32_16x16x64_i8 v[54:57], v[146:149], v[162:165], v[54:57]
	v_mfma_i32_16x16x64_i8 v[50:53], v[154:157], v[162:165], v[50:53]
	v_mfma_i32_16x16x64_i8 v[38:41], v[146:149], v[184:187], v[38:41]
	v_mfma_i32_16x16x64_i8 v[34:37], v[154:157], v[184:187], v[34:37]
	v_mfma_i32_16x16x64_i8 v[22:25], v[146:149], v[202:205], v[22:25]
	v_mfma_i32_16x16x64_i8 v[18:21], v[154:157], v[202:205], v[18:21]
	v_mfma_i32_16x16x64_i8 v[6:9], v[146:149], v[210:213], v[6:9]
	v_mfma_i32_16x16x64_i8 v[2:5], v[154:157], v[210:213], v[2:5]
	v_mfma_i32_16x16x64_i8 v[54:57], v[150:153], v[178:181], v[54:57]
	v_mfma_i32_16x16x64_i8 v[50:53], v[158:161], v[178:181], v[50:53]
	v_mfma_i32_16x16x64_i8 v[38:41], v[150:153], v[198:201], v[38:41]
	v_mfma_i32_16x16x64_i8 v[34:37], v[158:161], v[198:201], v[34:37]
	v_mfma_i32_16x16x64_i8 v[22:25], v[150:153], v[206:209], v[22:25]
	v_mfma_i32_16x16x64_i8 v[18:21], v[158:161], v[206:209], v[18:21]
	v_mfma_i32_16x16x64_i8 v[6:9], v[150:153], v[214:217], v[6:9]
	v_mfma_i32_16x16x64_i8 v[2:5], v[158:161], v[214:217], v[2:5]
	s_barrier
	s_add_i32 s53, s53, 2
	s_add_u32 s26, s26, 0x100
	s_addc_u32 s27, s27, 0
	s_add_u32 s51, s51, 0x100
	s_addc_u32 s52, s52, 0
	s_cmp_gt_u32 s53, 29
	s_cbranch_scc0 .LBB0_2322
	s_and_b64 vcc, exec, s[16:17]
	s_cbranch_vccz .LBB0_2325
	s_barrier
